# MFMA order: B-fragment pair stationary with m inner (was A-fragment pair stationary), same-accumulator k0,k1 back-to-back kept
# baseline (speedup 1.0000x reference)
.LBB0_146:
	s_ashr_i32 s25, s24, 31
	s_lshl_b64 s[26:27], s[24:25], 20
	s_add_u32 s26, s47, s26
	s_addc_u32 s27, s48, s27
	s_and_b64 s[28:29], s[38:39], exec
	s_cselect_b32 s2, s27, s41
	s_cselect_b32 s5, s26, s40
	s_ashr_i32 s23, s22, 31
	s_lshl_b64 s[28:29], s[22:23], 20
	s_add_u32 s28, s49, s28
	s_addc_u32 s29, s50, s29
	s_and_b64 s[44:45], s[38:39], exec
	s_cselect_b32 s23, s29, s43
	s_cselect_b32 s25, s28, s42
	s_add_u32 s40, s40, 0x80080
	s_addc_u32 s41, s41, 0
	s_add_u32 s31, s42, 0x100
	s_addc_u32 s62, s43, 0
	s_mov_b32 s63, -2
	s_sleep 1
	s_add_u32 s42, s40, 0xfff80080
	s_addc_u32 s43, s41, -1
	s_add_i32 s71, 0, 0x10000
	s_cmp_eq_u32 s63, 28
	s_cselect_b32 s45, s2, s43
	s_cselect_b32 s44, s5, s42
	s_cselect_b32 s43, s23, s62
	s_cselect_b32 s42, s25, s31
	s_add_i32 s73, 0, 0x14000
	s_waitcnt lgkmcnt(0)
	v_lshl_add_u64 v[202:203], s[40:41], 0, v[148:149]
	s_add_i32 m0, s53, 0xc000
	s_nop 0
	global_load_lds_dwordx4 v[202:203], off
	v_lshl_add_u64 v[202:203], s[40:41], 0, v[150:151]
	s_add_i32 m0, s53, 0xe000
	s_nop 0
	global_load_lds_dwordx4 v[202:203], off
	v_add_u32_e32 v156, s71, v169
	v_add_u32_e32 v178, s73, v169
	ds_read_b128 v[132:135], v156
	ds_read_b128 v[136:139], v156 offset:1024
	ds_read_b128 v[152:155], v156 offset:2048
	ds_read_b128 v[156:159], v156 offset:3072
	ds_read_b128 v[160:163], v178
	ds_read_b128 v[164:167], v178 offset:1024
	ds_read_b128 v[174:177], v178 offset:2048
	ds_read_b128 v[178:181], v178 offset:3072
	ds_read_b128 v[182:185], v171
	ds_read_b128 v[186:189], v171 offset:1024
	ds_read_b128 v[190:193], v171 offset:2048
	ds_read_b128 v[194:197], v171 offset:3072
	ds_read_b128 v[198:201], v171 offset:4096
	ds_read_b128 v[208:211], v171 offset:5120
	ds_read_b128 v[212:215], v171 offset:6144
	ds_read_b128 v[216:219], v171 offset:7168
	s_waitcnt vmcnt(8)
	s_waitcnt lgkmcnt(0)
	s_barrier
	s_setprio 1
	s_waitcnt lgkmcnt(0)
	v_mfma_f32_16x16x32_bf16 v[128:131], v[132:135], v[182:185], 0
	v_mfma_f32_16x16x32_bf16 v[128:131], v[136:139], v[186:189], v[128:131]
	v_mfma_f32_16x16x32_bf16 v[120:123], v[132:135], v[190:193], 0
	v_mfma_f32_16x16x32_bf16 v[120:123], v[136:139], v[194:197], v[120:123]
	v_mfma_f32_16x16x32_bf16 v[104:107], v[132:135], v[198:201], 0
	v_mfma_f32_16x16x32_bf16 v[104:107], v[136:139], v[208:211], v[104:107]
	v_mfma_f32_16x16x32_bf16 v[88:91], v[132:135], v[212:215], 0
	v_mfma_f32_16x16x32_bf16 v[88:91], v[136:139], v[216:219], v[88:91]
	v_mfma_f32_16x16x32_bf16 v[116:119], v[160:163], v[182:185], 0
	v_mfma_f32_16x16x32_bf16 v[116:119], v[164:167], v[186:189], v[116:119]
	v_mfma_f32_16x16x32_bf16 v[100:103], v[160:163], v[190:193], 0
	v_mfma_f32_16x16x32_bf16 v[100:103], v[164:167], v[194:197], v[100:103]
	v_mfma_f32_16x16x32_bf16 v[84:87], v[160:163], v[198:201], 0
	v_mfma_f32_16x16x32_bf16 v[84:87], v[164:167], v[208:211], v[84:87]
	v_mfma_f32_16x16x32_bf16 v[72:75], v[160:163], v[212:215], 0
	v_mfma_f32_16x16x32_bf16 v[72:75], v[164:167], v[216:219], v[72:75]
	v_mfma_f32_16x16x32_bf16 v[124:127], v[152:155], v[182:185], 0
	v_mfma_f32_16x16x32_bf16 v[124:127], v[156:159], v[186:189], v[124:127]
	v_mfma_f32_16x16x32_bf16 v[112:115], v[152:155], v[190:193], 0
	v_mfma_f32_16x16x32_bf16 v[112:115], v[156:159], v[194:197], v[112:115]
	v_mfma_f32_16x16x32_bf16 v[96:99], v[152:155], v[198:201], 0
	v_mfma_f32_16x16x32_bf16 v[96:99], v[156:159], v[208:211], v[96:99]
	v_mfma_f32_16x16x32_bf16 v[80:83], v[152:155], v[212:215], 0
	v_mfma_f32_16x16x32_bf16 v[80:83], v[156:159], v[216:219], v[80:83]
	v_mfma_f32_16x16x32_bf16 v[108:111], v[174:177], v[182:185], 0
	v_mfma_f32_16x16x32_bf16 v[108:111], v[178:181], v[186:189], v[108:111]
	v_mfma_f32_16x16x32_bf16 v[92:95], v[174:177], v[190:193], 0
	v_mfma_f32_16x16x32_bf16 v[92:95], v[178:181], v[194:197], v[92:95]
	v_mfma_f32_16x16x32_bf16 v[76:79], v[174:177], v[198:201], 0
	v_mfma_f32_16x16x32_bf16 v[76:79], v[178:181], v[208:211], v[76:79]
	v_mfma_f32_16x16x32_bf16 v[68:71], v[174:177], v[212:215], 0
	v_mfma_f32_16x16x32_bf16 v[68:71], v[178:181], v[216:219], v[68:71]
	s_setprio 0
	s_barrier
	s_sleep 2
	s_add_i32 s71, s71, s51
	v_lshl_add_u64 v[202:203], s[42:43], 0, v[2:3]
	s_mov_b32 m0, s71
	ds_read_b128 v[182:185], v171 offset:16384
	ds_read_b128 v[186:189], v171 offset:17408
	ds_read_b128 v[190:193], v171 offset:18432
	ds_read_b128 v[194:197], v171 offset:19456
	ds_read_b128 v[198:201], v171 offset:20480
	ds_read_b128 v[208:211], v171 offset:21504
	ds_read_b128 v[212:215], v171 offset:22528
	ds_read_b128 v[216:219], v171 offset:23552
	global_load_lds_dwordx4 v[202:203], off
	s_add_i32 m0, s71, 0x2000
	s_add_u32 s74, s42, 0x80000
	v_lshl_add_u64 v[204:205], s[42:43], 0, v[142:143]
	s_addc_u32 s75, s43, 0
	s_add_i32 s71, s73, s51
	global_load_lds_dwordx4 v[204:205], off
	v_lshl_add_u64 v[206:207], s[74:75], 0, v[2:3]
	s_mov_b32 m0, s71
	v_lshl_add_u64 v[220:221], s[44:45], 0, v[140:141]
	global_load_lds_dwordx4 v[206:207], off
	v_lshl_add_u64 v[206:207], s[74:75], 0, v[142:143]
	s_add_i32 m0, s71, 0x2000
	s_nop 0
	global_load_lds_dwordx4 v[206:207], off
	v_lshl_add_u64 v[206:207], s[44:45], 0, v[0:1]
	s_mov_b32 m0, s53
	s_nop 0
	global_load_lds_dwordx4 v[206:207], off
	s_mov_b32 m0, s54
	s_nop 0
	global_load_lds_dwordx4 v[220:221], off
	s_waitcnt vmcnt(8)
	s_waitcnt lgkmcnt(0)
	s_barrier
	s_setprio 1
	s_waitcnt lgkmcnt(0)
	v_mfma_f32_16x16x32_bf16 v[64:67], v[132:135], v[182:185], 0
	v_mfma_f32_16x16x32_bf16 v[64:67], v[136:139], v[186:189], v[64:67]
	v_mfma_f32_16x16x32_bf16 v[56:59], v[132:135], v[190:193], 0
	v_mfma_f32_16x16x32_bf16 v[56:59], v[136:139], v[194:197], v[56:59]
	v_mfma_f32_16x16x32_bf16 v[40:43], v[132:135], v[198:201], 0
	v_mfma_f32_16x16x32_bf16 v[40:43], v[136:139], v[208:211], v[40:43]
	v_mfma_f32_16x16x32_bf16 v[24:27], v[132:135], v[212:215], 0
	v_mfma_f32_16x16x32_bf16 v[24:27], v[136:139], v[216:219], v[24:27]
	v_mfma_f32_16x16x32_bf16 v[52:55], v[160:163], v[182:185], 0
	v_mfma_f32_16x16x32_bf16 v[52:55], v[164:167], v[186:189], v[52:55]
	v_mfma_f32_16x16x32_bf16 v[36:39], v[160:163], v[190:193], 0
	v_mfma_f32_16x16x32_bf16 v[36:39], v[164:167], v[194:197], v[36:39]
	v_mfma_f32_16x16x32_bf16 v[20:23], v[160:163], v[198:201], 0
	v_mfma_f32_16x16x32_bf16 v[20:23], v[164:167], v[208:211], v[20:23]
	v_mfma_f32_16x16x32_bf16 v[8:11], v[160:163], v[212:215], 0
	v_mfma_f32_16x16x32_bf16 v[8:11], v[164:167], v[216:219], v[8:11]
	v_mfma_f32_16x16x32_bf16 v[60:63], v[152:155], v[182:185], 0
	v_mfma_f32_16x16x32_bf16 v[60:63], v[156:159], v[186:189], v[60:63]
	v_mfma_f32_16x16x32_bf16 v[48:51], v[152:155], v[190:193], 0
	v_mfma_f32_16x16x32_bf16 v[48:51], v[156:159], v[194:197], v[48:51]
	v_mfma_f32_16x16x32_bf16 v[32:35], v[152:155], v[198:201], 0
	v_mfma_f32_16x16x32_bf16 v[32:35], v[156:159], v[208:211], v[32:35]
	v_mfma_f32_16x16x32_bf16 v[16:19], v[152:155], v[212:215], 0
	v_mfma_f32_16x16x32_bf16 v[16:19], v[156:159], v[216:219], v[16:19]
	v_mfma_f32_16x16x32_bf16 v[44:47], v[174:177], v[182:185], 0
	v_mfma_f32_16x16x32_bf16 v[44:47], v[178:181], v[186:189], v[44:47]
	v_mfma_f32_16x16x32_bf16 v[28:31], v[174:177], v[190:193], 0
	v_mfma_f32_16x16x32_bf16 v[28:31], v[178:181], v[194:197], v[28:31]
	v_mfma_f32_16x16x32_bf16 v[12:15], v[174:177], v[198:201], 0
	v_mfma_f32_16x16x32_bf16 v[12:15], v[178:181], v[208:211], v[12:15]
	v_mfma_f32_16x16x32_bf16 v[4:7], v[174:177], v[212:215], 0
	v_mfma_f32_16x16x32_bf16 v[4:7], v[178:181], v[216:219], v[4:7]
	s_setprio 0
	s_barrier
	s_sleep 1
	s_add_i32 s71, 0, 0x18000
	s_add_i32 s73, 0, 0x1c000
	s_add_u32 s44, s44, 0x80000
	s_addc_u32 s45, s45, 0
	s_mov_b32 m0, s55
	v_lshl_add_u64 v[222:223], s[44:45], 0, v[0:1]
	global_load_lds_dwordx4 v[222:223], off
	v_lshl_add_u64 v[222:223], s[44:45], 0, v[140:141]
	s_mov_b32 m0, s56
	s_nop 0
	global_load_lds_dwordx4 v[222:223], off
	v_add_u32_e32 v156, s71, v169
	v_add_u32_e32 v178, s73, v169
	ds_read_b128 v[132:135], v156
	ds_read_b128 v[136:139], v156 offset:1024
	ds_read_b128 v[152:155], v156 offset:2048
	ds_read_b128 v[156:159], v156 offset:3072
	ds_read_b128 v[160:163], v178
	ds_read_b128 v[164:167], v178 offset:1024
	ds_read_b128 v[174:177], v178 offset:2048
	ds_read_b128 v[178:181], v178 offset:3072
	ds_read_b128 v[182:185], v171 offset:32768
	ds_read_b128 v[186:189], v171 offset:33792
	ds_read_b128 v[190:193], v171 offset:34816
	ds_read_b128 v[194:197], v171 offset:35840
	ds_read_b128 v[198:201], v171 offset:36864
	ds_read_b128 v[208:211], v171 offset:37888
	ds_read_b128 v[212:215], v171 offset:38912
	ds_read_b128 v[216:219], v171 offset:39936
	s_waitcnt vmcnt(8)
	s_waitcnt lgkmcnt(0)
	s_barrier
	s_setprio 1
	s_waitcnt lgkmcnt(0)
	v_mfma_f32_16x16x32_bf16 v[128:131], v[132:135], v[182:185], v[128:131]
	v_mfma_f32_16x16x32_bf16 v[128:131], v[136:139], v[186:189], v[128:131]
	v_mfma_f32_16x16x32_bf16 v[120:123], v[132:135], v[190:193], v[120:123]
	v_mfma_f32_16x16x32_bf16 v[120:123], v[136:139], v[194:197], v[120:123]
	v_mfma_f32_16x16x32_bf16 v[104:107], v[132:135], v[198:201], v[104:107]
	v_mfma_f32_16x16x32_bf16 v[104:107], v[136:139], v[208:211], v[104:107]
	v_mfma_f32_16x16x32_bf16 v[88:91], v[132:135], v[212:215], v[88:91]
	v_mfma_f32_16x16x32_bf16 v[88:91], v[136:139], v[216:219], v[88:91]
	v_mfma_f32_16x16x32_bf16 v[116:119], v[160:163], v[182:185], v[116:119]
	v_mfma_f32_16x16x32_bf16 v[116:119], v[164:167], v[186:189], v[116:119]
	v_mfma_f32_16x16x32_bf16 v[100:103], v[160:163], v[190:193], v[100:103]
	v_mfma_f32_16x16x32_bf16 v[100:103], v[164:167], v[194:197], v[100:103]
	v_mfma_f32_16x16x32_bf16 v[84:87], v[160:163], v[198:201], v[84:87]
	v_mfma_f32_16x16x32_bf16 v[84:87], v[164:167], v[208:211], v[84:87]
	v_mfma_f32_16x16x32_bf16 v[72:75], v[160:163], v[212:215], v[72:75]
	v_mfma_f32_16x16x32_bf16 v[72:75], v[164:167], v[216:219], v[72:75]
	v_mfma_f32_16x16x32_bf16 v[124:127], v[152:155], v[182:185], v[124:127]
	v_mfma_f32_16x16x32_bf16 v[124:127], v[156:159], v[186:189], v[124:127]
	v_mfma_f32_16x16x32_bf16 v[112:115], v[152:155], v[190:193], v[112:115]
	v_mfma_f32_16x16x32_bf16 v[112:115], v[156:159], v[194:197], v[112:115]
	v_mfma_f32_16x16x32_bf16 v[96:99], v[152:155], v[198:201], v[96:99]
	v_mfma_f32_16x16x32_bf16 v[96:99], v[156:159], v[208:211], v[96:99]
	v_mfma_f32_16x16x32_bf16 v[80:83], v[152:155], v[212:215], v[80:83]
	v_mfma_f32_16x16x32_bf16 v[80:83], v[156:159], v[216:219], v[80:83]
	v_mfma_f32_16x16x32_bf16 v[108:111], v[174:177], v[182:185], v[108:111]
	v_mfma_f32_16x16x32_bf16 v[108:111], v[178:181], v[186:189], v[108:111]
	v_mfma_f32_16x16x32_bf16 v[92:95], v[174:177], v[190:193], v[92:95]
	v_mfma_f32_16x16x32_bf16 v[92:95], v[178:181], v[194:197], v[92:95]
	v_mfma_f32_16x16x32_bf16 v[76:79], v[174:177], v[198:201], v[76:79]
	v_mfma_f32_16x16x32_bf16 v[76:79], v[178:181], v[208:211], v[76:79]
	v_mfma_f32_16x16x32_bf16 v[68:71], v[174:177], v[212:215], v[68:71]
	v_mfma_f32_16x16x32_bf16 v[68:71], v[178:181], v[216:219], v[68:71]
	s_setprio 0
	s_barrier
	s_sleep 2
	s_add_i32 s44, s71, s51
	v_lshl_add_u64 v[202:203], v[202:203], 0, s[66:67]
	s_mov_b32 m0, s44
	ds_read_b128 v[182:185], v171 offset:49152
	ds_read_b128 v[186:189], v171 offset:50176
	ds_read_b128 v[190:193], v171 offset:51200
	ds_read_b128 v[194:197], v171 offset:52224
	ds_read_b128 v[198:201], v171 offset:53248
	ds_read_b128 v[208:211], v171 offset:54272
	ds_read_b128 v[212:215], v171 offset:55296
	ds_read_b128 v[216:219], v171 offset:56320
	global_load_lds_dwordx4 v[202:203], off
	s_add_i32 m0, s44, 0x2000
	s_add_u32 s42, s42, 0x80080
	v_lshl_add_u64 v[202:203], v[204:205], 0, s[66:67]
	s_addc_u32 s43, s43, 0
	s_add_i32 s44, s73, s51
	global_load_lds_dwordx4 v[202:203], off
	v_lshl_add_u64 v[202:203], s[42:43], 0, v[2:3]
	s_mov_b32 m0, s44
	s_nop 0
	global_load_lds_dwordx4 v[202:203], off
	v_lshl_add_u64 v[202:203], s[42:43], 0, v[142:143]
	s_add_i32 m0, s44, 0x2000
	s_nop 0
	global_load_lds_dwordx4 v[202:203], off
	v_lshl_add_u64 v[202:203], v[206:207], 0, s[66:67]
	s_mov_b32 m0, s65
	s_nop 0
	global_load_lds_dwordx4 v[202:203], off
	v_lshl_add_u64 v[202:203], v[220:221], 0, s[66:67]
	s_mov_b32 m0, s68
	s_nop 0
	global_load_lds_dwordx4 v[202:203], off
	s_waitcnt vmcnt(8)
	s_waitcnt lgkmcnt(0)
	s_barrier
	s_setprio 1
	s_waitcnt lgkmcnt(0)
	v_mfma_f32_16x16x32_bf16 v[64:67], v[132:135], v[182:185], v[64:67]
	v_mfma_f32_16x16x32_bf16 v[64:67], v[136:139], v[186:189], v[64:67]
	v_mfma_f32_16x16x32_bf16 v[56:59], v[132:135], v[190:193], v[56:59]
	v_mfma_f32_16x16x32_bf16 v[56:59], v[136:139], v[194:197], v[56:59]
	v_mfma_f32_16x16x32_bf16 v[40:43], v[132:135], v[198:201], v[40:43]
	v_mfma_f32_16x16x32_bf16 v[40:43], v[136:139], v[208:211], v[40:43]
	v_mfma_f32_16x16x32_bf16 v[24:27], v[132:135], v[212:215], v[24:27]
	v_mfma_f32_16x16x32_bf16 v[24:27], v[136:139], v[216:219], v[24:27]
	v_mfma_f32_16x16x32_bf16 v[52:55], v[160:163], v[182:185], v[52:55]
	v_mfma_f32_16x16x32_bf16 v[52:55], v[164:167], v[186:189], v[52:55]
	v_mfma_f32_16x16x32_bf16 v[36:39], v[160:163], v[190:193], v[36:39]
	v_mfma_f32_16x16x32_bf16 v[36:39], v[164:167], v[194:197], v[36:39]
	v_mfma_f32_16x16x32_bf16 v[20:23], v[160:163], v[198:201], v[20:23]
	v_mfma_f32_16x16x32_bf16 v[20:23], v[164:167], v[208:211], v[20:23]
	v_mfma_f32_16x16x32_bf16 v[8:11], v[160:163], v[212:215], v[8:11]
	v_mfma_f32_16x16x32_bf16 v[8:11], v[164:167], v[216:219], v[8:11]
	v_mfma_f32_16x16x32_bf16 v[60:63], v[152:155], v[182:185], v[60:63]
	v_mfma_f32_16x16x32_bf16 v[60:63], v[156:159], v[186:189], v[60:63]
	v_mfma_f32_16x16x32_bf16 v[48:51], v[152:155], v[190:193], v[48:51]
	v_mfma_f32_16x16x32_bf16 v[48:51], v[156:159], v[194:197], v[48:51]
	v_mfma_f32_16x16x32_bf16 v[32:35], v[152:155], v[198:201], v[32:35]
	v_mfma_f32_16x16x32_bf16 v[32:35], v[156:159], v[208:211], v[32:35]
	v_mfma_f32_16x16x32_bf16 v[16:19], v[152:155], v[212:215], v[16:19]
	v_mfma_f32_16x16x32_bf16 v[16:19], v[156:159], v[216:219], v[16:19]
	v_mfma_f32_16x16x32_bf16 v[44:47], v[174:177], v[182:185], v[44:47]
	v_mfma_f32_16x16x32_bf16 v[44:47], v[178:181], v[186:189], v[44:47]
	v_mfma_f32_16x16x32_bf16 v[28:31], v[174:177], v[190:193], v[28:31]
	v_mfma_f32_16x16x32_bf16 v[28:31], v[178:181], v[194:197], v[28:31]
	v_mfma_f32_16x16x32_bf16 v[12:15], v[174:177], v[198:201], v[12:15]
	v_mfma_f32_16x16x32_bf16 v[12:15], v[178:181], v[208:211], v[12:15]
	v_mfma_f32_16x16x32_bf16 v[4:7], v[174:177], v[212:215], v[4:7]
	v_mfma_f32_16x16x32_bf16 v[4:7], v[178:181], v[216:219], v[4:7]
	s_setprio 0
	s_barrier
	s_add_i32 s63, s63, 2
	s_add_u32 s40, s40, 0x100
	s_addc_u32 s41, s41, 0
	s_add_u32 s31, s31, 0x100
	s_addc_u32 s62, s62, 0
	s_cmp_gt_u32 s63, 29
.LBB0_147:
	s_sleep 1
	s_add_u32 s42, s40, 0xfff80080
	s_addc_u32 s43, s41, -1
	s_add_i32 s71, 0, 0x10000
	s_cmp_eq_u32 s63, 28
	s_cselect_b32 s45, s2, s43
	s_cselect_b32 s44, s5, s42
	s_cselect_b32 s43, s23, s62
	s_cselect_b32 s42, s25, s31
	s_add_i32 s73, 0, 0x14000
	s_waitcnt lgkmcnt(0)
	v_lshl_add_u64 v[202:203], s[40:41], 0, v[148:149]
	s_add_i32 m0, s53, 0xc000
	s_nop 0
	global_load_lds_dwordx4 v[202:203], off
	v_lshl_add_u64 v[202:203], s[40:41], 0, v[150:151]
	s_add_i32 m0, s53, 0xe000
	s_nop 0
	global_load_lds_dwordx4 v[202:203], off
	v_add_u32_e32 v156, s71, v169
	v_add_u32_e32 v178, s73, v169
	ds_read_b128 v[132:135], v156
	ds_read_b128 v[136:139], v156 offset:1024
	ds_read_b128 v[152:155], v156 offset:2048
	ds_read_b128 v[156:159], v156 offset:3072
	ds_read_b128 v[160:163], v178
	ds_read_b128 v[164:167], v178 offset:1024
	ds_read_b128 v[174:177], v178 offset:2048
	ds_read_b128 v[178:181], v178 offset:3072
	ds_read_b128 v[182:185], v171
	ds_read_b128 v[186:189], v171 offset:1024
	ds_read_b128 v[190:193], v171 offset:2048
	ds_read_b128 v[194:197], v171 offset:3072
	ds_read_b128 v[198:201], v171 offset:4096
	ds_read_b128 v[208:211], v171 offset:5120
	ds_read_b128 v[212:215], v171 offset:6144
	ds_read_b128 v[216:219], v171 offset:7168
	s_waitcnt vmcnt(8)
	s_waitcnt lgkmcnt(0)
	s_barrier
	s_setprio 1
	s_waitcnt lgkmcnt(0)
	v_mfma_f32_16x16x32_bf16 v[128:131], v[132:135], v[182:185], v[128:131]
	v_mfma_f32_16x16x32_bf16 v[128:131], v[136:139], v[186:189], v[128:131]
	v_mfma_f32_16x16x32_bf16 v[120:123], v[132:135], v[190:193], v[120:123]
	v_mfma_f32_16x16x32_bf16 v[120:123], v[136:139], v[194:197], v[120:123]
	v_mfma_f32_16x16x32_bf16 v[104:107], v[132:135], v[198:201], v[104:107]
	v_mfma_f32_16x16x32_bf16 v[104:107], v[136:139], v[208:211], v[104:107]
	v_mfma_f32_16x16x32_bf16 v[88:91], v[132:135], v[212:215], v[88:91]
	v_mfma_f32_16x16x32_bf16 v[88:91], v[136:139], v[216:219], v[88:91]
	v_mfma_f32_16x16x32_bf16 v[116:119], v[160:163], v[182:185], v[116:119]
	v_mfma_f32_16x16x32_bf16 v[116:119], v[164:167], v[186:189], v[116:119]
	v_mfma_f32_16x16x32_bf16 v[100:103], v[160:163], v[190:193], v[100:103]
	v_mfma_f32_16x16x32_bf16 v[100:103], v[164:167], v[194:197], v[100:103]
	v_mfma_f32_16x16x32_bf16 v[84:87], v[160:163], v[198:201], v[84:87]
	v_mfma_f32_16x16x32_bf16 v[84:87], v[164:167], v[208:211], v[84:87]
	v_mfma_f32_16x16x32_bf16 v[72:75], v[160:163], v[212:215], v[72:75]
	v_mfma_f32_16x16x32_bf16 v[72:75], v[164:167], v[216:219], v[72:75]
	v_mfma_f32_16x16x32_bf16 v[124:127], v[152:155], v[182:185], v[124:127]
	v_mfma_f32_16x16x32_bf16 v[124:127], v[156:159], v[186:189], v[124:127]
	v_mfma_f32_16x16x32_bf16 v[112:115], v[152:155], v[190:193], v[112:115]
	v_mfma_f32_16x16x32_bf16 v[112:115], v[156:159], v[194:197], v[112:115]
	v_mfma_f32_16x16x32_bf16 v[96:99], v[152:155], v[198:201], v[96:99]
	v_mfma_f32_16x16x32_bf16 v[96:99], v[156:159], v[208:211], v[96:99]
	v_mfma_f32_16x16x32_bf16 v[80:83], v[152:155], v[212:215], v[80:83]
	v_mfma_f32_16x16x32_bf16 v[80:83], v[156:159], v[216:219], v[80:83]
	v_mfma_f32_16x16x32_bf16 v[108:111], v[174:177], v[182:185], v[108:111]
	v_mfma_f32_16x16x32_bf16 v[108:111], v[178:181], v[186:189], v[108:111]
	v_mfma_f32_16x16x32_bf16 v[92:95], v[174:177], v[190:193], v[92:95]
	v_mfma_f32_16x16x32_bf16 v[92:95], v[178:181], v[194:197], v[92:95]
	v_mfma_f32_16x16x32_bf16 v[76:79], v[174:177], v[198:201], v[76:79]
	v_mfma_f32_16x16x32_bf16 v[76:79], v[178:181], v[208:211], v[76:79]
	v_mfma_f32_16x16x32_bf16 v[68:71], v[174:177], v[212:215], v[68:71]
	v_mfma_f32_16x16x32_bf16 v[68:71], v[178:181], v[216:219], v[68:71]
	s_setprio 0
	s_barrier
	s_sleep 2
	s_add_i32 s71, s71, s51
	v_lshl_add_u64 v[202:203], s[42:43], 0, v[2:3]
	s_mov_b32 m0, s71
	ds_read_b128 v[182:185], v171 offset:16384
	ds_read_b128 v[186:189], v171 offset:17408
	ds_read_b128 v[190:193], v171 offset:18432
	ds_read_b128 v[194:197], v171 offset:19456
	ds_read_b128 v[198:201], v171 offset:20480
	ds_read_b128 v[208:211], v171 offset:21504
	ds_read_b128 v[212:215], v171 offset:22528
	ds_read_b128 v[216:219], v171 offset:23552
	global_load_lds_dwordx4 v[202:203], off
	s_add_i32 m0, s71, 0x2000
	s_add_u32 s74, s42, 0x80000
	v_lshl_add_u64 v[204:205], s[42:43], 0, v[142:143]
	s_addc_u32 s75, s43, 0
	s_add_i32 s71, s73, s51
	global_load_lds_dwordx4 v[204:205], off
	v_lshl_add_u64 v[206:207], s[74:75], 0, v[2:3]
	s_mov_b32 m0, s71
	v_lshl_add_u64 v[220:221], s[44:45], 0, v[140:141]
	global_load_lds_dwordx4 v[206:207], off
	v_lshl_add_u64 v[206:207], s[74:75], 0, v[142:143]
	s_add_i32 m0, s71, 0x2000
	s_nop 0
	global_load_lds_dwordx4 v[206:207], off
	v_lshl_add_u64 v[206:207], s[44:45], 0, v[0:1]
	s_mov_b32 m0, s53
	s_nop 0
	global_load_lds_dwordx4 v[206:207], off
	s_mov_b32 m0, s54
	s_nop 0
	global_load_lds_dwordx4 v[220:221], off
	s_waitcnt vmcnt(8)
	s_waitcnt lgkmcnt(0)
	s_barrier
	s_setprio 1
	s_waitcnt lgkmcnt(0)
	v_mfma_f32_16x16x32_bf16 v[64:67], v[132:135], v[182:185], v[64:67]
	v_mfma_f32_16x16x32_bf16 v[64:67], v[136:139], v[186:189], v[64:67]
	v_mfma_f32_16x16x32_bf16 v[56:59], v[132:135], v[190:193], v[56:59]
	v_mfma_f32_16x16x32_bf16 v[56:59], v[136:139], v[194:197], v[56:59]
	v_mfma_f32_16x16x32_bf16 v[40:43], v[132:135], v[198:201], v[40:43]
	v_mfma_f32_16x16x32_bf16 v[40:43], v[136:139], v[208:211], v[40:43]
	v_mfma_f32_16x16x32_bf16 v[24:27], v[132:135], v[212:215], v[24:27]
	v_mfma_f32_16x16x32_bf16 v[24:27], v[136:139], v[216:219], v[24:27]
	v_mfma_f32_16x16x32_bf16 v[52:55], v[160:163], v[182:185], v[52:55]
	v_mfma_f32_16x16x32_bf16 v[52:55], v[164:167], v[186:189], v[52:55]
	v_mfma_f32_16x16x32_bf16 v[36:39], v[160:163], v[190:193], v[36:39]
	v_mfma_f32_16x16x32_bf16 v[36:39], v[164:167], v[194:197], v[36:39]
	v_mfma_f32_16x16x32_bf16 v[20:23], v[160:163], v[198:201], v[20:23]
	v_mfma_f32_16x16x32_bf16 v[20:23], v[164:167], v[208:211], v[20:23]
	v_mfma_f32_16x16x32_bf16 v[8:11], v[160:163], v[212:215], v[8:11]
	v_mfma_f32_16x16x32_bf16 v[8:11], v[164:167], v[216:219], v[8:11]
	v_mfma_f32_16x16x32_bf16 v[60:63], v[152:155], v[182:185], v[60:63]
	v_mfma_f32_16x16x32_bf16 v[60:63], v[156:159], v[186:189], v[60:63]
	v_mfma_f32_16x16x32_bf16 v[48:51], v[152:155], v[190:193], v[48:51]
	v_mfma_f32_16x16x32_bf16 v[48:51], v[156:159], v[194:197], v[48:51]
	v_mfma_f32_16x16x32_bf16 v[32:35], v[152:155], v[198:201], v[32:35]
	v_mfma_f32_16x16x32_bf16 v[32:35], v[156:159], v[208:211], v[32:35]
	v_mfma_f32_16x16x32_bf16 v[16:19], v[152:155], v[212:215], v[16:19]
	v_mfma_f32_16x16x32_bf16 v[16:19], v[156:159], v[216:219], v[16:19]
	v_mfma_f32_16x16x32_bf16 v[44:47], v[174:177], v[182:185], v[44:47]
	v_mfma_f32_16x16x32_bf16 v[44:47], v[178:181], v[186:189], v[44:47]
	v_mfma_f32_16x16x32_bf16 v[28:31], v[174:177], v[190:193], v[28:31]
	v_mfma_f32_16x16x32_bf16 v[28:31], v[178:181], v[194:197], v[28:31]
	v_mfma_f32_16x16x32_bf16 v[12:15], v[174:177], v[198:201], v[12:15]
	v_mfma_f32_16x16x32_bf16 v[12:15], v[178:181], v[208:211], v[12:15]
	v_mfma_f32_16x16x32_bf16 v[4:7], v[174:177], v[212:215], v[4:7]
	v_mfma_f32_16x16x32_bf16 v[4:7], v[178:181], v[216:219], v[4:7]
	s_setprio 0
	s_barrier
	s_sleep 1
	s_add_i32 s71, 0, 0x18000
	s_add_i32 s73, 0, 0x1c000
	s_add_u32 s44, s44, 0x80000
	s_addc_u32 s45, s45, 0
	s_mov_b32 m0, s55
	v_lshl_add_u64 v[222:223], s[44:45], 0, v[0:1]
	global_load_lds_dwordx4 v[222:223], off
	v_lshl_add_u64 v[222:223], s[44:45], 0, v[140:141]
	s_mov_b32 m0, s56
	s_nop 0
	global_load_lds_dwordx4 v[222:223], off
	v_add_u32_e32 v156, s71, v169
	v_add_u32_e32 v178, s73, v169
	ds_read_b128 v[132:135], v156
	ds_read_b128 v[136:139], v156 offset:1024
	ds_read_b128 v[152:155], v156 offset:2048
	ds_read_b128 v[156:159], v156 offset:3072
	ds_read_b128 v[160:163], v178
	ds_read_b128 v[164:167], v178 offset:1024
	ds_read_b128 v[174:177], v178 offset:2048
	ds_read_b128 v[178:181], v178 offset:3072
	ds_read_b128 v[182:185], v171 offset:32768
	ds_read_b128 v[186:189], v171 offset:33792
	ds_read_b128 v[190:193], v171 offset:34816
	ds_read_b128 v[194:197], v171 offset:35840
	ds_read_b128 v[198:201], v171 offset:36864
	ds_read_b128 v[208:211], v171 offset:37888
	ds_read_b128 v[212:215], v171 offset:38912
	ds_read_b128 v[216:219], v171 offset:39936
	s_waitcnt vmcnt(8)
	s_waitcnt lgkmcnt(0)
	s_barrier
	s_setprio 1
	s_waitcnt lgkmcnt(0)
	v_mfma_f32_16x16x32_bf16 v[128:131], v[132:135], v[182:185], v[128:131]
	v_mfma_f32_16x16x32_bf16 v[128:131], v[136:139], v[186:189], v[128:131]
	v_mfma_f32_16x16x32_bf16 v[120:123], v[132:135], v[190:193], v[120:123]
	v_mfma_f32_16x16x32_bf16 v[120:123], v[136:139], v[194:197], v[120:123]
	v_mfma_f32_16x16x32_bf16 v[104:107], v[132:135], v[198:201], v[104:107]
	v_mfma_f32_16x16x32_bf16 v[104:107], v[136:139], v[208:211], v[104:107]
	v_mfma_f32_16x16x32_bf16 v[88:91], v[132:135], v[212:215], v[88:91]
	v_mfma_f32_16x16x32_bf16 v[88:91], v[136:139], v[216:219], v[88:91]
	v_mfma_f32_16x16x32_bf16 v[116:119], v[160:163], v[182:185], v[116:119]
	v_mfma_f32_16x16x32_bf16 v[116:119], v[164:167], v[186:189], v[116:119]
	v_mfma_f32_16x16x32_bf16 v[100:103], v[160:163], v[190:193], v[100:103]
	v_mfma_f32_16x16x32_bf16 v[100:103], v[164:167], v[194:197], v[100:103]
	v_mfma_f32_16x16x32_bf16 v[84:87], v[160:163], v[198:201], v[84:87]
	v_mfma_f32_16x16x32_bf16 v[84:87], v[164:167], v[208:211], v[84:87]
	v_mfma_f32_16x16x32_bf16 v[72:75], v[160:163], v[212:215], v[72:75]
	v_mfma_f32_16x16x32_bf16 v[72:75], v[164:167], v[216:219], v[72:75]
	v_mfma_f32_16x16x32_bf16 v[124:127], v[152:155], v[182:185], v[124:127]
	v_mfma_f32_16x16x32_bf16 v[124:127], v[156:159], v[186:189], v[124:127]
	v_mfma_f32_16x16x32_bf16 v[112:115], v[152:155], v[190:193], v[112:115]
	v_mfma_f32_16x16x32_bf16 v[112:115], v[156:159], v[194:197], v[112:115]
	v_mfma_f32_16x16x32_bf16 v[96:99], v[152:155], v[198:201], v[96:99]
	v_mfma_f32_16x16x32_bf16 v[96:99], v[156:159], v[208:211], v[96:99]
	v_mfma_f32_16x16x32_bf16 v[80:83], v[152:155], v[212:215], v[80:83]
	v_mfma_f32_16x16x32_bf16 v[80:83], v[156:159], v[216:219], v[80:83]
	v_mfma_f32_16x16x32_bf16 v[108:111], v[174:177], v[182:185], v[108:111]
	v_mfma_f32_16x16x32_bf16 v[108:111], v[178:181], v[186:189], v[108:111]
	v_mfma_f32_16x16x32_bf16 v[92:95], v[174:177], v[190:193], v[92:95]
	v_mfma_f32_16x16x32_bf16 v[92:95], v[178:181], v[194:197], v[92:95]
	v_mfma_f32_16x16x32_bf16 v[76:79], v[174:177], v[198:201], v[76:79]
	v_mfma_f32_16x16x32_bf16 v[76:79], v[178:181], v[208:211], v[76:79]
	v_mfma_f32_16x16x32_bf16 v[68:71], v[174:177], v[212:215], v[68:71]
	v_mfma_f32_16x16x32_bf16 v[68:71], v[178:181], v[216:219], v[68:71]
	s_setprio 0
	s_barrier
	s_sleep 2
	s_add_i32 s44, s71, s51
	v_lshl_add_u64 v[202:203], v[202:203], 0, s[66:67]
	s_mov_b32 m0, s44
	ds_read_b128 v[182:185], v171 offset:49152
	ds_read_b128 v[186:189], v171 offset:50176
	ds_read_b128 v[190:193], v171 offset:51200
	ds_read_b128 v[194:197], v171 offset:52224
	ds_read_b128 v[198:201], v171 offset:53248
	ds_read_b128 v[208:211], v171 offset:54272
	ds_read_b128 v[212:215], v171 offset:55296
	ds_read_b128 v[216:219], v171 offset:56320
	global_load_lds_dwordx4 v[202:203], off
	s_add_i32 m0, s44, 0x2000
	s_add_u32 s42, s42, 0x80080
	v_lshl_add_u64 v[202:203], v[204:205], 0, s[66:67]
	s_addc_u32 s43, s43, 0
	s_add_i32 s44, s73, s51
	global_load_lds_dwordx4 v[202:203], off
	v_lshl_add_u64 v[202:203], s[42:43], 0, v[2:3]
	s_mov_b32 m0, s44
	s_nop 0
	global_load_lds_dwordx4 v[202:203], off
	v_lshl_add_u64 v[202:203], s[42:43], 0, v[142:143]
	s_add_i32 m0, s44, 0x2000
	s_nop 0
	global_load_lds_dwordx4 v[202:203], off
	v_lshl_add_u64 v[202:203], v[206:207], 0, s[66:67]
	s_mov_b32 m0, s65
	s_nop 0
	global_load_lds_dwordx4 v[202:203], off
	v_lshl_add_u64 v[202:203], v[220:221], 0, s[66:67]
	s_mov_b32 m0, s68
	s_nop 0
	global_load_lds_dwordx4 v[202:203], off
	s_waitcnt vmcnt(8)
	s_waitcnt lgkmcnt(0)
	s_barrier
	s_setprio 1
	s_waitcnt lgkmcnt(0)
	v_mfma_f32_16x16x32_bf16 v[64:67], v[132:135], v[182:185], v[64:67]
	v_mfma_f32_16x16x32_bf16 v[64:67], v[136:139], v[186:189], v[64:67]
	v_mfma_f32_16x16x32_bf16 v[56:59], v[132:135], v[190:193], v[56:59]
	v_mfma_f32_16x16x32_bf16 v[56:59], v[136:139], v[194:197], v[56:59]
	v_mfma_f32_16x16x32_bf16 v[40:43], v[132:135], v[198:201], v[40:43]
	v_mfma_f32_16x16x32_bf16 v[40:43], v[136:139], v[208:211], v[40:43]
	v_mfma_f32_16x16x32_bf16 v[24:27], v[132:135], v[212:215], v[24:27]
	v_mfma_f32_16x16x32_bf16 v[24:27], v[136:139], v[216:219], v[24:27]
	v_mfma_f32_16x16x32_bf16 v[52:55], v[160:163], v[182:185], v[52:55]
	v_mfma_f32_16x16x32_bf16 v[52:55], v[164:167], v[186:189], v[52:55]
	v_mfma_f32_16x16x32_bf16 v[36:39], v[160:163], v[190:193], v[36:39]
	v_mfma_f32_16x16x32_bf16 v[36:39], v[164:167], v[194:197], v[36:39]
	v_mfma_f32_16x16x32_bf16 v[20:23], v[160:163], v[198:201], v[20:23]
	v_mfma_f32_16x16x32_bf16 v[20:23], v[164:167], v[208:211], v[20:23]
	v_mfma_f32_16x16x32_bf16 v[8:11], v[160:163], v[212:215], v[8:11]
	v_mfma_f32_16x16x32_bf16 v[8:11], v[164:167], v[216:219], v[8:11]
	v_mfma_f32_16x16x32_bf16 v[60:63], v[152:155], v[182:185], v[60:63]
	v_mfma_f32_16x16x32_bf16 v[60:63], v[156:159], v[186:189], v[60:63]
	v_mfma_f32_16x16x32_bf16 v[48:51], v[152:155], v[190:193], v[48:51]
	v_mfma_f32_16x16x32_bf16 v[48:51], v[156:159], v[194:197], v[48:51]
	v_mfma_f32_16x16x32_bf16 v[32:35], v[152:155], v[198:201], v[32:35]
	v_mfma_f32_16x16x32_bf16 v[32:35], v[156:159], v[208:211], v[32:35]
	v_mfma_f32_16x16x32_bf16 v[16:19], v[152:155], v[212:215], v[16:19]
	v_mfma_f32_16x16x32_bf16 v[16:19], v[156:159], v[216:219], v[16:19]
	v_mfma_f32_16x16x32_bf16 v[44:47], v[174:177], v[182:185], v[44:47]
	v_mfma_f32_16x16x32_bf16 v[44:47], v[178:181], v[186:189], v[44:47]
	v_mfma_f32_16x16x32_bf16 v[28:31], v[174:177], v[190:193], v[28:31]
	v_mfma_f32_16x16x32_bf16 v[28:31], v[178:181], v[194:197], v[28:31]
	v_mfma_f32_16x16x32_bf16 v[12:15], v[174:177], v[198:201], v[12:15]
	v_mfma_f32_16x16x32_bf16 v[12:15], v[178:181], v[208:211], v[12:15]
	v_mfma_f32_16x16x32_bf16 v[4:7], v[174:177], v[212:215], v[4:7]
	v_mfma_f32_16x16x32_bf16 v[4:7], v[178:181], v[216:219], v[4:7]
	s_setprio 0
	s_barrier
	s_add_i32 s63, s63, 2
	s_add_u32 s40, s40, 0x100
	s_addc_u32 s41, s41, 0
	s_add_u32 s31, s31, 0x100
	s_addc_u32 s62, s62, 0
	s_cmp_gt_u32 s63, 29
	s_cbranch_scc0 .LBB0_147
	s_and_b64 vcc, exec, s[18:19]
	s_cbranch_vccz .LBB0_150
	s_barrier

.LBB0_210:
	s_ashr_i32 s21, s20, 31
	s_lshl_b64 s[22:23], s[20:21], 20
	s_add_u32 s22, s4, s22
	s_addc_u32 s23, s5, s23
	s_and_b64 s[24:25], s[34:35], exec
	s_cselect_b32 s21, s23, s29
	s_cselect_b32 s53, s22, s28
	s_ashr_i32 s19, s18, 31
	s_lshl_b64 s[24:25], s[18:19], 20
	s_add_u32 s24, s2, s24
	s_addc_u32 s25, s40, s25
	s_and_b64 s[38:39], s[34:35], exec
	s_cselect_b32 s19, s25, s31
	s_cselect_b32 s54, s24, s30
	s_add_u32 s28, s28, 0x80080
	s_addc_u32 s29, s29, 0
	s_add_u32 s55, s30, 0x100
	s_addc_u32 s56, s31, 0
	s_mov_b32 s57, -2
	s_sleep 1
	s_add_u32 s30, s28, 0xfff80080
	s_addc_u32 s31, s29, -1
	s_add_i32 s58, 0, 0x10000
	s_cmp_eq_u32 s57, 28
	s_cselect_b32 s39, s21, s31
	s_cselect_b32 s38, s53, s30
	s_cselect_b32 s31, s19, s56
	s_cselect_b32 s30, s54, s55
	s_add_i32 s60, 0, 0x14000
	s_add_i32 m0, s43, 0xc000
	s_nop 0
	global_load_lds_dwordx4 v136, s[28:29]
	s_add_i32 m0, s43, 0xe000
	s_nop 0
	global_load_lds_dwordx4 v138, s[28:29]
	v_add_u32_e32 v148, s58, v151
	ds_read_b128 v[140:143], v148
	ds_read_b128 v[144:147], v148 offset:1024
	ds_read_b128 v[156:159], v148 offset:2048
	ds_read_b128 v[160:163], v148 offset:3072
	v_add_u32_e32 v148, s60, v151
	ds_read_b128 v[164:167], v148
	ds_read_b128 v[168:171], v148 offset:1024
	ds_read_b128 v[172:175], v148 offset:2048
	ds_read_b128 v[176:179], v148 offset:3072
	ds_read_b128 v[180:183], v154
	ds_read_b128 v[184:187], v154 offset:1024
	ds_read_b128 v[188:191], v154 offset:2048
	ds_read_b128 v[192:195], v154 offset:3072
	ds_read_b128 v[196:199], v154 offset:4096
	ds_read_b128 v[200:203], v154 offset:5120
	ds_read_b128 v[208:211], v154 offset:6144
	ds_read_b128 v[212:215], v154 offset:7168
	s_waitcnt vmcnt(8)
	s_waitcnt lgkmcnt(0)
	s_barrier
	s_setprio 1
	s_waitcnt lgkmcnt(0)
	v_mfma_f32_16x16x32_bf16 v[128:131], v[140:143], v[180:183], 0
	v_mfma_f32_16x16x32_bf16 v[128:131], v[144:147], v[184:187], v[128:131]
	v_mfma_f32_16x16x32_bf16 v[112:115], v[140:143], v[188:191], 0
	v_mfma_f32_16x16x32_bf16 v[112:115], v[144:147], v[192:195], v[112:115]
	v_mfma_f32_16x16x32_bf16 v[96:99], v[140:143], v[196:199], 0
	v_mfma_f32_16x16x32_bf16 v[96:99], v[144:147], v[200:203], v[96:99]
	v_mfma_f32_16x16x32_bf16 v[80:83], v[140:143], v[208:211], 0
	v_mfma_f32_16x16x32_bf16 v[80:83], v[144:147], v[212:215], v[80:83]
	v_mfma_f32_16x16x32_bf16 v[120:123], v[164:167], v[180:183], 0
	v_mfma_f32_16x16x32_bf16 v[120:123], v[168:171], v[184:187], v[120:123]
	v_mfma_f32_16x16x32_bf16 v[104:107], v[164:167], v[188:191], 0
	v_mfma_f32_16x16x32_bf16 v[104:107], v[168:171], v[192:195], v[104:107]
	v_mfma_f32_16x16x32_bf16 v[88:91], v[164:167], v[196:199], 0
	v_mfma_f32_16x16x32_bf16 v[88:91], v[168:171], v[200:203], v[88:91]
	v_mfma_f32_16x16x32_bf16 v[72:75], v[164:167], v[208:211], 0
	v_mfma_f32_16x16x32_bf16 v[72:75], v[168:171], v[212:215], v[72:75]
	v_mfma_f32_16x16x32_bf16 v[124:127], v[156:159], v[180:183], 0
	v_mfma_f32_16x16x32_bf16 v[124:127], v[160:163], v[184:187], v[124:127]
	v_mfma_f32_16x16x32_bf16 v[108:111], v[156:159], v[188:191], 0
	v_mfma_f32_16x16x32_bf16 v[108:111], v[160:163], v[192:195], v[108:111]
	v_mfma_f32_16x16x32_bf16 v[92:95], v[156:159], v[196:199], 0
	v_mfma_f32_16x16x32_bf16 v[92:95], v[160:163], v[200:203], v[92:95]
	v_mfma_f32_16x16x32_bf16 v[76:79], v[156:159], v[208:211], 0
	v_mfma_f32_16x16x32_bf16 v[76:79], v[160:163], v[212:215], v[76:79]
	v_mfma_f32_16x16x32_bf16 v[116:119], v[172:175], v[180:183], 0
	v_mfma_f32_16x16x32_bf16 v[116:119], v[176:179], v[184:187], v[116:119]
	v_mfma_f32_16x16x32_bf16 v[100:103], v[172:175], v[188:191], 0
	v_mfma_f32_16x16x32_bf16 v[100:103], v[176:179], v[192:195], v[100:103]
	v_mfma_f32_16x16x32_bf16 v[84:87], v[172:175], v[196:199], 0
	v_mfma_f32_16x16x32_bf16 v[84:87], v[176:179], v[200:203], v[84:87]
	v_mfma_f32_16x16x32_bf16 v[68:71], v[172:175], v[208:211], 0
	v_mfma_f32_16x16x32_bf16 v[68:71], v[176:179], v[212:215], v[68:71]
	s_setprio 0
	s_barrier
	s_sleep 2
	s_add_i32 s58, s58, s41
	s_mov_b32 m0, s58
	ds_read_b128 v[180:183], v154 offset:16384
	ds_read_b128 v[184:187], v154 offset:17408
	ds_read_b128 v[188:191], v154 offset:18432
	ds_read_b128 v[192:195], v154 offset:19456
	ds_read_b128 v[196:199], v154 offset:20480
	ds_read_b128 v[200:203], v154 offset:21504
	ds_read_b128 v[208:211], v154 offset:22528
	ds_read_b128 v[212:215], v154 offset:23552
	global_load_lds_dwordx4 v2, s[30:31]
	s_add_i32 m0, s58, 0x2000
	s_add_u32 s62, s30, 0x80000
	s_addc_u32 s63, s31, 0
	s_add_i32 s58, s60, s41
	global_load_lds_dwordx4 v0, s[30:31]
	s_mov_b32 m0, s58
	s_nop 0
	global_load_lds_dwordx4 v2, s[62:63]
	s_add_i32 m0, s58, 0x2000
	s_nop 0
	global_load_lds_dwordx4 v0, s[62:63]
	s_mov_b32 m0, s43
	s_nop 0
	global_load_lds_dwordx4 v134, s[38:39]
	s_mov_b32 m0, s44
	s_nop 0
	global_load_lds_dwordx4 v132, s[38:39]
	s_waitcnt vmcnt(8)
	s_waitcnt lgkmcnt(0)
	s_barrier
	s_setprio 1
	s_waitcnt lgkmcnt(0)
	v_mfma_f32_16x16x32_bf16 v[64:67], v[140:143], v[180:183], 0
	v_mfma_f32_16x16x32_bf16 v[64:67], v[144:147], v[184:187], v[64:67]
	v_mfma_f32_16x16x32_bf16 v[48:51], v[140:143], v[188:191], 0
	v_mfma_f32_16x16x32_bf16 v[48:51], v[144:147], v[192:195], v[48:51]
	v_mfma_f32_16x16x32_bf16 v[32:35], v[140:143], v[196:199], 0
	v_mfma_f32_16x16x32_bf16 v[32:35], v[144:147], v[200:203], v[32:35]
	v_mfma_f32_16x16x32_bf16 v[16:19], v[140:143], v[208:211], 0
	v_mfma_f32_16x16x32_bf16 v[16:19], v[144:147], v[212:215], v[16:19]
	v_mfma_f32_16x16x32_bf16 v[56:59], v[164:167], v[180:183], 0
	v_mfma_f32_16x16x32_bf16 v[56:59], v[168:171], v[184:187], v[56:59]
	v_mfma_f32_16x16x32_bf16 v[40:43], v[164:167], v[188:191], 0
	v_mfma_f32_16x16x32_bf16 v[40:43], v[168:171], v[192:195], v[40:43]
	v_mfma_f32_16x16x32_bf16 v[24:27], v[164:167], v[196:199], 0
	v_mfma_f32_16x16x32_bf16 v[24:27], v[168:171], v[200:203], v[24:27]
	v_mfma_f32_16x16x32_bf16 v[8:11], v[164:167], v[208:211], 0
	v_mfma_f32_16x16x32_bf16 v[8:11], v[168:171], v[212:215], v[8:11]
	v_mfma_f32_16x16x32_bf16 v[60:63], v[156:159], v[180:183], 0
	v_mfma_f32_16x16x32_bf16 v[60:63], v[160:163], v[184:187], v[60:63]
	v_mfma_f32_16x16x32_bf16 v[44:47], v[156:159], v[188:191], 0
	v_mfma_f32_16x16x32_bf16 v[44:47], v[160:163], v[192:195], v[44:47]
	v_mfma_f32_16x16x32_bf16 v[28:31], v[156:159], v[196:199], 0
	v_mfma_f32_16x16x32_bf16 v[28:31], v[160:163], v[200:203], v[28:31]
	v_mfma_f32_16x16x32_bf16 v[12:15], v[156:159], v[208:211], 0
	v_mfma_f32_16x16x32_bf16 v[12:15], v[160:163], v[212:215], v[12:15]
	v_mfma_f32_16x16x32_bf16 v[52:55], v[172:175], v[180:183], 0
	v_mfma_f32_16x16x32_bf16 v[52:55], v[176:179], v[184:187], v[52:55]
	v_mfma_f32_16x16x32_bf16 v[36:39], v[172:175], v[188:191], 0
	v_mfma_f32_16x16x32_bf16 v[36:39], v[176:179], v[192:195], v[36:39]
	v_mfma_f32_16x16x32_bf16 v[20:23], v[172:175], v[196:199], 0
	v_mfma_f32_16x16x32_bf16 v[20:23], v[176:179], v[200:203], v[20:23]
	v_mfma_f32_16x16x32_bf16 v[4:7], v[172:175], v[208:211], 0
	v_mfma_f32_16x16x32_bf16 v[4:7], v[176:179], v[212:215], v[4:7]
	s_setprio 0
	s_barrier
	s_sleep 1
	s_add_i32 s58, 0, 0x18000
	s_add_i32 s60, 0, 0x1c000
	s_add_u32 s38, s38, 0x80000
	s_addc_u32 s39, s39, 0
	s_mov_b32 m0, s45
	s_nop 0
	global_load_lds_dwordx4 v134, s[38:39]
	s_mov_b32 m0, s47
	s_nop 0
	global_load_lds_dwordx4 v132, s[38:39]
	v_add_u32_e32 v155, s58, v151
	ds_read_b128 v[140:143], v155
	ds_read_b128 v[144:147], v155 offset:1024
	ds_read_b128 v[156:159], v155 offset:2048
	ds_read_b128 v[160:163], v155 offset:3072
	v_add_u32_e32 v155, s60, v151
	ds_read_b128 v[164:167], v155
	ds_read_b128 v[168:171], v155 offset:1024
	ds_read_b128 v[172:175], v155 offset:2048
	ds_read_b128 v[176:179], v155 offset:3072
	ds_read_b128 v[180:183], v154 offset:32768
	ds_read_b128 v[184:187], v154 offset:33792
	ds_read_b128 v[188:191], v154 offset:34816
	ds_read_b128 v[192:195], v154 offset:35840
	ds_read_b128 v[196:199], v154 offset:36864
	ds_read_b128 v[200:203], v154 offset:37888
	ds_read_b128 v[208:211], v154 offset:38912
	ds_read_b128 v[212:215], v154 offset:39936
	s_waitcnt vmcnt(8)
	s_waitcnt lgkmcnt(0)
	s_barrier
	s_setprio 1
	s_waitcnt lgkmcnt(0)
	v_mfma_f32_16x16x32_bf16 v[128:131], v[140:143], v[180:183], v[128:131]
	v_mfma_f32_16x16x32_bf16 v[128:131], v[144:147], v[184:187], v[128:131]
	v_mfma_f32_16x16x32_bf16 v[112:115], v[140:143], v[188:191], v[112:115]
	v_mfma_f32_16x16x32_bf16 v[112:115], v[144:147], v[192:195], v[112:115]
	v_mfma_f32_16x16x32_bf16 v[96:99], v[140:143], v[196:199], v[96:99]
	v_mfma_f32_16x16x32_bf16 v[96:99], v[144:147], v[200:203], v[96:99]
	v_mfma_f32_16x16x32_bf16 v[80:83], v[140:143], v[208:211], v[80:83]
	v_mfma_f32_16x16x32_bf16 v[80:83], v[144:147], v[212:215], v[80:83]
	v_mfma_f32_16x16x32_bf16 v[120:123], v[164:167], v[180:183], v[120:123]
	v_mfma_f32_16x16x32_bf16 v[120:123], v[168:171], v[184:187], v[120:123]
	v_mfma_f32_16x16x32_bf16 v[104:107], v[164:167], v[188:191], v[104:107]
	v_mfma_f32_16x16x32_bf16 v[104:107], v[168:171], v[192:195], v[104:107]
	v_mfma_f32_16x16x32_bf16 v[88:91], v[164:167], v[196:199], v[88:91]
	v_mfma_f32_16x16x32_bf16 v[88:91], v[168:171], v[200:203], v[88:91]
	v_mfma_f32_16x16x32_bf16 v[72:75], v[164:167], v[208:211], v[72:75]
	v_mfma_f32_16x16x32_bf16 v[72:75], v[168:171], v[212:215], v[72:75]
	v_mfma_f32_16x16x32_bf16 v[124:127], v[156:159], v[180:183], v[124:127]
	v_mfma_f32_16x16x32_bf16 v[124:127], v[160:163], v[184:187], v[124:127]
	v_mfma_f32_16x16x32_bf16 v[108:111], v[156:159], v[188:191], v[108:111]
	v_mfma_f32_16x16x32_bf16 v[108:111], v[160:163], v[192:195], v[108:111]
	v_mfma_f32_16x16x32_bf16 v[92:95], v[156:159], v[196:199], v[92:95]
	v_mfma_f32_16x16x32_bf16 v[92:95], v[160:163], v[200:203], v[92:95]
	v_mfma_f32_16x16x32_bf16 v[76:79], v[156:159], v[208:211], v[76:79]
	v_mfma_f32_16x16x32_bf16 v[76:79], v[160:163], v[212:215], v[76:79]
	v_mfma_f32_16x16x32_bf16 v[116:119], v[172:175], v[180:183], v[116:119]
	v_mfma_f32_16x16x32_bf16 v[116:119], v[176:179], v[184:187], v[116:119]
	v_mfma_f32_16x16x32_bf16 v[100:103], v[172:175], v[188:191], v[100:103]
	v_mfma_f32_16x16x32_bf16 v[100:103], v[176:179], v[192:195], v[100:103]
	v_mfma_f32_16x16x32_bf16 v[84:87], v[172:175], v[196:199], v[84:87]
	v_mfma_f32_16x16x32_bf16 v[84:87], v[176:179], v[200:203], v[84:87]
	v_mfma_f32_16x16x32_bf16 v[68:71], v[172:175], v[208:211], v[68:71]
	v_mfma_f32_16x16x32_bf16 v[68:71], v[176:179], v[212:215], v[68:71]
	s_setprio 0
	s_barrier
	s_sleep 2
	s_add_i32 s62, s58, s41
	s_add_u32 s30, s30, 0x80
	s_addc_u32 s31, s31, 0
	s_mov_b32 m0, s62
	ds_read_b128 v[180:183], v154 offset:49152
	ds_read_b128 v[184:187], v154 offset:50176
	ds_read_b128 v[188:191], v154 offset:51200
	ds_read_b128 v[192:195], v154 offset:52224
	ds_read_b128 v[196:199], v154 offset:53248
	ds_read_b128 v[200:203], v154 offset:54272
	ds_read_b128 v[208:211], v154 offset:55296
	ds_read_b128 v[212:215], v154 offset:56320
	global_load_lds_dwordx4 v2, s[30:31]
	s_add_i32 m0, s62, 0x2000
	s_nop 0
	s_add_i32 s62, s60, s41
	global_load_lds_dwordx4 v0, s[30:31]
	s_add_u32 s30, s30, 0x80000
	s_addc_u32 s31, s31, 0
	s_mov_b32 m0, s62
	s_nop 0
	global_load_lds_dwordx4 v2, s[30:31]
	s_add_i32 m0, s62, 0x2000
	s_nop 0
	global_load_lds_dwordx4 v0, s[30:31]
	s_sub_u32 s38, s38, 0x7ff80
	s_subb_u32 s39, s39, 0
	s_mov_b32 m0, s48
	s_nop 0
	global_load_lds_dwordx4 v134, s[38:39]
	s_mov_b32 m0, s49
	s_nop 0
	global_load_lds_dwordx4 v132, s[38:39]
	s_waitcnt vmcnt(8)
	s_waitcnt lgkmcnt(0)
	s_barrier
	s_setprio 1
	s_waitcnt lgkmcnt(0)
	v_mfma_f32_16x16x32_bf16 v[64:67], v[140:143], v[180:183], v[64:67]
	v_mfma_f32_16x16x32_bf16 v[64:67], v[144:147], v[184:187], v[64:67]
	v_mfma_f32_16x16x32_bf16 v[48:51], v[140:143], v[188:191], v[48:51]
	v_mfma_f32_16x16x32_bf16 v[48:51], v[144:147], v[192:195], v[48:51]
	v_mfma_f32_16x16x32_bf16 v[32:35], v[140:143], v[196:199], v[32:35]
	v_mfma_f32_16x16x32_bf16 v[32:35], v[144:147], v[200:203], v[32:35]
	v_mfma_f32_16x16x32_bf16 v[16:19], v[140:143], v[208:211], v[16:19]
	v_mfma_f32_16x16x32_bf16 v[16:19], v[144:147], v[212:215], v[16:19]
	v_mfma_f32_16x16x32_bf16 v[56:59], v[164:167], v[180:183], v[56:59]
	v_mfma_f32_16x16x32_bf16 v[56:59], v[168:171], v[184:187], v[56:59]
	v_mfma_f32_16x16x32_bf16 v[40:43], v[164:167], v[188:191], v[40:43]
	v_mfma_f32_16x16x32_bf16 v[40:43], v[168:171], v[192:195], v[40:43]
	v_mfma_f32_16x16x32_bf16 v[24:27], v[164:167], v[196:199], v[24:27]
	v_mfma_f32_16x16x32_bf16 v[24:27], v[168:171], v[200:203], v[24:27]
	v_mfma_f32_16x16x32_bf16 v[8:11], v[164:167], v[208:211], v[8:11]
	v_mfma_f32_16x16x32_bf16 v[8:11], v[168:171], v[212:215], v[8:11]
	v_mfma_f32_16x16x32_bf16 v[60:63], v[156:159], v[180:183], v[60:63]
	v_mfma_f32_16x16x32_bf16 v[60:63], v[160:163], v[184:187], v[60:63]
	v_mfma_f32_16x16x32_bf16 v[44:47], v[156:159], v[188:191], v[44:47]
	v_mfma_f32_16x16x32_bf16 v[44:47], v[160:163], v[192:195], v[44:47]
	v_mfma_f32_16x16x32_bf16 v[28:31], v[156:159], v[196:199], v[28:31]
	v_mfma_f32_16x16x32_bf16 v[28:31], v[160:163], v[200:203], v[28:31]
	v_mfma_f32_16x16x32_bf16 v[12:15], v[156:159], v[208:211], v[12:15]
	v_mfma_f32_16x16x32_bf16 v[12:15], v[160:163], v[212:215], v[12:15]
	v_mfma_f32_16x16x32_bf16 v[52:55], v[172:175], v[180:183], v[52:55]
	v_mfma_f32_16x16x32_bf16 v[52:55], v[176:179], v[184:187], v[52:55]
	v_mfma_f32_16x16x32_bf16 v[36:39], v[172:175], v[188:191], v[36:39]
	v_mfma_f32_16x16x32_bf16 v[36:39], v[176:179], v[192:195], v[36:39]
	v_mfma_f32_16x16x32_bf16 v[20:23], v[172:175], v[196:199], v[20:23]
	v_mfma_f32_16x16x32_bf16 v[20:23], v[176:179], v[200:203], v[20:23]
	v_mfma_f32_16x16x32_bf16 v[4:7], v[172:175], v[208:211], v[4:7]
	v_mfma_f32_16x16x32_bf16 v[4:7], v[176:179], v[212:215], v[4:7]
	s_setprio 0
	s_barrier
	s_add_i32 s57, s57, 2
	s_add_u32 s28, s28, 0x100
	s_addc_u32 s29, s29, 0
	s_add_u32 s55, s55, 0x100
	s_addc_u32 s56, s56, 0
	s_cmp_gt_u32 s57, 29
.LBB0_211:
	s_sleep 1
	s_add_u32 s30, s28, 0xfff80080
	s_addc_u32 s31, s29, -1
	s_add_i32 s58, 0, 0x10000
	s_cmp_eq_u32 s57, 28
	s_cselect_b32 s39, s21, s31
	s_cselect_b32 s38, s53, s30
	s_cselect_b32 s31, s19, s56
	s_cselect_b32 s30, s54, s55
	s_add_i32 s60, 0, 0x14000
	s_add_i32 m0, s43, 0xc000
	s_nop 0
	global_load_lds_dwordx4 v136, s[28:29]
	s_add_i32 m0, s43, 0xe000
	s_nop 0
	global_load_lds_dwordx4 v138, s[28:29]
	v_add_u32_e32 v148, s58, v151
	ds_read_b128 v[140:143], v148
	ds_read_b128 v[144:147], v148 offset:1024
	ds_read_b128 v[156:159], v148 offset:2048
	ds_read_b128 v[160:163], v148 offset:3072
	v_add_u32_e32 v148, s60, v151
	ds_read_b128 v[164:167], v148
	ds_read_b128 v[168:171], v148 offset:1024
	ds_read_b128 v[172:175], v148 offset:2048
	ds_read_b128 v[176:179], v148 offset:3072
	ds_read_b128 v[180:183], v154
	ds_read_b128 v[184:187], v154 offset:1024
	ds_read_b128 v[188:191], v154 offset:2048
	ds_read_b128 v[192:195], v154 offset:3072
	ds_read_b128 v[196:199], v154 offset:4096
	ds_read_b128 v[200:203], v154 offset:5120
	ds_read_b128 v[208:211], v154 offset:6144
	ds_read_b128 v[212:215], v154 offset:7168
	s_waitcnt vmcnt(8)
	s_waitcnt lgkmcnt(0)
	s_barrier
	s_setprio 1
	s_waitcnt lgkmcnt(0)
	v_mfma_f32_16x16x32_bf16 v[128:131], v[140:143], v[180:183], v[128:131]
	v_mfma_f32_16x16x32_bf16 v[128:131], v[144:147], v[184:187], v[128:131]
	v_mfma_f32_16x16x32_bf16 v[112:115], v[140:143], v[188:191], v[112:115]
	v_mfma_f32_16x16x32_bf16 v[112:115], v[144:147], v[192:195], v[112:115]
	v_mfma_f32_16x16x32_bf16 v[96:99], v[140:143], v[196:199], v[96:99]
	v_mfma_f32_16x16x32_bf16 v[96:99], v[144:147], v[200:203], v[96:99]
	v_mfma_f32_16x16x32_bf16 v[80:83], v[140:143], v[208:211], v[80:83]
	v_mfma_f32_16x16x32_bf16 v[80:83], v[144:147], v[212:215], v[80:83]
	v_mfma_f32_16x16x32_bf16 v[120:123], v[164:167], v[180:183], v[120:123]
	v_mfma_f32_16x16x32_bf16 v[120:123], v[168:171], v[184:187], v[120:123]
	v_mfma_f32_16x16x32_bf16 v[104:107], v[164:167], v[188:191], v[104:107]
	v_mfma_f32_16x16x32_bf16 v[104:107], v[168:171], v[192:195], v[104:107]
	v_mfma_f32_16x16x32_bf16 v[88:91], v[164:167], v[196:199], v[88:91]
	v_mfma_f32_16x16x32_bf16 v[88:91], v[168:171], v[200:203], v[88:91]
	v_mfma_f32_16x16x32_bf16 v[72:75], v[164:167], v[208:211], v[72:75]
	v_mfma_f32_16x16x32_bf16 v[72:75], v[168:171], v[212:215], v[72:75]
	v_mfma_f32_16x16x32_bf16 v[124:127], v[156:159], v[180:183], v[124:127]
	v_mfma_f32_16x16x32_bf16 v[124:127], v[160:163], v[184:187], v[124:127]
	v_mfma_f32_16x16x32_bf16 v[108:111], v[156:159], v[188:191], v[108:111]
	v_mfma_f32_16x16x32_bf16 v[108:111], v[160:163], v[192:195], v[108:111]
	v_mfma_f32_16x16x32_bf16 v[92:95], v[156:159], v[196:199], v[92:95]
	v_mfma_f32_16x16x32_bf16 v[92:95], v[160:163], v[200:203], v[92:95]
	v_mfma_f32_16x16x32_bf16 v[76:79], v[156:159], v[208:211], v[76:79]
	v_mfma_f32_16x16x32_bf16 v[76:79], v[160:163], v[212:215], v[76:79]
	v_mfma_f32_16x16x32_bf16 v[116:119], v[172:175], v[180:183], v[116:119]
	v_mfma_f32_16x16x32_bf16 v[116:119], v[176:179], v[184:187], v[116:119]
	v_mfma_f32_16x16x32_bf16 v[100:103], v[172:175], v[188:191], v[100:103]
	v_mfma_f32_16x16x32_bf16 v[100:103], v[176:179], v[192:195], v[100:103]
	v_mfma_f32_16x16x32_bf16 v[84:87], v[172:175], v[196:199], v[84:87]
	v_mfma_f32_16x16x32_bf16 v[84:87], v[176:179], v[200:203], v[84:87]
	v_mfma_f32_16x16x32_bf16 v[68:71], v[172:175], v[208:211], v[68:71]
	v_mfma_f32_16x16x32_bf16 v[68:71], v[176:179], v[212:215], v[68:71]
	s_setprio 0
	s_barrier
	s_sleep 2
	s_add_i32 s58, s58, s41
	s_mov_b32 m0, s58
	ds_read_b128 v[180:183], v154 offset:16384
	ds_read_b128 v[184:187], v154 offset:17408
	ds_read_b128 v[188:191], v154 offset:18432
	ds_read_b128 v[192:195], v154 offset:19456
	ds_read_b128 v[196:199], v154 offset:20480
	ds_read_b128 v[200:203], v154 offset:21504
	ds_read_b128 v[208:211], v154 offset:22528
	ds_read_b128 v[212:215], v154 offset:23552
	global_load_lds_dwordx4 v2, s[30:31]
	s_add_i32 m0, s58, 0x2000
	s_add_u32 s62, s30, 0x80000
	s_addc_u32 s63, s31, 0
	s_add_i32 s58, s60, s41
	global_load_lds_dwordx4 v0, s[30:31]
	s_mov_b32 m0, s58
	s_nop 0
	global_load_lds_dwordx4 v2, s[62:63]
	s_add_i32 m0, s58, 0x2000
	s_nop 0
	global_load_lds_dwordx4 v0, s[62:63]
	s_mov_b32 m0, s43
	s_nop 0
	global_load_lds_dwordx4 v134, s[38:39]
	s_mov_b32 m0, s44
	s_nop 0
	global_load_lds_dwordx4 v132, s[38:39]
	s_waitcnt vmcnt(8)
	s_waitcnt lgkmcnt(0)
	s_barrier
	s_setprio 1
	s_waitcnt lgkmcnt(0)
	v_mfma_f32_16x16x32_bf16 v[64:67], v[140:143], v[180:183], v[64:67]
	v_mfma_f32_16x16x32_bf16 v[64:67], v[144:147], v[184:187], v[64:67]
	v_mfma_f32_16x16x32_bf16 v[48:51], v[140:143], v[188:191], v[48:51]
	v_mfma_f32_16x16x32_bf16 v[48:51], v[144:147], v[192:195], v[48:51]
	v_mfma_f32_16x16x32_bf16 v[32:35], v[140:143], v[196:199], v[32:35]
	v_mfma_f32_16x16x32_bf16 v[32:35], v[144:147], v[200:203], v[32:35]
	v_mfma_f32_16x16x32_bf16 v[16:19], v[140:143], v[208:211], v[16:19]
	v_mfma_f32_16x16x32_bf16 v[16:19], v[144:147], v[212:215], v[16:19]
	v_mfma_f32_16x16x32_bf16 v[56:59], v[164:167], v[180:183], v[56:59]
	v_mfma_f32_16x16x32_bf16 v[56:59], v[168:171], v[184:187], v[56:59]
	v_mfma_f32_16x16x32_bf16 v[40:43], v[164:167], v[188:191], v[40:43]
	v_mfma_f32_16x16x32_bf16 v[40:43], v[168:171], v[192:195], v[40:43]
	v_mfma_f32_16x16x32_bf16 v[24:27], v[164:167], v[196:199], v[24:27]
	v_mfma_f32_16x16x32_bf16 v[24:27], v[168:171], v[200:203], v[24:27]
	v_mfma_f32_16x16x32_bf16 v[8:11], v[164:167], v[208:211], v[8:11]
	v_mfma_f32_16x16x32_bf16 v[8:11], v[168:171], v[212:215], v[8:11]
	v_mfma_f32_16x16x32_bf16 v[60:63], v[156:159], v[180:183], v[60:63]
	v_mfma_f32_16x16x32_bf16 v[60:63], v[160:163], v[184:187], v[60:63]
	v_mfma_f32_16x16x32_bf16 v[44:47], v[156:159], v[188:191], v[44:47]
	v_mfma_f32_16x16x32_bf16 v[44:47], v[160:163], v[192:195], v[44:47]
	v_mfma_f32_16x16x32_bf16 v[28:31], v[156:159], v[196:199], v[28:31]
	v_mfma_f32_16x16x32_bf16 v[28:31], v[160:163], v[200:203], v[28:31]
	v_mfma_f32_16x16x32_bf16 v[12:15], v[156:159], v[208:211], v[12:15]
	v_mfma_f32_16x16x32_bf16 v[12:15], v[160:163], v[212:215], v[12:15]
	v_mfma_f32_16x16x32_bf16 v[52:55], v[172:175], v[180:183], v[52:55]
	v_mfma_f32_16x16x32_bf16 v[52:55], v[176:179], v[184:187], v[52:55]
	v_mfma_f32_16x16x32_bf16 v[36:39], v[172:175], v[188:191], v[36:39]
	v_mfma_f32_16x16x32_bf16 v[36:39], v[176:179], v[192:195], v[36:39]
	v_mfma_f32_16x16x32_bf16 v[20:23], v[172:175], v[196:199], v[20:23]
	v_mfma_f32_16x16x32_bf16 v[20:23], v[176:179], v[200:203], v[20:23]
	v_mfma_f32_16x16x32_bf16 v[4:7], v[172:175], v[208:211], v[4:7]
	v_mfma_f32_16x16x32_bf16 v[4:7], v[176:179], v[212:215], v[4:7]
	s_setprio 0
	s_barrier
	s_sleep 1
	s_add_i32 s58, 0, 0x18000
	s_add_i32 s60, 0, 0x1c000
	s_add_u32 s38, s38, 0x80000
	s_addc_u32 s39, s39, 0
	s_mov_b32 m0, s45
	s_nop 0
	global_load_lds_dwordx4 v134, s[38:39]
	s_mov_b32 m0, s47
	s_nop 0
	global_load_lds_dwordx4 v132, s[38:39]
	v_add_u32_e32 v155, s58, v151
	ds_read_b128 v[140:143], v155
	ds_read_b128 v[144:147], v155 offset:1024
	ds_read_b128 v[156:159], v155 offset:2048
	ds_read_b128 v[160:163], v155 offset:3072
	v_add_u32_e32 v155, s60, v151
	ds_read_b128 v[164:167], v155
	ds_read_b128 v[168:171], v155 offset:1024
	ds_read_b128 v[172:175], v155 offset:2048
	ds_read_b128 v[176:179], v155 offset:3072
	ds_read_b128 v[180:183], v154 offset:32768
	ds_read_b128 v[184:187], v154 offset:33792
	ds_read_b128 v[188:191], v154 offset:34816
	ds_read_b128 v[192:195], v154 offset:35840
	ds_read_b128 v[196:199], v154 offset:36864
	ds_read_b128 v[200:203], v154 offset:37888
	ds_read_b128 v[208:211], v154 offset:38912
	ds_read_b128 v[212:215], v154 offset:39936
	s_waitcnt vmcnt(8)
	s_waitcnt lgkmcnt(0)
	s_barrier
	s_setprio 1
	s_waitcnt lgkmcnt(0)
	v_mfma_f32_16x16x32_bf16 v[128:131], v[140:143], v[180:183], v[128:131]
	v_mfma_f32_16x16x32_bf16 v[128:131], v[144:147], v[184:187], v[128:131]
	v_mfma_f32_16x16x32_bf16 v[112:115], v[140:143], v[188:191], v[112:115]
	v_mfma_f32_16x16x32_bf16 v[112:115], v[144:147], v[192:195], v[112:115]
	v_mfma_f32_16x16x32_bf16 v[96:99], v[140:143], v[196:199], v[96:99]
	v_mfma_f32_16x16x32_bf16 v[96:99], v[144:147], v[200:203], v[96:99]
	v_mfma_f32_16x16x32_bf16 v[80:83], v[140:143], v[208:211], v[80:83]
	v_mfma_f32_16x16x32_bf16 v[80:83], v[144:147], v[212:215], v[80:83]
	v_mfma_f32_16x16x32_bf16 v[120:123], v[164:167], v[180:183], v[120:123]
	v_mfma_f32_16x16x32_bf16 v[120:123], v[168:171], v[184:187], v[120:123]
	v_mfma_f32_16x16x32_bf16 v[104:107], v[164:167], v[188:191], v[104:107]
	v_mfma_f32_16x16x32_bf16 v[104:107], v[168:171], v[192:195], v[104:107]
	v_mfma_f32_16x16x32_bf16 v[88:91], v[164:167], v[196:199], v[88:91]
	v_mfma_f32_16x16x32_bf16 v[88:91], v[168:171], v[200:203], v[88:91]
	v_mfma_f32_16x16x32_bf16 v[72:75], v[164:167], v[208:211], v[72:75]
	v_mfma_f32_16x16x32_bf16 v[72:75], v[168:171], v[212:215], v[72:75]
	v_mfma_f32_16x16x32_bf16 v[124:127], v[156:159], v[180:183], v[124:127]
	v_mfma_f32_16x16x32_bf16 v[124:127], v[160:163], v[184:187], v[124:127]
	v_mfma_f32_16x16x32_bf16 v[108:111], v[156:159], v[188:191], v[108:111]
	v_mfma_f32_16x16x32_bf16 v[108:111], v[160:163], v[192:195], v[108:111]
	v_mfma_f32_16x16x32_bf16 v[92:95], v[156:159], v[196:199], v[92:95]
	v_mfma_f32_16x16x32_bf16 v[92:95], v[160:163], v[200:203], v[92:95]
	v_mfma_f32_16x16x32_bf16 v[76:79], v[156:159], v[208:211], v[76:79]
	v_mfma_f32_16x16x32_bf16 v[76:79], v[160:163], v[212:215], v[76:79]
	v_mfma_f32_16x16x32_bf16 v[116:119], v[172:175], v[180:183], v[116:119]
	v_mfma_f32_16x16x32_bf16 v[116:119], v[176:179], v[184:187], v[116:119]
	v_mfma_f32_16x16x32_bf16 v[100:103], v[172:175], v[188:191], v[100:103]
	v_mfma_f32_16x16x32_bf16 v[100:103], v[176:179], v[192:195], v[100:103]
	v_mfma_f32_16x16x32_bf16 v[84:87], v[172:175], v[196:199], v[84:87]
	v_mfma_f32_16x16x32_bf16 v[84:87], v[176:179], v[200:203], v[84:87]
	v_mfma_f32_16x16x32_bf16 v[68:71], v[172:175], v[208:211], v[68:71]
	v_mfma_f32_16x16x32_bf16 v[68:71], v[176:179], v[212:215], v[68:71]
	s_setprio 0
	s_barrier
	s_sleep 2
	s_add_i32 s62, s58, s41
	s_add_u32 s30, s30, 0x80
	s_addc_u32 s31, s31, 0
	s_mov_b32 m0, s62
	ds_read_b128 v[180:183], v154 offset:49152
	ds_read_b128 v[184:187], v154 offset:50176
	ds_read_b128 v[188:191], v154 offset:51200
	ds_read_b128 v[192:195], v154 offset:52224
	ds_read_b128 v[196:199], v154 offset:53248
	ds_read_b128 v[200:203], v154 offset:54272
	ds_read_b128 v[208:211], v154 offset:55296
	ds_read_b128 v[212:215], v154 offset:56320
	global_load_lds_dwordx4 v2, s[30:31]
	s_add_i32 m0, s62, 0x2000
	s_nop 0
	s_add_i32 s62, s60, s41
	global_load_lds_dwordx4 v0, s[30:31]
	s_add_u32 s30, s30, 0x80000
	s_addc_u32 s31, s31, 0
	s_mov_b32 m0, s62
	s_nop 0
	global_load_lds_dwordx4 v2, s[30:31]
	s_add_i32 m0, s62, 0x2000
	s_nop 0
	global_load_lds_dwordx4 v0, s[30:31]
	s_sub_u32 s38, s38, 0x7ff80
	s_subb_u32 s39, s39, 0
	s_mov_b32 m0, s48
	s_nop 0
	global_load_lds_dwordx4 v134, s[38:39]
	s_mov_b32 m0, s49
	s_nop 0
	global_load_lds_dwordx4 v132, s[38:39]
	s_waitcnt vmcnt(8)
	s_waitcnt lgkmcnt(0)
	s_barrier
	s_setprio 1
	s_waitcnt lgkmcnt(0)
	v_mfma_f32_16x16x32_bf16 v[64:67], v[140:143], v[180:183], v[64:67]
	v_mfma_f32_16x16x32_bf16 v[64:67], v[144:147], v[184:187], v[64:67]
	v_mfma_f32_16x16x32_bf16 v[48:51], v[140:143], v[188:191], v[48:51]
	v_mfma_f32_16x16x32_bf16 v[48:51], v[144:147], v[192:195], v[48:51]
	v_mfma_f32_16x16x32_bf16 v[32:35], v[140:143], v[196:199], v[32:35]
	v_mfma_f32_16x16x32_bf16 v[32:35], v[144:147], v[200:203], v[32:35]
	v_mfma_f32_16x16x32_bf16 v[16:19], v[140:143], v[208:211], v[16:19]
	v_mfma_f32_16x16x32_bf16 v[16:19], v[144:147], v[212:215], v[16:19]
	v_mfma_f32_16x16x32_bf16 v[56:59], v[164:167], v[180:183], v[56:59]
	v_mfma_f32_16x16x32_bf16 v[56:59], v[168:171], v[184:187], v[56:59]
	v_mfma_f32_16x16x32_bf16 v[40:43], v[164:167], v[188:191], v[40:43]
	v_mfma_f32_16x16x32_bf16 v[40:43], v[168:171], v[192:195], v[40:43]
	v_mfma_f32_16x16x32_bf16 v[24:27], v[164:167], v[196:199], v[24:27]
	v_mfma_f32_16x16x32_bf16 v[24:27], v[168:171], v[200:203], v[24:27]
	v_mfma_f32_16x16x32_bf16 v[8:11], v[164:167], v[208:211], v[8:11]
	v_mfma_f32_16x16x32_bf16 v[8:11], v[168:171], v[212:215], v[8:11]
	v_mfma_f32_16x16x32_bf16 v[60:63], v[156:159], v[180:183], v[60:63]
	v_mfma_f32_16x16x32_bf16 v[60:63], v[160:163], v[184:187], v[60:63]
	v_mfma_f32_16x16x32_bf16 v[44:47], v[156:159], v[188:191], v[44:47]
	v_mfma_f32_16x16x32_bf16 v[44:47], v[160:163], v[192:195], v[44:47]
	v_mfma_f32_16x16x32_bf16 v[28:31], v[156:159], v[196:199], v[28:31]
	v_mfma_f32_16x16x32_bf16 v[28:31], v[160:163], v[200:203], v[28:31]
	v_mfma_f32_16x16x32_bf16 v[12:15], v[156:159], v[208:211], v[12:15]
	v_mfma_f32_16x16x32_bf16 v[12:15], v[160:163], v[212:215], v[12:15]
	v_mfma_f32_16x16x32_bf16 v[52:55], v[172:175], v[180:183], v[52:55]
	v_mfma_f32_16x16x32_bf16 v[52:55], v[176:179], v[184:187], v[52:55]
	v_mfma_f32_16x16x32_bf16 v[36:39], v[172:175], v[188:191], v[36:39]
	v_mfma_f32_16x16x32_bf16 v[36:39], v[176:179], v[192:195], v[36:39]
	v_mfma_f32_16x16x32_bf16 v[20:23], v[172:175], v[196:199], v[20:23]
	v_mfma_f32_16x16x32_bf16 v[20:23], v[176:179], v[200:203], v[20:23]
	v_mfma_f32_16x16x32_bf16 v[4:7], v[172:175], v[208:211], v[4:7]
	v_mfma_f32_16x16x32_bf16 v[4:7], v[176:179], v[212:215], v[4:7]
	s_setprio 0
	s_barrier
	s_add_i32 s57, s57, 2
	s_add_u32 s28, s28, 0x100
	s_addc_u32 s29, s29, 0
	s_add_u32 s55, s55, 0x100
	s_addc_u32 s56, s56, 0
	s_cmp_gt_u32 s57, 29
	s_cbranch_scc0 .LBB0_211
	s_and_b64 vcc, exec, s[16:17]
	s_cbranch_vccz .LBB0_214
	s_barrier

.LBB0_300:
	s_add_u32 s40, s18, 0x100
	s_addc_u32 s41, s19, 0
	s_mov_b32 s48, -2
	s_sleep 1
	s_add_u32 s18, s16, 0x100
	s_addc_u32 s19, s17, 0
	s_add_i32 s49, 0, 0x10000
	s_cmpk_eq_i32 s48, 0x54
	s_cselect_b32 s23, s13, s19
	s_cselect_b32 s22, s12, s18
	s_cselect_b32 s21, s15, s41
	s_cselect_b32 s20, s14, s40
	s_add_i32 s50, 0, 0x14000
	v_lshl_add_u64 v[204:205], s[16:17], 0, v[192:193]
	s_add_i32 m0, s28, 0xc000
	s_nop 0
	global_load_lds_dwordx4 v[204:205], off
	v_lshl_add_u64 v[204:205], s[16:17], 0, v[194:195]
	s_add_i32 m0, s28, 0xe000
	s_nop 0
	global_load_lds_dwordx4 v[204:205], off
	v_add_u32_e32 v144, s49, v219
	v_add_u32_e32 v160, s50, v219
	ds_read_b128 v[124:127], v144
	ds_read_b128 v[128:131], v144 offset:1024
	ds_read_b128 v[140:143], v144 offset:2048
	ds_read_b128 v[144:147], v144 offset:3072
	ds_read_b128 v[148:151], v160
	ds_read_b128 v[152:155], v160 offset:1024
	ds_read_b128 v[156:159], v160 offset:2048
	ds_read_b128 v[160:163], v160 offset:3072
	ds_read_b128 v[164:167], v221
	ds_read_b128 v[168:171], v221 offset:1024
	ds_read_b128 v[172:175], v221 offset:2048
	ds_read_b128 v[176:179], v221 offset:3072
	ds_read_b128 v[180:183], v221 offset:4096
	ds_read_b128 v[184:187], v221 offset:5120
	ds_read_b128 v[196:199], v221 offset:6144
	ds_read_b128 v[200:203], v221 offset:7168
	s_waitcnt vmcnt(8)
	s_waitcnt lgkmcnt(0)
	s_barrier
	s_setprio 1
	s_waitcnt lgkmcnt(0)
	v_mfma_f32_16x16x32_bf16 v[136:139], v[124:127], v[164:167], 0
	v_mfma_f32_16x16x32_bf16 v[136:139], v[128:131], v[168:171], v[136:139]
	v_mfma_f32_16x16x32_bf16 v[112:115], v[124:127], v[172:175], 0
	v_mfma_f32_16x16x32_bf16 v[112:115], v[128:131], v[176:179], v[112:115]
	v_mfma_f32_16x16x32_bf16 v[96:99], v[124:127], v[180:183], 0
	v_mfma_f32_16x16x32_bf16 v[96:99], v[128:131], v[184:187], v[96:99]
	v_mfma_f32_16x16x32_bf16 v[80:83], v[124:127], v[196:199], 0
	v_mfma_f32_16x16x32_bf16 v[80:83], v[128:131], v[200:203], v[80:83]
	v_mfma_f32_16x16x32_bf16 v[120:123], v[148:151], v[164:167], 0
	v_mfma_f32_16x16x32_bf16 v[120:123], v[152:155], v[168:171], v[120:123]
	v_mfma_f32_16x16x32_bf16 v[104:107], v[148:151], v[172:175], 0
	v_mfma_f32_16x16x32_bf16 v[104:107], v[152:155], v[176:179], v[104:107]
	v_mfma_f32_16x16x32_bf16 v[88:91], v[148:151], v[180:183], 0
	v_mfma_f32_16x16x32_bf16 v[88:91], v[152:155], v[184:187], v[88:91]
	v_mfma_f32_16x16x32_bf16 v[72:75], v[148:151], v[196:199], 0
	v_mfma_f32_16x16x32_bf16 v[72:75], v[152:155], v[200:203], v[72:75]
	v_mfma_f32_16x16x32_bf16 v[132:135], v[140:143], v[164:167], 0
	v_mfma_f32_16x16x32_bf16 v[132:135], v[144:147], v[168:171], v[132:135]
	v_mfma_f32_16x16x32_bf16 v[108:111], v[140:143], v[172:175], 0
	v_mfma_f32_16x16x32_bf16 v[108:111], v[144:147], v[176:179], v[108:111]
	v_mfma_f32_16x16x32_bf16 v[92:95], v[140:143], v[180:183], 0
	v_mfma_f32_16x16x32_bf16 v[92:95], v[144:147], v[184:187], v[92:95]
	v_mfma_f32_16x16x32_bf16 v[76:79], v[140:143], v[196:199], 0
	v_mfma_f32_16x16x32_bf16 v[76:79], v[144:147], v[200:203], v[76:79]
	v_mfma_f32_16x16x32_bf16 v[116:119], v[156:159], v[164:167], 0
	v_mfma_f32_16x16x32_bf16 v[116:119], v[160:163], v[168:171], v[116:119]
	v_mfma_f32_16x16x32_bf16 v[100:103], v[156:159], v[172:175], 0
	v_mfma_f32_16x16x32_bf16 v[100:103], v[160:163], v[176:179], v[100:103]
	v_mfma_f32_16x16x32_bf16 v[84:87], v[156:159], v[180:183], 0
	v_mfma_f32_16x16x32_bf16 v[84:87], v[160:163], v[184:187], v[84:87]
	v_mfma_f32_16x16x32_bf16 v[68:71], v[156:159], v[196:199], 0
	v_mfma_f32_16x16x32_bf16 v[68:71], v[160:163], v[200:203], v[68:71]
	s_setprio 0
	s_barrier
	s_sleep 2
	s_add_i32 s16, s49, s2
	v_lshl_add_u64 v[204:205], s[20:21], 0, v[2:3]
	s_mov_b32 m0, s16
	ds_read_b128 v[164:167], v221 offset:16384
	ds_read_b128 v[168:171], v221 offset:17408
	ds_read_b128 v[172:175], v221 offset:18432
	ds_read_b128 v[176:179], v221 offset:19456
	ds_read_b128 v[180:183], v221 offset:20480
	ds_read_b128 v[184:187], v221 offset:21504
	ds_read_b128 v[196:199], v221 offset:22528
	ds_read_b128 v[200:203], v221 offset:23552
	global_load_lds_dwordx4 v[204:205], off
	s_add_i32 m0, s16, 0x2000
	s_add_u32 s16, s20, 0x160000
	v_lshl_add_u64 v[206:207], s[20:21], 0, v[190:191]
	s_addc_u32 s17, s21, 0
	s_add_i32 s49, s50, s2
	global_load_lds_dwordx4 v[206:207], off
	v_lshl_add_u64 v[208:209], s[16:17], 0, v[2:3]
	s_mov_b32 m0, s49
	v_lshl_add_u64 v[210:211], s[22:23], 0, v[188:189]
	global_load_lds_dwordx4 v[208:209], off
	v_lshl_add_u64 v[208:209], s[16:17], 0, v[190:191]
	s_add_i32 m0, s49, 0x2000
	s_nop 0
	global_load_lds_dwordx4 v[208:209], off
	v_lshl_add_u64 v[208:209], s[22:23], 0, v[0:1]
	s_mov_b32 m0, s28
	s_nop 0
	global_load_lds_dwordx4 v[208:209], off
	s_mov_b32 m0, s29
	s_nop 0
	global_load_lds_dwordx4 v[210:211], off
	s_waitcnt vmcnt(8)
	s_waitcnt lgkmcnt(0)
	s_barrier
	s_setprio 1
	s_waitcnt lgkmcnt(0)
	v_mfma_f32_16x16x32_bf16 v[64:67], v[124:127], v[164:167], 0
	v_mfma_f32_16x16x32_bf16 v[64:67], v[128:131], v[168:171], v[64:67]
	v_mfma_f32_16x16x32_bf16 v[48:51], v[124:127], v[172:175], 0
	v_mfma_f32_16x16x32_bf16 v[48:51], v[128:131], v[176:179], v[48:51]
	v_mfma_f32_16x16x32_bf16 v[32:35], v[124:127], v[180:183], 0
	v_mfma_f32_16x16x32_bf16 v[32:35], v[128:131], v[184:187], v[32:35]
	v_mfma_f32_16x16x32_bf16 v[16:19], v[124:127], v[196:199], 0
	v_mfma_f32_16x16x32_bf16 v[16:19], v[128:131], v[200:203], v[16:19]
	v_mfma_f32_16x16x32_bf16 v[56:59], v[148:151], v[164:167], 0
	v_mfma_f32_16x16x32_bf16 v[56:59], v[152:155], v[168:171], v[56:59]
	v_mfma_f32_16x16x32_bf16 v[40:43], v[148:151], v[172:175], 0
	v_mfma_f32_16x16x32_bf16 v[40:43], v[152:155], v[176:179], v[40:43]
	v_mfma_f32_16x16x32_bf16 v[24:27], v[148:151], v[180:183], 0
	v_mfma_f32_16x16x32_bf16 v[24:27], v[152:155], v[184:187], v[24:27]
	v_mfma_f32_16x16x32_bf16 v[8:11], v[148:151], v[196:199], 0
	v_mfma_f32_16x16x32_bf16 v[8:11], v[152:155], v[200:203], v[8:11]
	v_mfma_f32_16x16x32_bf16 v[60:63], v[140:143], v[164:167], 0
	v_mfma_f32_16x16x32_bf16 v[60:63], v[144:147], v[168:171], v[60:63]
	v_mfma_f32_16x16x32_bf16 v[44:47], v[140:143], v[172:175], 0
	v_mfma_f32_16x16x32_bf16 v[44:47], v[144:147], v[176:179], v[44:47]
	v_mfma_f32_16x16x32_bf16 v[28:31], v[140:143], v[180:183], 0
	v_mfma_f32_16x16x32_bf16 v[28:31], v[144:147], v[184:187], v[28:31]
	v_mfma_f32_16x16x32_bf16 v[12:15], v[140:143], v[196:199], 0
	v_mfma_f32_16x16x32_bf16 v[12:15], v[144:147], v[200:203], v[12:15]
	v_mfma_f32_16x16x32_bf16 v[52:55], v[156:159], v[164:167], 0
	v_mfma_f32_16x16x32_bf16 v[52:55], v[160:163], v[168:171], v[52:55]
	v_mfma_f32_16x16x32_bf16 v[36:39], v[156:159], v[172:175], 0
	v_mfma_f32_16x16x32_bf16 v[36:39], v[160:163], v[176:179], v[36:39]
	v_mfma_f32_16x16x32_bf16 v[20:23], v[156:159], v[180:183], 0
	v_mfma_f32_16x16x32_bf16 v[20:23], v[160:163], v[184:187], v[20:23]
	v_mfma_f32_16x16x32_bf16 v[4:7], v[156:159], v[196:199], 0
	v_mfma_f32_16x16x32_bf16 v[4:7], v[160:163], v[200:203], v[4:7]
	s_setprio 0
	s_barrier
	s_sleep 1
	s_add_i32 s49, 0, 0x18000
	s_add_i32 s50, 0, 0x1c000
	s_add_u32 s16, s22, 0x160000
	s_addc_u32 s17, s23, 0
	s_mov_b32 m0, s30
	v_lshl_add_u64 v[212:213], s[16:17], 0, v[0:1]
	global_load_lds_dwordx4 v[212:213], off
	v_lshl_add_u64 v[212:213], s[16:17], 0, v[188:189]
	s_mov_b32 m0, s31
	s_nop 0
	global_load_lds_dwordx4 v[212:213], off
	v_add_u32_e32 v144, s49, v219
	v_add_u32_e32 v160, s50, v219
	ds_read_b128 v[124:127], v144
	ds_read_b128 v[128:131], v144 offset:1024
	ds_read_b128 v[140:143], v144 offset:2048
	ds_read_b128 v[144:147], v144 offset:3072
	ds_read_b128 v[148:151], v160
	ds_read_b128 v[152:155], v160 offset:1024
	ds_read_b128 v[156:159], v160 offset:2048
	ds_read_b128 v[160:163], v160 offset:3072
	ds_read_b128 v[164:167], v221 offset:32768
	ds_read_b128 v[168:171], v221 offset:33792
	ds_read_b128 v[172:175], v221 offset:34816
	ds_read_b128 v[176:179], v221 offset:35840
	ds_read_b128 v[180:183], v221 offset:36864
	ds_read_b128 v[184:187], v221 offset:37888
	ds_read_b128 v[196:199], v221 offset:38912
	ds_read_b128 v[200:203], v221 offset:39936
	s_waitcnt vmcnt(8)
	s_waitcnt lgkmcnt(0)
	s_barrier
	s_setprio 1
	s_waitcnt lgkmcnt(0)
	v_mfma_f32_16x16x32_bf16 v[136:139], v[124:127], v[164:167], v[136:139]
	v_mfma_f32_16x16x32_bf16 v[136:139], v[128:131], v[168:171], v[136:139]
	v_mfma_f32_16x16x32_bf16 v[112:115], v[124:127], v[172:175], v[112:115]
	v_mfma_f32_16x16x32_bf16 v[112:115], v[128:131], v[176:179], v[112:115]
	v_mfma_f32_16x16x32_bf16 v[96:99], v[124:127], v[180:183], v[96:99]
	v_mfma_f32_16x16x32_bf16 v[96:99], v[128:131], v[184:187], v[96:99]
	v_mfma_f32_16x16x32_bf16 v[80:83], v[124:127], v[196:199], v[80:83]
	v_mfma_f32_16x16x32_bf16 v[80:83], v[128:131], v[200:203], v[80:83]
	v_mfma_f32_16x16x32_bf16 v[120:123], v[148:151], v[164:167], v[120:123]
	v_mfma_f32_16x16x32_bf16 v[120:123], v[152:155], v[168:171], v[120:123]
	v_mfma_f32_16x16x32_bf16 v[104:107], v[148:151], v[172:175], v[104:107]
	v_mfma_f32_16x16x32_bf16 v[104:107], v[152:155], v[176:179], v[104:107]
	v_mfma_f32_16x16x32_bf16 v[88:91], v[148:151], v[180:183], v[88:91]
	v_mfma_f32_16x16x32_bf16 v[88:91], v[152:155], v[184:187], v[88:91]
	v_mfma_f32_16x16x32_bf16 v[72:75], v[148:151], v[196:199], v[72:75]
	v_mfma_f32_16x16x32_bf16 v[72:75], v[152:155], v[200:203], v[72:75]
	v_mfma_f32_16x16x32_bf16 v[132:135], v[140:143], v[164:167], v[132:135]
	v_mfma_f32_16x16x32_bf16 v[132:135], v[144:147], v[168:171], v[132:135]
	v_mfma_f32_16x16x32_bf16 v[108:111], v[140:143], v[172:175], v[108:111]
	v_mfma_f32_16x16x32_bf16 v[108:111], v[144:147], v[176:179], v[108:111]
	v_mfma_f32_16x16x32_bf16 v[92:95], v[140:143], v[180:183], v[92:95]
	v_mfma_f32_16x16x32_bf16 v[92:95], v[144:147], v[184:187], v[92:95]
	v_mfma_f32_16x16x32_bf16 v[76:79], v[140:143], v[196:199], v[76:79]
	v_mfma_f32_16x16x32_bf16 v[76:79], v[144:147], v[200:203], v[76:79]
	v_mfma_f32_16x16x32_bf16 v[116:119], v[156:159], v[164:167], v[116:119]
	v_mfma_f32_16x16x32_bf16 v[116:119], v[160:163], v[168:171], v[116:119]
	v_mfma_f32_16x16x32_bf16 v[100:103], v[156:159], v[172:175], v[100:103]
	v_mfma_f32_16x16x32_bf16 v[100:103], v[160:163], v[176:179], v[100:103]
	v_mfma_f32_16x16x32_bf16 v[84:87], v[156:159], v[180:183], v[84:87]
	v_mfma_f32_16x16x32_bf16 v[84:87], v[160:163], v[184:187], v[84:87]
	v_mfma_f32_16x16x32_bf16 v[68:71], v[156:159], v[196:199], v[68:71]
	v_mfma_f32_16x16x32_bf16 v[68:71], v[160:163], v[200:203], v[68:71]
	s_setprio 0
	s_barrier
	s_sleep 2
	s_add_i32 s16, s49, s2
	v_lshl_add_u64 v[204:205], v[204:205], 0, s[66:67]
	s_mov_b32 m0, s16
	ds_read_b128 v[164:167], v221 offset:49152
	ds_read_b128 v[168:171], v221 offset:50176
	ds_read_b128 v[172:175], v221 offset:51200
	ds_read_b128 v[176:179], v221 offset:52224
	ds_read_b128 v[180:183], v221 offset:53248
	ds_read_b128 v[184:187], v221 offset:54272
	ds_read_b128 v[196:199], v221 offset:55296
	ds_read_b128 v[200:203], v221 offset:56320
	global_load_lds_dwordx4 v[204:205], off
	s_add_i32 m0, s16, 0x2000
	s_add_u32 s16, s20, 0x160080
	v_lshl_add_u64 v[204:205], v[206:207], 0, s[66:67]
	s_addc_u32 s17, s21, 0
	s_add_i32 s20, s50, s2
	global_load_lds_dwordx4 v[204:205], off
	v_lshl_add_u64 v[204:205], s[16:17], 0, v[2:3]
	s_mov_b32 m0, s20
	s_nop 0
	global_load_lds_dwordx4 v[204:205], off
	v_lshl_add_u64 v[204:205], s[16:17], 0, v[190:191]
	s_add_i32 m0, s20, 0x2000
	s_nop 0
	global_load_lds_dwordx4 v[204:205], off
	v_lshl_add_u64 v[204:205], v[208:209], 0, s[66:67]
	s_mov_b32 m0, s34
	s_nop 0
	global_load_lds_dwordx4 v[204:205], off
	v_lshl_add_u64 v[204:205], v[210:211], 0, s[66:67]
	s_mov_b32 m0, s35
	s_nop 0
	global_load_lds_dwordx4 v[204:205], off
	s_waitcnt vmcnt(8)
	s_waitcnt lgkmcnt(0)
	s_barrier
	s_setprio 1
	s_waitcnt lgkmcnt(0)
	v_mfma_f32_16x16x32_bf16 v[64:67], v[124:127], v[164:167], v[64:67]
	v_mfma_f32_16x16x32_bf16 v[64:67], v[128:131], v[168:171], v[64:67]
	v_mfma_f32_16x16x32_bf16 v[48:51], v[124:127], v[172:175], v[48:51]
	v_mfma_f32_16x16x32_bf16 v[48:51], v[128:131], v[176:179], v[48:51]
	v_mfma_f32_16x16x32_bf16 v[32:35], v[124:127], v[180:183], v[32:35]
	v_mfma_f32_16x16x32_bf16 v[32:35], v[128:131], v[184:187], v[32:35]
	v_mfma_f32_16x16x32_bf16 v[16:19], v[124:127], v[196:199], v[16:19]
	v_mfma_f32_16x16x32_bf16 v[16:19], v[128:131], v[200:203], v[16:19]
	v_mfma_f32_16x16x32_bf16 v[56:59], v[148:151], v[164:167], v[56:59]
	v_mfma_f32_16x16x32_bf16 v[56:59], v[152:155], v[168:171], v[56:59]
	v_mfma_f32_16x16x32_bf16 v[40:43], v[148:151], v[172:175], v[40:43]
	v_mfma_f32_16x16x32_bf16 v[40:43], v[152:155], v[176:179], v[40:43]
	v_mfma_f32_16x16x32_bf16 v[24:27], v[148:151], v[180:183], v[24:27]
	v_mfma_f32_16x16x32_bf16 v[24:27], v[152:155], v[184:187], v[24:27]
	v_mfma_f32_16x16x32_bf16 v[8:11], v[148:151], v[196:199], v[8:11]
	v_mfma_f32_16x16x32_bf16 v[8:11], v[152:155], v[200:203], v[8:11]
	v_mfma_f32_16x16x32_bf16 v[60:63], v[140:143], v[164:167], v[60:63]
	v_mfma_f32_16x16x32_bf16 v[60:63], v[144:147], v[168:171], v[60:63]
	v_mfma_f32_16x16x32_bf16 v[44:47], v[140:143], v[172:175], v[44:47]
	v_mfma_f32_16x16x32_bf16 v[44:47], v[144:147], v[176:179], v[44:47]
	v_mfma_f32_16x16x32_bf16 v[28:31], v[140:143], v[180:183], v[28:31]
	v_mfma_f32_16x16x32_bf16 v[28:31], v[144:147], v[184:187], v[28:31]
	v_mfma_f32_16x16x32_bf16 v[12:15], v[140:143], v[196:199], v[12:15]
	v_mfma_f32_16x16x32_bf16 v[12:15], v[144:147], v[200:203], v[12:15]
	v_mfma_f32_16x16x32_bf16 v[52:55], v[156:159], v[164:167], v[52:55]
	v_mfma_f32_16x16x32_bf16 v[52:55], v[160:163], v[168:171], v[52:55]
	v_mfma_f32_16x16x32_bf16 v[36:39], v[156:159], v[172:175], v[36:39]
	v_mfma_f32_16x16x32_bf16 v[36:39], v[160:163], v[176:179], v[36:39]
	v_mfma_f32_16x16x32_bf16 v[20:23], v[156:159], v[180:183], v[20:23]
	v_mfma_f32_16x16x32_bf16 v[20:23], v[160:163], v[184:187], v[20:23]
	v_mfma_f32_16x16x32_bf16 v[4:7], v[156:159], v[196:199], v[4:7]
	v_mfma_f32_16x16x32_bf16 v[4:7], v[160:163], v[200:203], v[4:7]
	s_setprio 0
	s_barrier
	s_add_i32 s48, s48, 2
	s_add_u32 s40, s40, 0x100
	s_addc_u32 s41, s41, 0
	s_cmpk_gt_u32 s48, 0x55
	s_mov_b64 s[16:17], s[18:19]
.LBB0_301:
	s_sleep 1
	s_add_u32 s18, s16, 0x100
	s_addc_u32 s19, s17, 0
	s_add_i32 s49, 0, 0x10000
	s_cmpk_eq_i32 s48, 0x54
	s_cselect_b32 s23, s13, s19
	s_cselect_b32 s22, s12, s18
	s_cselect_b32 s21, s15, s41
	s_cselect_b32 s20, s14, s40
	s_add_i32 s50, 0, 0x14000
	v_lshl_add_u64 v[204:205], s[16:17], 0, v[192:193]
	s_add_i32 m0, s28, 0xc000
	s_nop 0
	global_load_lds_dwordx4 v[204:205], off
	v_lshl_add_u64 v[204:205], s[16:17], 0, v[194:195]
	s_add_i32 m0, s28, 0xe000
	s_nop 0
	global_load_lds_dwordx4 v[204:205], off
	v_add_u32_e32 v144, s49, v219
	v_add_u32_e32 v160, s50, v219
	ds_read_b128 v[124:127], v144
	ds_read_b128 v[128:131], v144 offset:1024
	ds_read_b128 v[140:143], v144 offset:2048
	ds_read_b128 v[144:147], v144 offset:3072
	ds_read_b128 v[148:151], v160
	ds_read_b128 v[152:155], v160 offset:1024
	ds_read_b128 v[156:159], v160 offset:2048
	ds_read_b128 v[160:163], v160 offset:3072
	ds_read_b128 v[164:167], v221
	ds_read_b128 v[168:171], v221 offset:1024
	ds_read_b128 v[172:175], v221 offset:2048
	ds_read_b128 v[176:179], v221 offset:3072
	ds_read_b128 v[180:183], v221 offset:4096
	ds_read_b128 v[184:187], v221 offset:5120
	ds_read_b128 v[196:199], v221 offset:6144
	ds_read_b128 v[200:203], v221 offset:7168
	s_waitcnt vmcnt(8)
	s_waitcnt lgkmcnt(0)
	s_barrier
	s_setprio 1
	s_waitcnt lgkmcnt(0)
	v_mfma_f32_16x16x32_bf16 v[136:139], v[124:127], v[164:167], v[136:139]
	v_mfma_f32_16x16x32_bf16 v[136:139], v[128:131], v[168:171], v[136:139]
	v_mfma_f32_16x16x32_bf16 v[112:115], v[124:127], v[172:175], v[112:115]
	v_mfma_f32_16x16x32_bf16 v[112:115], v[128:131], v[176:179], v[112:115]
	v_mfma_f32_16x16x32_bf16 v[96:99], v[124:127], v[180:183], v[96:99]
	v_mfma_f32_16x16x32_bf16 v[96:99], v[128:131], v[184:187], v[96:99]
	v_mfma_f32_16x16x32_bf16 v[80:83], v[124:127], v[196:199], v[80:83]
	v_mfma_f32_16x16x32_bf16 v[80:83], v[128:131], v[200:203], v[80:83]
	v_mfma_f32_16x16x32_bf16 v[120:123], v[148:151], v[164:167], v[120:123]
	v_mfma_f32_16x16x32_bf16 v[120:123], v[152:155], v[168:171], v[120:123]
	v_mfma_f32_16x16x32_bf16 v[104:107], v[148:151], v[172:175], v[104:107]
	v_mfma_f32_16x16x32_bf16 v[104:107], v[152:155], v[176:179], v[104:107]
	v_mfma_f32_16x16x32_bf16 v[88:91], v[148:151], v[180:183], v[88:91]
	v_mfma_f32_16x16x32_bf16 v[88:91], v[152:155], v[184:187], v[88:91]
	v_mfma_f32_16x16x32_bf16 v[72:75], v[148:151], v[196:199], v[72:75]
	v_mfma_f32_16x16x32_bf16 v[72:75], v[152:155], v[200:203], v[72:75]
	v_mfma_f32_16x16x32_bf16 v[132:135], v[140:143], v[164:167], v[132:135]
	v_mfma_f32_16x16x32_bf16 v[132:135], v[144:147], v[168:171], v[132:135]
	v_mfma_f32_16x16x32_bf16 v[108:111], v[140:143], v[172:175], v[108:111]
	v_mfma_f32_16x16x32_bf16 v[108:111], v[144:147], v[176:179], v[108:111]
	v_mfma_f32_16x16x32_bf16 v[92:95], v[140:143], v[180:183], v[92:95]
	v_mfma_f32_16x16x32_bf16 v[92:95], v[144:147], v[184:187], v[92:95]
	v_mfma_f32_16x16x32_bf16 v[76:79], v[140:143], v[196:199], v[76:79]
	v_mfma_f32_16x16x32_bf16 v[76:79], v[144:147], v[200:203], v[76:79]
	v_mfma_f32_16x16x32_bf16 v[116:119], v[156:159], v[164:167], v[116:119]
	v_mfma_f32_16x16x32_bf16 v[116:119], v[160:163], v[168:171], v[116:119]
	v_mfma_f32_16x16x32_bf16 v[100:103], v[156:159], v[172:175], v[100:103]
	v_mfma_f32_16x16x32_bf16 v[100:103], v[160:163], v[176:179], v[100:103]
	v_mfma_f32_16x16x32_bf16 v[84:87], v[156:159], v[180:183], v[84:87]
	v_mfma_f32_16x16x32_bf16 v[84:87], v[160:163], v[184:187], v[84:87]
	v_mfma_f32_16x16x32_bf16 v[68:71], v[156:159], v[196:199], v[68:71]
	v_mfma_f32_16x16x32_bf16 v[68:71], v[160:163], v[200:203], v[68:71]
	s_setprio 0
	s_barrier
	s_sleep 2
	s_add_i32 s16, s49, s2
	v_lshl_add_u64 v[204:205], s[20:21], 0, v[2:3]
	s_mov_b32 m0, s16
	ds_read_b128 v[164:167], v221 offset:16384
	ds_read_b128 v[168:171], v221 offset:17408
	ds_read_b128 v[172:175], v221 offset:18432
	ds_read_b128 v[176:179], v221 offset:19456
	ds_read_b128 v[180:183], v221 offset:20480
	ds_read_b128 v[184:187], v221 offset:21504
	ds_read_b128 v[196:199], v221 offset:22528
	ds_read_b128 v[200:203], v221 offset:23552
	global_load_lds_dwordx4 v[204:205], off
	s_add_i32 m0, s16, 0x2000
	s_add_u32 s16, s20, 0x160000
	v_lshl_add_u64 v[206:207], s[20:21], 0, v[190:191]
	s_addc_u32 s17, s21, 0
	s_add_i32 s49, s50, s2
	global_load_lds_dwordx4 v[206:207], off
	v_lshl_add_u64 v[208:209], s[16:17], 0, v[2:3]
	s_mov_b32 m0, s49
	v_lshl_add_u64 v[210:211], s[22:23], 0, v[188:189]
	global_load_lds_dwordx4 v[208:209], off
	v_lshl_add_u64 v[208:209], s[16:17], 0, v[190:191]
	s_add_i32 m0, s49, 0x2000
	s_nop 0
	global_load_lds_dwordx4 v[208:209], off
	v_lshl_add_u64 v[208:209], s[22:23], 0, v[0:1]
	s_mov_b32 m0, s28
	s_nop 0
	global_load_lds_dwordx4 v[208:209], off
	s_mov_b32 m0, s29
	s_nop 0
	global_load_lds_dwordx4 v[210:211], off
	s_waitcnt vmcnt(8)
	s_waitcnt lgkmcnt(0)
	s_barrier
	s_setprio 1
	s_waitcnt lgkmcnt(0)
	v_mfma_f32_16x16x32_bf16 v[64:67], v[124:127], v[164:167], v[64:67]
	v_mfma_f32_16x16x32_bf16 v[64:67], v[128:131], v[168:171], v[64:67]
	v_mfma_f32_16x16x32_bf16 v[48:51], v[124:127], v[172:175], v[48:51]
	v_mfma_f32_16x16x32_bf16 v[48:51], v[128:131], v[176:179], v[48:51]
	v_mfma_f32_16x16x32_bf16 v[32:35], v[124:127], v[180:183], v[32:35]
	v_mfma_f32_16x16x32_bf16 v[32:35], v[128:131], v[184:187], v[32:35]
	v_mfma_f32_16x16x32_bf16 v[16:19], v[124:127], v[196:199], v[16:19]
	v_mfma_f32_16x16x32_bf16 v[16:19], v[128:131], v[200:203], v[16:19]
	v_mfma_f32_16x16x32_bf16 v[56:59], v[148:151], v[164:167], v[56:59]
	v_mfma_f32_16x16x32_bf16 v[56:59], v[152:155], v[168:171], v[56:59]
	v_mfma_f32_16x16x32_bf16 v[40:43], v[148:151], v[172:175], v[40:43]
	v_mfma_f32_16x16x32_bf16 v[40:43], v[152:155], v[176:179], v[40:43]
	v_mfma_f32_16x16x32_bf16 v[24:27], v[148:151], v[180:183], v[24:27]
	v_mfma_f32_16x16x32_bf16 v[24:27], v[152:155], v[184:187], v[24:27]
	v_mfma_f32_16x16x32_bf16 v[8:11], v[148:151], v[196:199], v[8:11]
	v_mfma_f32_16x16x32_bf16 v[8:11], v[152:155], v[200:203], v[8:11]
	v_mfma_f32_16x16x32_bf16 v[60:63], v[140:143], v[164:167], v[60:63]
	v_mfma_f32_16x16x32_bf16 v[60:63], v[144:147], v[168:171], v[60:63]
	v_mfma_f32_16x16x32_bf16 v[44:47], v[140:143], v[172:175], v[44:47]
	v_mfma_f32_16x16x32_bf16 v[44:47], v[144:147], v[176:179], v[44:47]
	v_mfma_f32_16x16x32_bf16 v[28:31], v[140:143], v[180:183], v[28:31]
	v_mfma_f32_16x16x32_bf16 v[28:31], v[144:147], v[184:187], v[28:31]
	v_mfma_f32_16x16x32_bf16 v[12:15], v[140:143], v[196:199], v[12:15]
	v_mfma_f32_16x16x32_bf16 v[12:15], v[144:147], v[200:203], v[12:15]
	v_mfma_f32_16x16x32_bf16 v[52:55], v[156:159], v[164:167], v[52:55]
	v_mfma_f32_16x16x32_bf16 v[52:55], v[160:163], v[168:171], v[52:55]
	v_mfma_f32_16x16x32_bf16 v[36:39], v[156:159], v[172:175], v[36:39]
	v_mfma_f32_16x16x32_bf16 v[36:39], v[160:163], v[176:179], v[36:39]
	v_mfma_f32_16x16x32_bf16 v[20:23], v[156:159], v[180:183], v[20:23]
	v_mfma_f32_16x16x32_bf16 v[20:23], v[160:163], v[184:187], v[20:23]
	v_mfma_f32_16x16x32_bf16 v[4:7], v[156:159], v[196:199], v[4:7]
	v_mfma_f32_16x16x32_bf16 v[4:7], v[160:163], v[200:203], v[4:7]
	s_setprio 0
	s_barrier
	s_sleep 1
	s_add_i32 s49, 0, 0x18000
	s_add_i32 s50, 0, 0x1c000
	s_add_u32 s16, s22, 0x160000
	s_addc_u32 s17, s23, 0
	s_mov_b32 m0, s30
	v_lshl_add_u64 v[212:213], s[16:17], 0, v[0:1]
	global_load_lds_dwordx4 v[212:213], off
	v_lshl_add_u64 v[212:213], s[16:17], 0, v[188:189]
	s_mov_b32 m0, s31
	s_nop 0
	global_load_lds_dwordx4 v[212:213], off
	v_add_u32_e32 v144, s49, v219
	v_add_u32_e32 v160, s50, v219
	ds_read_b128 v[124:127], v144
	ds_read_b128 v[128:131], v144 offset:1024
	ds_read_b128 v[140:143], v144 offset:2048
	ds_read_b128 v[144:147], v144 offset:3072
	ds_read_b128 v[148:151], v160
	ds_read_b128 v[152:155], v160 offset:1024
	ds_read_b128 v[156:159], v160 offset:2048
	ds_read_b128 v[160:163], v160 offset:3072
	ds_read_b128 v[164:167], v221 offset:32768
	ds_read_b128 v[168:171], v221 offset:33792
	ds_read_b128 v[172:175], v221 offset:34816
	ds_read_b128 v[176:179], v221 offset:35840
	ds_read_b128 v[180:183], v221 offset:36864
	ds_read_b128 v[184:187], v221 offset:37888
	ds_read_b128 v[196:199], v221 offset:38912
	ds_read_b128 v[200:203], v221 offset:39936
	s_waitcnt vmcnt(8)
	s_waitcnt lgkmcnt(0)
	s_barrier
	s_setprio 1
	s_waitcnt lgkmcnt(0)
	v_mfma_f32_16x16x32_bf16 v[136:139], v[124:127], v[164:167], v[136:139]
	v_mfma_f32_16x16x32_bf16 v[136:139], v[128:131], v[168:171], v[136:139]
	v_mfma_f32_16x16x32_bf16 v[112:115], v[124:127], v[172:175], v[112:115]
	v_mfma_f32_16x16x32_bf16 v[112:115], v[128:131], v[176:179], v[112:115]
	v_mfma_f32_16x16x32_bf16 v[96:99], v[124:127], v[180:183], v[96:99]
	v_mfma_f32_16x16x32_bf16 v[96:99], v[128:131], v[184:187], v[96:99]
	v_mfma_f32_16x16x32_bf16 v[80:83], v[124:127], v[196:199], v[80:83]
	v_mfma_f32_16x16x32_bf16 v[80:83], v[128:131], v[200:203], v[80:83]
	v_mfma_f32_16x16x32_bf16 v[120:123], v[148:151], v[164:167], v[120:123]
	v_mfma_f32_16x16x32_bf16 v[120:123], v[152:155], v[168:171], v[120:123]
	v_mfma_f32_16x16x32_bf16 v[104:107], v[148:151], v[172:175], v[104:107]
	v_mfma_f32_16x16x32_bf16 v[104:107], v[152:155], v[176:179], v[104:107]
	v_mfma_f32_16x16x32_bf16 v[88:91], v[148:151], v[180:183], v[88:91]
	v_mfma_f32_16x16x32_bf16 v[88:91], v[152:155], v[184:187], v[88:91]
	v_mfma_f32_16x16x32_bf16 v[72:75], v[148:151], v[196:199], v[72:75]
	v_mfma_f32_16x16x32_bf16 v[72:75], v[152:155], v[200:203], v[72:75]
	v_mfma_f32_16x16x32_bf16 v[132:135], v[140:143], v[164:167], v[132:135]
	v_mfma_f32_16x16x32_bf16 v[132:135], v[144:147], v[168:171], v[132:135]
	v_mfma_f32_16x16x32_bf16 v[108:111], v[140:143], v[172:175], v[108:111]
	v_mfma_f32_16x16x32_bf16 v[108:111], v[144:147], v[176:179], v[108:111]
	v_mfma_f32_16x16x32_bf16 v[92:95], v[140:143], v[180:183], v[92:95]
	v_mfma_f32_16x16x32_bf16 v[92:95], v[144:147], v[184:187], v[92:95]
	v_mfma_f32_16x16x32_bf16 v[76:79], v[140:143], v[196:199], v[76:79]
	v_mfma_f32_16x16x32_bf16 v[76:79], v[144:147], v[200:203], v[76:79]
	v_mfma_f32_16x16x32_bf16 v[116:119], v[156:159], v[164:167], v[116:119]
	v_mfma_f32_16x16x32_bf16 v[116:119], v[160:163], v[168:171], v[116:119]
	v_mfma_f32_16x16x32_bf16 v[100:103], v[156:159], v[172:175], v[100:103]
	v_mfma_f32_16x16x32_bf16 v[100:103], v[160:163], v[176:179], v[100:103]
	v_mfma_f32_16x16x32_bf16 v[84:87], v[156:159], v[180:183], v[84:87]
	v_mfma_f32_16x16x32_bf16 v[84:87], v[160:163], v[184:187], v[84:87]
	v_mfma_f32_16x16x32_bf16 v[68:71], v[156:159], v[196:199], v[68:71]
	v_mfma_f32_16x16x32_bf16 v[68:71], v[160:163], v[200:203], v[68:71]
	s_setprio 0
	s_barrier
	s_sleep 2
	s_add_i32 s16, s49, s2
	v_lshl_add_u64 v[204:205], v[204:205], 0, s[66:67]
	s_mov_b32 m0, s16
	ds_read_b128 v[164:167], v221 offset:49152
	ds_read_b128 v[168:171], v221 offset:50176
	ds_read_b128 v[172:175], v221 offset:51200
	ds_read_b128 v[176:179], v221 offset:52224
	ds_read_b128 v[180:183], v221 offset:53248
	ds_read_b128 v[184:187], v221 offset:54272
	ds_read_b128 v[196:199], v221 offset:55296
	ds_read_b128 v[200:203], v221 offset:56320
	global_load_lds_dwordx4 v[204:205], off
	s_add_i32 m0, s16, 0x2000
	s_add_u32 s16, s20, 0x160080
	v_lshl_add_u64 v[204:205], v[206:207], 0, s[66:67]
	s_addc_u32 s17, s21, 0
	s_add_i32 s20, s50, s2
	global_load_lds_dwordx4 v[204:205], off
	v_lshl_add_u64 v[204:205], s[16:17], 0, v[2:3]
	s_mov_b32 m0, s20
	s_nop 0
	global_load_lds_dwordx4 v[204:205], off
	v_lshl_add_u64 v[204:205], s[16:17], 0, v[190:191]
	s_add_i32 m0, s20, 0x2000
	s_nop 0
	global_load_lds_dwordx4 v[204:205], off
	v_lshl_add_u64 v[204:205], v[208:209], 0, s[66:67]
	s_mov_b32 m0, s34
	s_nop 0
	global_load_lds_dwordx4 v[204:205], off
	v_lshl_add_u64 v[204:205], v[210:211], 0, s[66:67]
	s_mov_b32 m0, s35
	s_nop 0
	global_load_lds_dwordx4 v[204:205], off
	s_waitcnt vmcnt(8)
	s_waitcnt lgkmcnt(0)
	s_barrier
	s_setprio 1
	s_waitcnt lgkmcnt(0)
	v_mfma_f32_16x16x32_bf16 v[64:67], v[124:127], v[164:167], v[64:67]
	v_mfma_f32_16x16x32_bf16 v[64:67], v[128:131], v[168:171], v[64:67]
	v_mfma_f32_16x16x32_bf16 v[48:51], v[124:127], v[172:175], v[48:51]
	v_mfma_f32_16x16x32_bf16 v[48:51], v[128:131], v[176:179], v[48:51]
	v_mfma_f32_16x16x32_bf16 v[32:35], v[124:127], v[180:183], v[32:35]
	v_mfma_f32_16x16x32_bf16 v[32:35], v[128:131], v[184:187], v[32:35]
	v_mfma_f32_16x16x32_bf16 v[16:19], v[124:127], v[196:199], v[16:19]
	v_mfma_f32_16x16x32_bf16 v[16:19], v[128:131], v[200:203], v[16:19]
	v_mfma_f32_16x16x32_bf16 v[56:59], v[148:151], v[164:167], v[56:59]
	v_mfma_f32_16x16x32_bf16 v[56:59], v[152:155], v[168:171], v[56:59]
	v_mfma_f32_16x16x32_bf16 v[40:43], v[148:151], v[172:175], v[40:43]
	v_mfma_f32_16x16x32_bf16 v[40:43], v[152:155], v[176:179], v[40:43]
	v_mfma_f32_16x16x32_bf16 v[24:27], v[148:151], v[180:183], v[24:27]
	v_mfma_f32_16x16x32_bf16 v[24:27], v[152:155], v[184:187], v[24:27]
	v_mfma_f32_16x16x32_bf16 v[8:11], v[148:151], v[196:199], v[8:11]
	v_mfma_f32_16x16x32_bf16 v[8:11], v[152:155], v[200:203], v[8:11]
	v_mfma_f32_16x16x32_bf16 v[60:63], v[140:143], v[164:167], v[60:63]
	v_mfma_f32_16x16x32_bf16 v[60:63], v[144:147], v[168:171], v[60:63]
	v_mfma_f32_16x16x32_bf16 v[44:47], v[140:143], v[172:175], v[44:47]
	v_mfma_f32_16x16x32_bf16 v[44:47], v[144:147], v[176:179], v[44:47]
	v_mfma_f32_16x16x32_bf16 v[28:31], v[140:143], v[180:183], v[28:31]
	v_mfma_f32_16x16x32_bf16 v[28:31], v[144:147], v[184:187], v[28:31]
	v_mfma_f32_16x16x32_bf16 v[12:15], v[140:143], v[196:199], v[12:15]
	v_mfma_f32_16x16x32_bf16 v[12:15], v[144:147], v[200:203], v[12:15]
	v_mfma_f32_16x16x32_bf16 v[52:55], v[156:159], v[164:167], v[52:55]
	v_mfma_f32_16x16x32_bf16 v[52:55], v[160:163], v[168:171], v[52:55]
	v_mfma_f32_16x16x32_bf16 v[36:39], v[156:159], v[172:175], v[36:39]
	v_mfma_f32_16x16x32_bf16 v[36:39], v[160:163], v[176:179], v[36:39]
	v_mfma_f32_16x16x32_bf16 v[20:23], v[156:159], v[180:183], v[20:23]
	v_mfma_f32_16x16x32_bf16 v[20:23], v[160:163], v[184:187], v[20:23]
	v_mfma_f32_16x16x32_bf16 v[4:7], v[156:159], v[196:199], v[4:7]
	v_mfma_f32_16x16x32_bf16 v[4:7], v[160:163], v[200:203], v[4:7]
	s_setprio 0
	s_barrier
	s_add_i32 s48, s48, 2
	s_add_u32 s40, s40, 0x100
	s_addc_u32 s41, s41, 0
	s_cmpk_gt_u32 s48, 0x55
	s_mov_b64 s[16:17], s[18:19]
	s_cbranch_scc0 .LBB0_301
	s_and_b64 vcc, exec, s[10:11]
	s_cbranch_vccz .LBB0_304
	s_barrier

.LBB0_346:
	s_add_u32 s38, s16, 0x100
	s_addc_u32 s39, s17, 0
	s_mov_b32 s43, -2
	s_sleep 1
	s_add_u32 s16, s14, 0x100
	s_addc_u32 s17, s15, 0
	s_add_i32 s44, 0, 0x10000
	s_cmpk_eq_i32 s43, 0x54
	s_cselect_b32 s21, s11, s17
	s_cselect_b32 s20, s10, s16
	s_cselect_b32 s19, s13, s39
	s_cselect_b32 s18, s12, s38
	s_add_i32 s45, 0, 0x14000
	v_lshl_add_u64 v[204:205], s[14:15], 0, v[200:201]
	s_add_i32 m0, s23, 0xc000
	s_nop 0
	global_load_lds_dwordx4 v[204:205], off
	v_lshl_add_u64 v[204:205], s[14:15], 0, v[202:203]
	s_add_i32 m0, s23, 0xe000
	s_nop 0
	global_load_lds_dwordx4 v[204:205], off
	v_add_u32_e32 v144, s44, v236
	v_add_u32_e32 v160, s45, v236
	ds_read_b128 v[132:135], v144
	ds_read_b128 v[136:139], v144 offset:1024
	ds_read_b128 v[140:143], v144 offset:2048
	ds_read_b128 v[144:147], v144 offset:3072
	ds_read_b128 v[148:151], v160
	ds_read_b128 v[152:155], v160 offset:1024
	ds_read_b128 v[156:159], v160 offset:2048
	ds_read_b128 v[160:163], v160 offset:3072
	ds_read_b128 v[164:167], v238
	ds_read_b128 v[168:171], v238 offset:1024
	ds_read_b128 v[172:175], v238 offset:2048
	ds_read_b128 v[176:179], v238 offset:3072
	ds_read_b128 v[180:183], v238 offset:4096
	ds_read_b128 v[184:187], v238 offset:5120
	ds_read_b128 v[188:191], v238 offset:6144
	ds_read_b128 v[192:195], v238 offset:7168
	s_waitcnt vmcnt(8)
	s_waitcnt lgkmcnt(0)
	s_barrier
	s_setprio 1
	s_waitcnt lgkmcnt(0)
	v_mfma_f32_16x16x32_bf16 v[128:131], v[132:135], v[164:167], 0
	v_mfma_f32_16x16x32_bf16 v[128:131], v[136:139], v[168:171], v[128:131]
	v_mfma_f32_16x16x32_bf16 v[116:119], v[132:135], v[172:175], 0
	v_mfma_f32_16x16x32_bf16 v[116:119], v[136:139], v[176:179], v[116:119]
	v_mfma_f32_16x16x32_bf16 v[100:103], v[132:135], v[180:183], 0
	v_mfma_f32_16x16x32_bf16 v[100:103], v[136:139], v[184:187], v[100:103]
	v_mfma_f32_16x16x32_bf16 v[84:87], v[132:135], v[188:191], 0
	v_mfma_f32_16x16x32_bf16 v[84:87], v[136:139], v[192:195], v[84:87]
	v_mfma_f32_16x16x32_bf16 v[120:123], v[148:151], v[164:167], 0
	v_mfma_f32_16x16x32_bf16 v[120:123], v[152:155], v[168:171], v[120:123]
	v_mfma_f32_16x16x32_bf16 v[104:107], v[148:151], v[172:175], 0
	v_mfma_f32_16x16x32_bf16 v[104:107], v[152:155], v[176:179], v[104:107]
	v_mfma_f32_16x16x32_bf16 v[88:91], v[148:151], v[180:183], 0
	v_mfma_f32_16x16x32_bf16 v[88:91], v[152:155], v[184:187], v[88:91]
	v_mfma_f32_16x16x32_bf16 v[72:75], v[148:151], v[188:191], 0
	v_mfma_f32_16x16x32_bf16 v[72:75], v[152:155], v[192:195], v[72:75]
	v_mfma_f32_16x16x32_bf16 v[124:127], v[140:143], v[164:167], 0
	v_mfma_f32_16x16x32_bf16 v[124:127], v[144:147], v[168:171], v[124:127]
	v_mfma_f32_16x16x32_bf16 v[108:111], v[140:143], v[172:175], 0
	v_mfma_f32_16x16x32_bf16 v[108:111], v[144:147], v[176:179], v[108:111]
	v_mfma_f32_16x16x32_bf16 v[92:95], v[140:143], v[180:183], 0
	v_mfma_f32_16x16x32_bf16 v[92:95], v[144:147], v[184:187], v[92:95]
	v_mfma_f32_16x16x32_bf16 v[76:79], v[140:143], v[188:191], 0
	v_mfma_f32_16x16x32_bf16 v[76:79], v[144:147], v[192:195], v[76:79]
	v_mfma_f32_16x16x32_bf16 v[112:115], v[156:159], v[164:167], 0
	v_mfma_f32_16x16x32_bf16 v[112:115], v[160:163], v[168:171], v[112:115]
	v_mfma_f32_16x16x32_bf16 v[96:99], v[156:159], v[172:175], 0
	v_mfma_f32_16x16x32_bf16 v[96:99], v[160:163], v[176:179], v[96:99]
	v_mfma_f32_16x16x32_bf16 v[80:83], v[156:159], v[180:183], 0
	v_mfma_f32_16x16x32_bf16 v[80:83], v[160:163], v[184:187], v[80:83]
	v_mfma_f32_16x16x32_bf16 v[68:71], v[156:159], v[188:191], 0
	v_mfma_f32_16x16x32_bf16 v[68:71], v[160:163], v[192:195], v[68:71]
	s_setprio 0
	s_barrier
	s_sleep 2
	s_add_i32 s14, s44, s22
	v_lshl_add_u64 v[204:205], s[18:19], 0, v[2:3]
	s_mov_b32 m0, s14
	ds_read_b128 v[164:167], v238 offset:16384
	ds_read_b128 v[168:171], v238 offset:17408
	ds_read_b128 v[172:175], v238 offset:18432
	ds_read_b128 v[176:179], v238 offset:19456
	ds_read_b128 v[180:183], v238 offset:20480
	ds_read_b128 v[184:187], v238 offset:21504
	ds_read_b128 v[188:191], v238 offset:22528
	ds_read_b128 v[192:195], v238 offset:23552
	global_load_lds_dwordx4 v[204:205], off
	s_add_i32 m0, s14, 0x2000
	s_add_u32 s14, s18, 0x160000
	v_lshl_add_u64 v[206:207], s[18:19], 0, v[198:199]
	s_addc_u32 s15, s19, 0
	s_add_i32 s44, s45, s22
	global_load_lds_dwordx4 v[206:207], off
	v_lshl_add_u64 v[208:209], s[14:15], 0, v[2:3]
	s_mov_b32 m0, s44
	v_lshl_add_u64 v[210:211], s[20:21], 0, v[196:197]
	global_load_lds_dwordx4 v[208:209], off
	v_lshl_add_u64 v[208:209], s[14:15], 0, v[198:199]
	s_add_i32 m0, s44, 0x2000
	s_nop 0
	global_load_lds_dwordx4 v[208:209], off
	v_lshl_add_u64 v[208:209], s[20:21], 0, v[0:1]
	s_mov_b32 m0, s23
	s_nop 0
	global_load_lds_dwordx4 v[208:209], off
	s_mov_b32 m0, s28
	s_nop 0
	global_load_lds_dwordx4 v[210:211], off
	s_waitcnt vmcnt(8)
	s_waitcnt lgkmcnt(0)
	s_barrier
	s_setprio 1
	s_waitcnt lgkmcnt(0)
	v_mfma_f32_16x16x32_bf16 v[64:67], v[132:135], v[164:167], 0
	v_mfma_f32_16x16x32_bf16 v[64:67], v[136:139], v[168:171], v[64:67]
	v_mfma_f32_16x16x32_bf16 v[52:55], v[132:135], v[172:175], 0
	v_mfma_f32_16x16x32_bf16 v[52:55], v[136:139], v[176:179], v[52:55]
	v_mfma_f32_16x16x32_bf16 v[36:39], v[132:135], v[180:183], 0
	v_mfma_f32_16x16x32_bf16 v[36:39], v[136:139], v[184:187], v[36:39]
	v_mfma_f32_16x16x32_bf16 v[20:23], v[132:135], v[188:191], 0
	v_mfma_f32_16x16x32_bf16 v[20:23], v[136:139], v[192:195], v[20:23]
	v_mfma_f32_16x16x32_bf16 v[56:59], v[148:151], v[164:167], 0
	v_mfma_f32_16x16x32_bf16 v[56:59], v[152:155], v[168:171], v[56:59]
	v_mfma_f32_16x16x32_bf16 v[40:43], v[148:151], v[172:175], 0
	v_mfma_f32_16x16x32_bf16 v[40:43], v[152:155], v[176:179], v[40:43]
	v_mfma_f32_16x16x32_bf16 v[24:27], v[148:151], v[180:183], 0
	v_mfma_f32_16x16x32_bf16 v[24:27], v[152:155], v[184:187], v[24:27]
	v_mfma_f32_16x16x32_bf16 v[8:11], v[148:151], v[188:191], 0
	v_mfma_f32_16x16x32_bf16 v[8:11], v[152:155], v[192:195], v[8:11]
	v_mfma_f32_16x16x32_bf16 v[60:63], v[140:143], v[164:167], 0
	v_mfma_f32_16x16x32_bf16 v[60:63], v[144:147], v[168:171], v[60:63]
	v_mfma_f32_16x16x32_bf16 v[44:47], v[140:143], v[172:175], 0
	v_mfma_f32_16x16x32_bf16 v[44:47], v[144:147], v[176:179], v[44:47]
	v_mfma_f32_16x16x32_bf16 v[28:31], v[140:143], v[180:183], 0
	v_mfma_f32_16x16x32_bf16 v[28:31], v[144:147], v[184:187], v[28:31]
	v_mfma_f32_16x16x32_bf16 v[12:15], v[140:143], v[188:191], 0
	v_mfma_f32_16x16x32_bf16 v[12:15], v[144:147], v[192:195], v[12:15]
	v_mfma_f32_16x16x32_bf16 v[48:51], v[156:159], v[164:167], 0
	v_mfma_f32_16x16x32_bf16 v[48:51], v[160:163], v[168:171], v[48:51]
	v_mfma_f32_16x16x32_bf16 v[32:35], v[156:159], v[172:175], 0
	v_mfma_f32_16x16x32_bf16 v[32:35], v[160:163], v[176:179], v[32:35]
	v_mfma_f32_16x16x32_bf16 v[16:19], v[156:159], v[180:183], 0
	v_mfma_f32_16x16x32_bf16 v[16:19], v[160:163], v[184:187], v[16:19]
	v_mfma_f32_16x16x32_bf16 v[4:7], v[156:159], v[188:191], 0
	v_mfma_f32_16x16x32_bf16 v[4:7], v[160:163], v[192:195], v[4:7]
	s_setprio 0
	s_barrier
	s_sleep 1
	s_add_i32 s44, 0, 0x18000
	s_add_i32 s45, 0, 0x1c000
	s_add_u32 s14, s20, 0x160000
	s_addc_u32 s15, s21, 0
	s_mov_b32 m0, s29
	v_lshl_add_u64 v[212:213], s[14:15], 0, v[0:1]
	global_load_lds_dwordx4 v[212:213], off
	v_lshl_add_u64 v[212:213], s[14:15], 0, v[196:197]
	s_mov_b32 m0, s30
	s_nop 0
	global_load_lds_dwordx4 v[212:213], off
	v_add_u32_e32 v144, s44, v236
	v_add_u32_e32 v160, s45, v236
	ds_read_b128 v[132:135], v144
	ds_read_b128 v[136:139], v144 offset:1024
	ds_read_b128 v[140:143], v144 offset:2048
	ds_read_b128 v[144:147], v144 offset:3072
	ds_read_b128 v[148:151], v160
	ds_read_b128 v[152:155], v160 offset:1024
	ds_read_b128 v[156:159], v160 offset:2048
	ds_read_b128 v[160:163], v160 offset:3072
	ds_read_b128 v[164:167], v238 offset:32768
	ds_read_b128 v[168:171], v238 offset:33792
	ds_read_b128 v[172:175], v238 offset:34816
	ds_read_b128 v[176:179], v238 offset:35840
	ds_read_b128 v[180:183], v238 offset:36864
	ds_read_b128 v[184:187], v238 offset:37888
	ds_read_b128 v[188:191], v238 offset:38912
	ds_read_b128 v[192:195], v238 offset:39936
	s_waitcnt vmcnt(8)
	s_waitcnt lgkmcnt(0)
	s_barrier
	s_setprio 1
	s_waitcnt lgkmcnt(0)
	v_mfma_f32_16x16x32_bf16 v[128:131], v[132:135], v[164:167], v[128:131]
	v_mfma_f32_16x16x32_bf16 v[128:131], v[136:139], v[168:171], v[128:131]
	v_mfma_f32_16x16x32_bf16 v[116:119], v[132:135], v[172:175], v[116:119]
	v_mfma_f32_16x16x32_bf16 v[116:119], v[136:139], v[176:179], v[116:119]
	v_mfma_f32_16x16x32_bf16 v[100:103], v[132:135], v[180:183], v[100:103]
	v_mfma_f32_16x16x32_bf16 v[100:103], v[136:139], v[184:187], v[100:103]
	v_mfma_f32_16x16x32_bf16 v[84:87], v[132:135], v[188:191], v[84:87]
	v_mfma_f32_16x16x32_bf16 v[84:87], v[136:139], v[192:195], v[84:87]
	v_mfma_f32_16x16x32_bf16 v[120:123], v[148:151], v[164:167], v[120:123]
	v_mfma_f32_16x16x32_bf16 v[120:123], v[152:155], v[168:171], v[120:123]
	v_mfma_f32_16x16x32_bf16 v[104:107], v[148:151], v[172:175], v[104:107]
	v_mfma_f32_16x16x32_bf16 v[104:107], v[152:155], v[176:179], v[104:107]
	v_mfma_f32_16x16x32_bf16 v[88:91], v[148:151], v[180:183], v[88:91]
	v_mfma_f32_16x16x32_bf16 v[88:91], v[152:155], v[184:187], v[88:91]
	v_mfma_f32_16x16x32_bf16 v[72:75], v[148:151], v[188:191], v[72:75]
	v_mfma_f32_16x16x32_bf16 v[72:75], v[152:155], v[192:195], v[72:75]
	v_mfma_f32_16x16x32_bf16 v[124:127], v[140:143], v[164:167], v[124:127]
	v_mfma_f32_16x16x32_bf16 v[124:127], v[144:147], v[168:171], v[124:127]
	v_mfma_f32_16x16x32_bf16 v[108:111], v[140:143], v[172:175], v[108:111]
	v_mfma_f32_16x16x32_bf16 v[108:111], v[144:147], v[176:179], v[108:111]
	v_mfma_f32_16x16x32_bf16 v[92:95], v[140:143], v[180:183], v[92:95]
	v_mfma_f32_16x16x32_bf16 v[92:95], v[144:147], v[184:187], v[92:95]
	v_mfma_f32_16x16x32_bf16 v[76:79], v[140:143], v[188:191], v[76:79]
	v_mfma_f32_16x16x32_bf16 v[76:79], v[144:147], v[192:195], v[76:79]
	v_mfma_f32_16x16x32_bf16 v[112:115], v[156:159], v[164:167], v[112:115]
	v_mfma_f32_16x16x32_bf16 v[112:115], v[160:163], v[168:171], v[112:115]
	v_mfma_f32_16x16x32_bf16 v[96:99], v[156:159], v[172:175], v[96:99]
	v_mfma_f32_16x16x32_bf16 v[96:99], v[160:163], v[176:179], v[96:99]
	v_mfma_f32_16x16x32_bf16 v[80:83], v[156:159], v[180:183], v[80:83]
	v_mfma_f32_16x16x32_bf16 v[80:83], v[160:163], v[184:187], v[80:83]
	v_mfma_f32_16x16x32_bf16 v[68:71], v[156:159], v[188:191], v[68:71]
	v_mfma_f32_16x16x32_bf16 v[68:71], v[160:163], v[192:195], v[68:71]
	s_setprio 0
	s_barrier
	s_sleep 2
	s_add_i32 s14, s44, s22
	v_lshl_add_u64 v[204:205], v[204:205], 0, s[66:67]
	s_mov_b32 m0, s14
	ds_read_b128 v[164:167], v238 offset:49152
	ds_read_b128 v[168:171], v238 offset:50176
	ds_read_b128 v[172:175], v238 offset:51200
	ds_read_b128 v[176:179], v238 offset:52224
	ds_read_b128 v[180:183], v238 offset:53248
	ds_read_b128 v[184:187], v238 offset:54272
	ds_read_b128 v[188:191], v238 offset:55296
	ds_read_b128 v[192:195], v238 offset:56320
	global_load_lds_dwordx4 v[204:205], off
	s_add_i32 m0, s14, 0x2000
	s_add_u32 s14, s18, 0x160080
	v_lshl_add_u64 v[204:205], v[206:207], 0, s[66:67]
	s_addc_u32 s15, s19, 0
	s_add_i32 s18, s45, s22
	global_load_lds_dwordx4 v[204:205], off
	v_lshl_add_u64 v[204:205], s[14:15], 0, v[2:3]
	s_mov_b32 m0, s18
	s_nop 0
	global_load_lds_dwordx4 v[204:205], off
	v_lshl_add_u64 v[204:205], s[14:15], 0, v[198:199]
	s_add_i32 m0, s18, 0x2000
	s_nop 0
	global_load_lds_dwordx4 v[204:205], off
	v_lshl_add_u64 v[204:205], v[208:209], 0, s[66:67]
	s_mov_b32 m0, s31
	s_nop 0
	global_load_lds_dwordx4 v[204:205], off
	v_lshl_add_u64 v[204:205], v[210:211], 0, s[66:67]
	s_mov_b32 m0, s34
	s_nop 0
	global_load_lds_dwordx4 v[204:205], off
	s_waitcnt vmcnt(8)
	s_waitcnt lgkmcnt(0)
	s_barrier
	s_setprio 1
	s_waitcnt lgkmcnt(0)
	v_mfma_f32_16x16x32_bf16 v[64:67], v[132:135], v[164:167], v[64:67]
	v_mfma_f32_16x16x32_bf16 v[64:67], v[136:139], v[168:171], v[64:67]
	v_mfma_f32_16x16x32_bf16 v[52:55], v[132:135], v[172:175], v[52:55]
	v_mfma_f32_16x16x32_bf16 v[52:55], v[136:139], v[176:179], v[52:55]
	v_mfma_f32_16x16x32_bf16 v[36:39], v[132:135], v[180:183], v[36:39]
	v_mfma_f32_16x16x32_bf16 v[36:39], v[136:139], v[184:187], v[36:39]
	v_mfma_f32_16x16x32_bf16 v[20:23], v[132:135], v[188:191], v[20:23]
	v_mfma_f32_16x16x32_bf16 v[20:23], v[136:139], v[192:195], v[20:23]
	v_mfma_f32_16x16x32_bf16 v[56:59], v[148:151], v[164:167], v[56:59]
	v_mfma_f32_16x16x32_bf16 v[56:59], v[152:155], v[168:171], v[56:59]
	v_mfma_f32_16x16x32_bf16 v[40:43], v[148:151], v[172:175], v[40:43]
	v_mfma_f32_16x16x32_bf16 v[40:43], v[152:155], v[176:179], v[40:43]
	v_mfma_f32_16x16x32_bf16 v[24:27], v[148:151], v[180:183], v[24:27]
	v_mfma_f32_16x16x32_bf16 v[24:27], v[152:155], v[184:187], v[24:27]
	v_mfma_f32_16x16x32_bf16 v[8:11], v[148:151], v[188:191], v[8:11]
	v_mfma_f32_16x16x32_bf16 v[8:11], v[152:155], v[192:195], v[8:11]
	v_mfma_f32_16x16x32_bf16 v[60:63], v[140:143], v[164:167], v[60:63]
	v_mfma_f32_16x16x32_bf16 v[60:63], v[144:147], v[168:171], v[60:63]
	v_mfma_f32_16x16x32_bf16 v[44:47], v[140:143], v[172:175], v[44:47]
	v_mfma_f32_16x16x32_bf16 v[44:47], v[144:147], v[176:179], v[44:47]
	v_mfma_f32_16x16x32_bf16 v[28:31], v[140:143], v[180:183], v[28:31]
	v_mfma_f32_16x16x32_bf16 v[28:31], v[144:147], v[184:187], v[28:31]
	v_mfma_f32_16x16x32_bf16 v[12:15], v[140:143], v[188:191], v[12:15]
	v_mfma_f32_16x16x32_bf16 v[12:15], v[144:147], v[192:195], v[12:15]
	v_mfma_f32_16x16x32_bf16 v[48:51], v[156:159], v[164:167], v[48:51]
	v_mfma_f32_16x16x32_bf16 v[48:51], v[160:163], v[168:171], v[48:51]
	v_mfma_f32_16x16x32_bf16 v[32:35], v[156:159], v[172:175], v[32:35]
	v_mfma_f32_16x16x32_bf16 v[32:35], v[160:163], v[176:179], v[32:35]
	v_mfma_f32_16x16x32_bf16 v[16:19], v[156:159], v[180:183], v[16:19]
	v_mfma_f32_16x16x32_bf16 v[16:19], v[160:163], v[184:187], v[16:19]
	v_mfma_f32_16x16x32_bf16 v[4:7], v[156:159], v[188:191], v[4:7]
	v_mfma_f32_16x16x32_bf16 v[4:7], v[160:163], v[192:195], v[4:7]
	s_setprio 0
	s_barrier
	s_add_i32 s43, s43, 2
	s_add_u32 s38, s38, 0x100
	s_addc_u32 s39, s39, 0
	s_cmpk_gt_u32 s43, 0x55
	s_mov_b64 s[14:15], s[16:17]
.LBB0_347:
	s_sleep 1
	s_add_u32 s16, s14, 0x100
	s_addc_u32 s17, s15, 0
	s_add_i32 s44, 0, 0x10000
	s_cmpk_eq_i32 s43, 0x54
	s_cselect_b32 s21, s11, s17
	s_cselect_b32 s20, s10, s16
	s_cselect_b32 s19, s13, s39
	s_cselect_b32 s18, s12, s38
	s_add_i32 s45, 0, 0x14000
	v_lshl_add_u64 v[204:205], s[14:15], 0, v[200:201]
	s_add_i32 m0, s23, 0xc000
	s_nop 0
	global_load_lds_dwordx4 v[204:205], off
	v_lshl_add_u64 v[204:205], s[14:15], 0, v[202:203]
	s_add_i32 m0, s23, 0xe000
	s_nop 0
	global_load_lds_dwordx4 v[204:205], off
	v_add_u32_e32 v144, s44, v236
	v_add_u32_e32 v160, s45, v236
	ds_read_b128 v[132:135], v144
	ds_read_b128 v[136:139], v144 offset:1024
	ds_read_b128 v[140:143], v144 offset:2048
	ds_read_b128 v[144:147], v144 offset:3072
	ds_read_b128 v[148:151], v160
	ds_read_b128 v[152:155], v160 offset:1024
	ds_read_b128 v[156:159], v160 offset:2048
	ds_read_b128 v[160:163], v160 offset:3072
	ds_read_b128 v[164:167], v238
	ds_read_b128 v[168:171], v238 offset:1024
	ds_read_b128 v[172:175], v238 offset:2048
	ds_read_b128 v[176:179], v238 offset:3072
	ds_read_b128 v[180:183], v238 offset:4096
	ds_read_b128 v[184:187], v238 offset:5120
	ds_read_b128 v[188:191], v238 offset:6144
	ds_read_b128 v[192:195], v238 offset:7168
	s_waitcnt vmcnt(8)
	s_waitcnt lgkmcnt(0)
	s_barrier
	s_setprio 1
	s_waitcnt lgkmcnt(0)
	v_mfma_f32_16x16x32_bf16 v[128:131], v[132:135], v[164:167], v[128:131]
	v_mfma_f32_16x16x32_bf16 v[128:131], v[136:139], v[168:171], v[128:131]
	v_mfma_f32_16x16x32_bf16 v[116:119], v[132:135], v[172:175], v[116:119]
	v_mfma_f32_16x16x32_bf16 v[116:119], v[136:139], v[176:179], v[116:119]
	v_mfma_f32_16x16x32_bf16 v[100:103], v[132:135], v[180:183], v[100:103]
	v_mfma_f32_16x16x32_bf16 v[100:103], v[136:139], v[184:187], v[100:103]
	v_mfma_f32_16x16x32_bf16 v[84:87], v[132:135], v[188:191], v[84:87]
	v_mfma_f32_16x16x32_bf16 v[84:87], v[136:139], v[192:195], v[84:87]
	v_mfma_f32_16x16x32_bf16 v[120:123], v[148:151], v[164:167], v[120:123]
	v_mfma_f32_16x16x32_bf16 v[120:123], v[152:155], v[168:171], v[120:123]
	v_mfma_f32_16x16x32_bf16 v[104:107], v[148:151], v[172:175], v[104:107]
	v_mfma_f32_16x16x32_bf16 v[104:107], v[152:155], v[176:179], v[104:107]
	v_mfma_f32_16x16x32_bf16 v[88:91], v[148:151], v[180:183], v[88:91]
	v_mfma_f32_16x16x32_bf16 v[88:91], v[152:155], v[184:187], v[88:91]
	v_mfma_f32_16x16x32_bf16 v[72:75], v[148:151], v[188:191], v[72:75]
	v_mfma_f32_16x16x32_bf16 v[72:75], v[152:155], v[192:195], v[72:75]
	v_mfma_f32_16x16x32_bf16 v[124:127], v[140:143], v[164:167], v[124:127]
	v_mfma_f32_16x16x32_bf16 v[124:127], v[144:147], v[168:171], v[124:127]
	v_mfma_f32_16x16x32_bf16 v[108:111], v[140:143], v[172:175], v[108:111]
	v_mfma_f32_16x16x32_bf16 v[108:111], v[144:147], v[176:179], v[108:111]
	v_mfma_f32_16x16x32_bf16 v[92:95], v[140:143], v[180:183], v[92:95]
	v_mfma_f32_16x16x32_bf16 v[92:95], v[144:147], v[184:187], v[92:95]
	v_mfma_f32_16x16x32_bf16 v[76:79], v[140:143], v[188:191], v[76:79]
	v_mfma_f32_16x16x32_bf16 v[76:79], v[144:147], v[192:195], v[76:79]
	v_mfma_f32_16x16x32_bf16 v[112:115], v[156:159], v[164:167], v[112:115]
	v_mfma_f32_16x16x32_bf16 v[112:115], v[160:163], v[168:171], v[112:115]
	v_mfma_f32_16x16x32_bf16 v[96:99], v[156:159], v[172:175], v[96:99]
	v_mfma_f32_16x16x32_bf16 v[96:99], v[160:163], v[176:179], v[96:99]
	v_mfma_f32_16x16x32_bf16 v[80:83], v[156:159], v[180:183], v[80:83]
	v_mfma_f32_16x16x32_bf16 v[80:83], v[160:163], v[184:187], v[80:83]
	v_mfma_f32_16x16x32_bf16 v[68:71], v[156:159], v[188:191], v[68:71]
	v_mfma_f32_16x16x32_bf16 v[68:71], v[160:163], v[192:195], v[68:71]
	s_setprio 0
	s_barrier
	s_sleep 2
	s_add_i32 s14, s44, s22
	v_lshl_add_u64 v[204:205], s[18:19], 0, v[2:3]
	s_mov_b32 m0, s14
	ds_read_b128 v[164:167], v238 offset:16384
	ds_read_b128 v[168:171], v238 offset:17408
	ds_read_b128 v[172:175], v238 offset:18432
	ds_read_b128 v[176:179], v238 offset:19456
	ds_read_b128 v[180:183], v238 offset:20480
	ds_read_b128 v[184:187], v238 offset:21504
	ds_read_b128 v[188:191], v238 offset:22528
	ds_read_b128 v[192:195], v238 offset:23552
	global_load_lds_dwordx4 v[204:205], off
	s_add_i32 m0, s14, 0x2000
	s_add_u32 s14, s18, 0x160000
	v_lshl_add_u64 v[206:207], s[18:19], 0, v[198:199]
	s_addc_u32 s15, s19, 0
	s_add_i32 s44, s45, s22
	global_load_lds_dwordx4 v[206:207], off
	v_lshl_add_u64 v[208:209], s[14:15], 0, v[2:3]
	s_mov_b32 m0, s44
	v_lshl_add_u64 v[210:211], s[20:21], 0, v[196:197]
	global_load_lds_dwordx4 v[208:209], off
	v_lshl_add_u64 v[208:209], s[14:15], 0, v[198:199]
	s_add_i32 m0, s44, 0x2000
	s_nop 0
	global_load_lds_dwordx4 v[208:209], off
	v_lshl_add_u64 v[208:209], s[20:21], 0, v[0:1]
	s_mov_b32 m0, s23
	s_nop 0
	global_load_lds_dwordx4 v[208:209], off
	s_mov_b32 m0, s28
	s_nop 0
	global_load_lds_dwordx4 v[210:211], off
	s_waitcnt vmcnt(8)
	s_waitcnt lgkmcnt(0)
	s_barrier
	s_setprio 1
	s_waitcnt lgkmcnt(0)
	v_mfma_f32_16x16x32_bf16 v[64:67], v[132:135], v[164:167], v[64:67]
	v_mfma_f32_16x16x32_bf16 v[64:67], v[136:139], v[168:171], v[64:67]
	v_mfma_f32_16x16x32_bf16 v[52:55], v[132:135], v[172:175], v[52:55]
	v_mfma_f32_16x16x32_bf16 v[52:55], v[136:139], v[176:179], v[52:55]
	v_mfma_f32_16x16x32_bf16 v[36:39], v[132:135], v[180:183], v[36:39]
	v_mfma_f32_16x16x32_bf16 v[36:39], v[136:139], v[184:187], v[36:39]
	v_mfma_f32_16x16x32_bf16 v[20:23], v[132:135], v[188:191], v[20:23]
	v_mfma_f32_16x16x32_bf16 v[20:23], v[136:139], v[192:195], v[20:23]
	v_mfma_f32_16x16x32_bf16 v[56:59], v[148:151], v[164:167], v[56:59]
	v_mfma_f32_16x16x32_bf16 v[56:59], v[152:155], v[168:171], v[56:59]
	v_mfma_f32_16x16x32_bf16 v[40:43], v[148:151], v[172:175], v[40:43]
	v_mfma_f32_16x16x32_bf16 v[40:43], v[152:155], v[176:179], v[40:43]
	v_mfma_f32_16x16x32_bf16 v[24:27], v[148:151], v[180:183], v[24:27]
	v_mfma_f32_16x16x32_bf16 v[24:27], v[152:155], v[184:187], v[24:27]
	v_mfma_f32_16x16x32_bf16 v[8:11], v[148:151], v[188:191], v[8:11]
	v_mfma_f32_16x16x32_bf16 v[8:11], v[152:155], v[192:195], v[8:11]
	v_mfma_f32_16x16x32_bf16 v[60:63], v[140:143], v[164:167], v[60:63]
	v_mfma_f32_16x16x32_bf16 v[60:63], v[144:147], v[168:171], v[60:63]
	v_mfma_f32_16x16x32_bf16 v[44:47], v[140:143], v[172:175], v[44:47]
	v_mfma_f32_16x16x32_bf16 v[44:47], v[144:147], v[176:179], v[44:47]
	v_mfma_f32_16x16x32_bf16 v[28:31], v[140:143], v[180:183], v[28:31]
	v_mfma_f32_16x16x32_bf16 v[28:31], v[144:147], v[184:187], v[28:31]
	v_mfma_f32_16x16x32_bf16 v[12:15], v[140:143], v[188:191], v[12:15]
	v_mfma_f32_16x16x32_bf16 v[12:15], v[144:147], v[192:195], v[12:15]
	v_mfma_f32_16x16x32_bf16 v[48:51], v[156:159], v[164:167], v[48:51]
	v_mfma_f32_16x16x32_bf16 v[48:51], v[160:163], v[168:171], v[48:51]
	v_mfma_f32_16x16x32_bf16 v[32:35], v[156:159], v[172:175], v[32:35]
	v_mfma_f32_16x16x32_bf16 v[32:35], v[160:163], v[176:179], v[32:35]
	v_mfma_f32_16x16x32_bf16 v[16:19], v[156:159], v[180:183], v[16:19]
	v_mfma_f32_16x16x32_bf16 v[16:19], v[160:163], v[184:187], v[16:19]
	v_mfma_f32_16x16x32_bf16 v[4:7], v[156:159], v[188:191], v[4:7]
	v_mfma_f32_16x16x32_bf16 v[4:7], v[160:163], v[192:195], v[4:7]
	s_setprio 0
	s_barrier
	s_sleep 1
	s_add_i32 s44, 0, 0x18000
	s_add_i32 s45, 0, 0x1c000
	s_add_u32 s14, s20, 0x160000
	s_addc_u32 s15, s21, 0
	s_mov_b32 m0, s29
	v_lshl_add_u64 v[212:213], s[14:15], 0, v[0:1]
	global_load_lds_dwordx4 v[212:213], off
	v_lshl_add_u64 v[212:213], s[14:15], 0, v[196:197]
	s_mov_b32 m0, s30
	s_nop 0
	global_load_lds_dwordx4 v[212:213], off
	v_add_u32_e32 v144, s44, v236
	v_add_u32_e32 v160, s45, v236
	ds_read_b128 v[132:135], v144
	ds_read_b128 v[136:139], v144 offset:1024
	ds_read_b128 v[140:143], v144 offset:2048
	ds_read_b128 v[144:147], v144 offset:3072
	ds_read_b128 v[148:151], v160
	ds_read_b128 v[152:155], v160 offset:1024
	ds_read_b128 v[156:159], v160 offset:2048
	ds_read_b128 v[160:163], v160 offset:3072
	ds_read_b128 v[164:167], v238 offset:32768
	ds_read_b128 v[168:171], v238 offset:33792
	ds_read_b128 v[172:175], v238 offset:34816
	ds_read_b128 v[176:179], v238 offset:35840
	ds_read_b128 v[180:183], v238 offset:36864
	ds_read_b128 v[184:187], v238 offset:37888
	ds_read_b128 v[188:191], v238 offset:38912
	ds_read_b128 v[192:195], v238 offset:39936
	s_waitcnt vmcnt(8)
	s_waitcnt lgkmcnt(0)
	s_barrier
	s_setprio 1
	s_waitcnt lgkmcnt(0)
	v_mfma_f32_16x16x32_bf16 v[128:131], v[132:135], v[164:167], v[128:131]
	v_mfma_f32_16x16x32_bf16 v[128:131], v[136:139], v[168:171], v[128:131]
	v_mfma_f32_16x16x32_bf16 v[116:119], v[132:135], v[172:175], v[116:119]
	v_mfma_f32_16x16x32_bf16 v[116:119], v[136:139], v[176:179], v[116:119]
	v_mfma_f32_16x16x32_bf16 v[100:103], v[132:135], v[180:183], v[100:103]
	v_mfma_f32_16x16x32_bf16 v[100:103], v[136:139], v[184:187], v[100:103]
	v_mfma_f32_16x16x32_bf16 v[84:87], v[132:135], v[188:191], v[84:87]
	v_mfma_f32_16x16x32_bf16 v[84:87], v[136:139], v[192:195], v[84:87]
	v_mfma_f32_16x16x32_bf16 v[120:123], v[148:151], v[164:167], v[120:123]
	v_mfma_f32_16x16x32_bf16 v[120:123], v[152:155], v[168:171], v[120:123]
	v_mfma_f32_16x16x32_bf16 v[104:107], v[148:151], v[172:175], v[104:107]
	v_mfma_f32_16x16x32_bf16 v[104:107], v[152:155], v[176:179], v[104:107]
	v_mfma_f32_16x16x32_bf16 v[88:91], v[148:151], v[180:183], v[88:91]
	v_mfma_f32_16x16x32_bf16 v[88:91], v[152:155], v[184:187], v[88:91]
	v_mfma_f32_16x16x32_bf16 v[72:75], v[148:151], v[188:191], v[72:75]
	v_mfma_f32_16x16x32_bf16 v[72:75], v[152:155], v[192:195], v[72:75]
	v_mfma_f32_16x16x32_bf16 v[124:127], v[140:143], v[164:167], v[124:127]
	v_mfma_f32_16x16x32_bf16 v[124:127], v[144:147], v[168:171], v[124:127]
	v_mfma_f32_16x16x32_bf16 v[108:111], v[140:143], v[172:175], v[108:111]
	v_mfma_f32_16x16x32_bf16 v[108:111], v[144:147], v[176:179], v[108:111]
	v_mfma_f32_16x16x32_bf16 v[92:95], v[140:143], v[180:183], v[92:95]
	v_mfma_f32_16x16x32_bf16 v[92:95], v[144:147], v[184:187], v[92:95]
	v_mfma_f32_16x16x32_bf16 v[76:79], v[140:143], v[188:191], v[76:79]
	v_mfma_f32_16x16x32_bf16 v[76:79], v[144:147], v[192:195], v[76:79]
	v_mfma_f32_16x16x32_bf16 v[112:115], v[156:159], v[164:167], v[112:115]
	v_mfma_f32_16x16x32_bf16 v[112:115], v[160:163], v[168:171], v[112:115]
	v_mfma_f32_16x16x32_bf16 v[96:99], v[156:159], v[172:175], v[96:99]
	v_mfma_f32_16x16x32_bf16 v[96:99], v[160:163], v[176:179], v[96:99]
	v_mfma_f32_16x16x32_bf16 v[80:83], v[156:159], v[180:183], v[80:83]
	v_mfma_f32_16x16x32_bf16 v[80:83], v[160:163], v[184:187], v[80:83]
	v_mfma_f32_16x16x32_bf16 v[68:71], v[156:159], v[188:191], v[68:71]
	v_mfma_f32_16x16x32_bf16 v[68:71], v[160:163], v[192:195], v[68:71]
	s_setprio 0
	s_barrier
	s_sleep 2
	s_add_i32 s14, s44, s22
	v_lshl_add_u64 v[204:205], v[204:205], 0, s[66:67]
	s_mov_b32 m0, s14
	ds_read_b128 v[164:167], v238 offset:49152
	ds_read_b128 v[168:171], v238 offset:50176
	ds_read_b128 v[172:175], v238 offset:51200
	ds_read_b128 v[176:179], v238 offset:52224
	ds_read_b128 v[180:183], v238 offset:53248
	ds_read_b128 v[184:187], v238 offset:54272
	ds_read_b128 v[188:191], v238 offset:55296
	ds_read_b128 v[192:195], v238 offset:56320
	global_load_lds_dwordx4 v[204:205], off
	s_add_i32 m0, s14, 0x2000
	s_add_u32 s14, s18, 0x160080
	v_lshl_add_u64 v[204:205], v[206:207], 0, s[66:67]
	s_addc_u32 s15, s19, 0
	s_add_i32 s18, s45, s22
	global_load_lds_dwordx4 v[204:205], off
	v_lshl_add_u64 v[204:205], s[14:15], 0, v[2:3]
	s_mov_b32 m0, s18
	s_nop 0
	global_load_lds_dwordx4 v[204:205], off
	v_lshl_add_u64 v[204:205], s[14:15], 0, v[198:199]
	s_add_i32 m0, s18, 0x2000
	s_nop 0
	global_load_lds_dwordx4 v[204:205], off
	v_lshl_add_u64 v[204:205], v[208:209], 0, s[66:67]
	s_mov_b32 m0, s31
	s_nop 0
	global_load_lds_dwordx4 v[204:205], off
	v_lshl_add_u64 v[204:205], v[210:211], 0, s[66:67]
	s_mov_b32 m0, s34
	s_nop 0
	global_load_lds_dwordx4 v[204:205], off
	s_waitcnt vmcnt(8)
	s_waitcnt lgkmcnt(0)
	s_barrier
	s_setprio 1
	s_waitcnt lgkmcnt(0)
	v_mfma_f32_16x16x32_bf16 v[64:67], v[132:135], v[164:167], v[64:67]
	v_mfma_f32_16x16x32_bf16 v[64:67], v[136:139], v[168:171], v[64:67]
	v_mfma_f32_16x16x32_bf16 v[52:55], v[132:135], v[172:175], v[52:55]
	v_mfma_f32_16x16x32_bf16 v[52:55], v[136:139], v[176:179], v[52:55]
	v_mfma_f32_16x16x32_bf16 v[36:39], v[132:135], v[180:183], v[36:39]
	v_mfma_f32_16x16x32_bf16 v[36:39], v[136:139], v[184:187], v[36:39]
	v_mfma_f32_16x16x32_bf16 v[20:23], v[132:135], v[188:191], v[20:23]
	v_mfma_f32_16x16x32_bf16 v[20:23], v[136:139], v[192:195], v[20:23]
	v_mfma_f32_16x16x32_bf16 v[56:59], v[148:151], v[164:167], v[56:59]
	v_mfma_f32_16x16x32_bf16 v[56:59], v[152:155], v[168:171], v[56:59]
	v_mfma_f32_16x16x32_bf16 v[40:43], v[148:151], v[172:175], v[40:43]
	v_mfma_f32_16x16x32_bf16 v[40:43], v[152:155], v[176:179], v[40:43]
	v_mfma_f32_16x16x32_bf16 v[24:27], v[148:151], v[180:183], v[24:27]
	v_mfma_f32_16x16x32_bf16 v[24:27], v[152:155], v[184:187], v[24:27]
	v_mfma_f32_16x16x32_bf16 v[8:11], v[148:151], v[188:191], v[8:11]
	v_mfma_f32_16x16x32_bf16 v[8:11], v[152:155], v[192:195], v[8:11]
	v_mfma_f32_16x16x32_bf16 v[60:63], v[140:143], v[164:167], v[60:63]
	v_mfma_f32_16x16x32_bf16 v[60:63], v[144:147], v[168:171], v[60:63]
	v_mfma_f32_16x16x32_bf16 v[44:47], v[140:143], v[172:175], v[44:47]
	v_mfma_f32_16x16x32_bf16 v[44:47], v[144:147], v[176:179], v[44:47]
	v_mfma_f32_16x16x32_bf16 v[28:31], v[140:143], v[180:183], v[28:31]
	v_mfma_f32_16x16x32_bf16 v[28:31], v[144:147], v[184:187], v[28:31]
	v_mfma_f32_16x16x32_bf16 v[12:15], v[140:143], v[188:191], v[12:15]
	v_mfma_f32_16x16x32_bf16 v[12:15], v[144:147], v[192:195], v[12:15]
	v_mfma_f32_16x16x32_bf16 v[48:51], v[156:159], v[164:167], v[48:51]
	v_mfma_f32_16x16x32_bf16 v[48:51], v[160:163], v[168:171], v[48:51]
	v_mfma_f32_16x16x32_bf16 v[32:35], v[156:159], v[172:175], v[32:35]
	v_mfma_f32_16x16x32_bf16 v[32:35], v[160:163], v[176:179], v[32:35]
	v_mfma_f32_16x16x32_bf16 v[16:19], v[156:159], v[180:183], v[16:19]
	v_mfma_f32_16x16x32_bf16 v[16:19], v[160:163], v[184:187], v[16:19]
	v_mfma_f32_16x16x32_bf16 v[4:7], v[156:159], v[188:191], v[4:7]
	v_mfma_f32_16x16x32_bf16 v[4:7], v[160:163], v[192:195], v[4:7]
	s_setprio 0
	s_barrier
	s_add_i32 s43, s43, 2
	s_add_u32 s38, s38, 0x100
	s_addc_u32 s39, s39, 0
	s_cmpk_gt_u32 s43, 0x55
	s_mov_b64 s[14:15], s[16:17]
	s_cbranch_scc0 .LBB0_347
	s_and_b64 vcc, exec, s[6:7]
	s_cbranch_vccz .LBB0_350
	s_barrier

.LBB0_429:
	s_ashr_i32 s23, s22, 31
	s_lshl_b64 s[24:25], s[22:23], 20
	s_add_u32 s24, s51, s24
	s_addc_u32 s25, s52, s25
	s_and_b64 s[26:27], s[40:41], exec
	s_cselect_b32 s5, s25, s29
	s_cselect_b32 s23, s24, s28
	s_ashr_i32 s21, s20, 31
	s_lshl_b64 s[26:27], s[20:21], 20
	s_add_u32 s26, s12, s26
	s_addc_u32 s27, s13, s27
	s_and_b64 s[42:43], s[40:41], exec
	s_cselect_b32 s21, s27, s31
	s_cselect_b32 s62, s26, s30
	s_add_u32 s28, s28, 0x80080
	s_addc_u32 s29, s29, 0
	s_add_u32 s63, s30, 0x100
	s_addc_u32 s68, s31, 0
	s_mov_b32 s69, -2
	s_sleep 1
	s_add_u32 s30, s28, 0xfff80080
	s_addc_u32 s31, s29, -1
	s_add_i32 s70, 0, 0x10000
	s_cmp_eq_u32 s69, 28
	s_cselect_b32 s43, s5, s31
	s_cselect_b32 s42, s23, s30
	s_cselect_b32 s31, s21, s68
	s_cselect_b32 s30, s62, s63
	s_add_i32 s73, 0, 0x14000
	s_waitcnt lgkmcnt(0)
	v_lshl_add_u64 v[160:161], s[28:29], 0, v[144:145]
	s_add_i32 m0, s15, 0xc000
	s_nop 0
	global_load_lds_dwordx4 v[160:161], off
	v_lshl_add_u64 v[160:161], s[28:29], 0, v[146:147]
	s_add_i32 m0, s15, 0xe000
	s_nop 0
	global_load_lds_dwordx4 v[160:161], off
	v_add_u32_e32 v152, s70, v163
	v_add_u32_e32 v160, s73, v163
	ds_read_b128 v[132:135], v152
	ds_read_b128 v[136:139], v152 offset:1024
	ds_read_b128 v[148:151], v152 offset:2048
	ds_read_b128 v[152:155], v152 offset:3072
	ds_read_b128 v[156:159], v160
	ds_read_b128 v[170:173], v160 offset:1024
	ds_read_b128 v[174:177], v160 offset:2048
	ds_read_b128 v[178:181], v160 offset:3072
	ds_read_b128 v[182:185], v167
	ds_read_b128 v[186:189], v167 offset:1024
	ds_read_b128 v[190:193], v167 offset:2048
	ds_read_b128 v[194:197], v167 offset:3072
	ds_read_b128 v[198:201], v167 offset:4096
	ds_read_b128 v[208:211], v167 offset:5120
	ds_read_b128 v[212:215], v167 offset:6144
	ds_read_b128 v[216:219], v167 offset:7168
	s_waitcnt vmcnt(8)
	s_waitcnt lgkmcnt(0)
	s_barrier
	s_setprio 1
	s_waitcnt lgkmcnt(0)
	v_mfma_f32_16x16x32_bf16 v[128:131], v[132:135], v[182:185], 0
	v_mfma_f32_16x16x32_bf16 v[128:131], v[136:139], v[186:189], v[128:131]
	v_mfma_f32_16x16x32_bf16 v[120:123], v[132:135], v[190:193], 0
	v_mfma_f32_16x16x32_bf16 v[120:123], v[136:139], v[194:197], v[120:123]
	v_mfma_f32_16x16x32_bf16 v[104:107], v[132:135], v[198:201], 0
	v_mfma_f32_16x16x32_bf16 v[104:107], v[136:139], v[208:211], v[104:107]
	v_mfma_f32_16x16x32_bf16 v[88:91], v[132:135], v[212:215], 0
	v_mfma_f32_16x16x32_bf16 v[88:91], v[136:139], v[216:219], v[88:91]
	v_mfma_f32_16x16x32_bf16 v[116:119], v[156:159], v[182:185], 0
	v_mfma_f32_16x16x32_bf16 v[116:119], v[170:173], v[186:189], v[116:119]
	v_mfma_f32_16x16x32_bf16 v[100:103], v[156:159], v[190:193], 0
	v_mfma_f32_16x16x32_bf16 v[100:103], v[170:173], v[194:197], v[100:103]
	v_mfma_f32_16x16x32_bf16 v[84:87], v[156:159], v[198:201], 0
	v_mfma_f32_16x16x32_bf16 v[84:87], v[170:173], v[208:211], v[84:87]
	v_mfma_f32_16x16x32_bf16 v[72:75], v[156:159], v[212:215], 0
	v_mfma_f32_16x16x32_bf16 v[72:75], v[170:173], v[216:219], v[72:75]
	v_mfma_f32_16x16x32_bf16 v[124:127], v[148:151], v[182:185], 0
	v_mfma_f32_16x16x32_bf16 v[124:127], v[152:155], v[186:189], v[124:127]
	v_mfma_f32_16x16x32_bf16 v[112:115], v[148:151], v[190:193], 0
	v_mfma_f32_16x16x32_bf16 v[112:115], v[152:155], v[194:197], v[112:115]
	v_mfma_f32_16x16x32_bf16 v[96:99], v[148:151], v[198:201], 0
	v_mfma_f32_16x16x32_bf16 v[96:99], v[152:155], v[208:211], v[96:99]
	v_mfma_f32_16x16x32_bf16 v[80:83], v[148:151], v[212:215], 0
	v_mfma_f32_16x16x32_bf16 v[80:83], v[152:155], v[216:219], v[80:83]
	v_mfma_f32_16x16x32_bf16 v[108:111], v[174:177], v[182:185], 0
	v_mfma_f32_16x16x32_bf16 v[108:111], v[178:181], v[186:189], v[108:111]
	v_mfma_f32_16x16x32_bf16 v[92:95], v[174:177], v[190:193], 0
	v_mfma_f32_16x16x32_bf16 v[92:95], v[178:181], v[194:197], v[92:95]
	v_mfma_f32_16x16x32_bf16 v[76:79], v[174:177], v[198:201], 0
	v_mfma_f32_16x16x32_bf16 v[76:79], v[178:181], v[208:211], v[76:79]
	v_mfma_f32_16x16x32_bf16 v[68:71], v[174:177], v[212:215], 0
	v_mfma_f32_16x16x32_bf16 v[68:71], v[178:181], v[216:219], v[68:71]
	s_setprio 0
	s_barrier
	s_sleep 2
	s_add_i32 s70, s70, s0
	v_lshl_add_u64 v[160:161], s[30:31], 0, v[2:3]
	s_mov_b32 m0, s70
	ds_read_b128 v[182:185], v167 offset:16384
	ds_read_b128 v[186:189], v167 offset:17408
	ds_read_b128 v[190:193], v167 offset:18432
	ds_read_b128 v[194:197], v167 offset:19456
	ds_read_b128 v[198:201], v167 offset:20480
	ds_read_b128 v[208:211], v167 offset:21504
	ds_read_b128 v[212:215], v167 offset:22528
	ds_read_b128 v[216:219], v167 offset:23552
	global_load_lds_dwordx4 v[160:161], off
	s_add_i32 m0, s70, 0x2000
	s_add_u32 s70, s30, 0x80000
	v_lshl_add_u64 v[202:203], s[30:31], 0, v[142:143]
	s_addc_u32 s71, s31, 0
	s_add_i32 s73, s73, s0
	global_load_lds_dwordx4 v[202:203], off
	v_lshl_add_u64 v[204:205], s[70:71], 0, v[2:3]
	s_mov_b32 m0, s73
	v_lshl_add_u64 v[206:207], s[42:43], 0, v[140:141]
	global_load_lds_dwordx4 v[204:205], off
	v_lshl_add_u64 v[204:205], s[70:71], 0, v[142:143]
	s_add_i32 m0, s73, 0x2000
	s_nop 0
	global_load_lds_dwordx4 v[204:205], off
	v_lshl_add_u64 v[204:205], s[42:43], 0, v[0:1]
	s_mov_b32 m0, s15
	s_nop 0
	global_load_lds_dwordx4 v[204:205], off
	s_mov_b32 m0, s53
	s_nop 0
	global_load_lds_dwordx4 v[206:207], off
	s_waitcnt vmcnt(8)
	s_waitcnt lgkmcnt(0)
	s_barrier
	s_setprio 1
	s_waitcnt lgkmcnt(0)
	v_mfma_f32_16x16x32_bf16 v[64:67], v[132:135], v[182:185], 0
	v_mfma_f32_16x16x32_bf16 v[64:67], v[136:139], v[186:189], v[64:67]
	v_mfma_f32_16x16x32_bf16 v[56:59], v[132:135], v[190:193], 0
	v_mfma_f32_16x16x32_bf16 v[56:59], v[136:139], v[194:197], v[56:59]
	v_mfma_f32_16x16x32_bf16 v[40:43], v[132:135], v[198:201], 0
	v_mfma_f32_16x16x32_bf16 v[40:43], v[136:139], v[208:211], v[40:43]
	v_mfma_f32_16x16x32_bf16 v[24:27], v[132:135], v[212:215], 0
	v_mfma_f32_16x16x32_bf16 v[24:27], v[136:139], v[216:219], v[24:27]
	v_mfma_f32_16x16x32_bf16 v[52:55], v[156:159], v[182:185], 0
	v_mfma_f32_16x16x32_bf16 v[52:55], v[170:173], v[186:189], v[52:55]
	v_mfma_f32_16x16x32_bf16 v[36:39], v[156:159], v[190:193], 0
	v_mfma_f32_16x16x32_bf16 v[36:39], v[170:173], v[194:197], v[36:39]
	v_mfma_f32_16x16x32_bf16 v[20:23], v[156:159], v[198:201], 0
	v_mfma_f32_16x16x32_bf16 v[20:23], v[170:173], v[208:211], v[20:23]
	v_mfma_f32_16x16x32_bf16 v[8:11], v[156:159], v[212:215], 0
	v_mfma_f32_16x16x32_bf16 v[8:11], v[170:173], v[216:219], v[8:11]
	v_mfma_f32_16x16x32_bf16 v[60:63], v[148:151], v[182:185], 0
	v_mfma_f32_16x16x32_bf16 v[60:63], v[152:155], v[186:189], v[60:63]
	v_mfma_f32_16x16x32_bf16 v[48:51], v[148:151], v[190:193], 0
	v_mfma_f32_16x16x32_bf16 v[48:51], v[152:155], v[194:197], v[48:51]
	v_mfma_f32_16x16x32_bf16 v[32:35], v[148:151], v[198:201], 0
	v_mfma_f32_16x16x32_bf16 v[32:35], v[152:155], v[208:211], v[32:35]
	v_mfma_f32_16x16x32_bf16 v[16:19], v[148:151], v[212:215], 0
	v_mfma_f32_16x16x32_bf16 v[16:19], v[152:155], v[216:219], v[16:19]
	v_mfma_f32_16x16x32_bf16 v[44:47], v[174:177], v[182:185], 0
	v_mfma_f32_16x16x32_bf16 v[44:47], v[178:181], v[186:189], v[44:47]
	v_mfma_f32_16x16x32_bf16 v[28:31], v[174:177], v[190:193], 0
	v_mfma_f32_16x16x32_bf16 v[28:31], v[178:181], v[194:197], v[28:31]
	v_mfma_f32_16x16x32_bf16 v[12:15], v[174:177], v[198:201], 0
	v_mfma_f32_16x16x32_bf16 v[12:15], v[178:181], v[208:211], v[12:15]
	v_mfma_f32_16x16x32_bf16 v[4:7], v[174:177], v[212:215], 0
	v_mfma_f32_16x16x32_bf16 v[4:7], v[178:181], v[216:219], v[4:7]
	s_setprio 0
	s_barrier
	s_sleep 1
	s_add_i32 s70, 0, 0x18000
	s_add_i32 s71, 0, 0x1c000
	s_add_u32 s42, s42, 0x80000
	s_addc_u32 s43, s43, 0
	s_mov_b32 m0, s54
	v_lshl_add_u64 v[220:221], s[42:43], 0, v[0:1]
	global_load_lds_dwordx4 v[220:221], off
	v_lshl_add_u64 v[220:221], s[42:43], 0, v[140:141]
	s_mov_b32 m0, s55
	s_nop 0
	global_load_lds_dwordx4 v[220:221], off
	v_add_u32_e32 v152, s70, v163
	v_add_u32_e32 v178, s71, v163
	ds_read_b128 v[132:135], v152
	ds_read_b128 v[136:139], v152 offset:1024
	ds_read_b128 v[148:151], v152 offset:2048
	ds_read_b128 v[152:155], v152 offset:3072
	ds_read_b128 v[156:159], v178
	ds_read_b128 v[170:173], v178 offset:1024
	ds_read_b128 v[174:177], v178 offset:2048
	ds_read_b128 v[178:181], v178 offset:3072
	ds_read_b128 v[182:185], v167 offset:32768
	ds_read_b128 v[186:189], v167 offset:33792
	ds_read_b128 v[190:193], v167 offset:34816
	ds_read_b128 v[194:197], v167 offset:35840
	ds_read_b128 v[198:201], v167 offset:36864
	ds_read_b128 v[208:211], v167 offset:37888
	ds_read_b128 v[212:215], v167 offset:38912
	ds_read_b128 v[216:219], v167 offset:39936
	s_waitcnt vmcnt(8)
	s_waitcnt lgkmcnt(0)
	s_barrier
	s_setprio 1
	s_waitcnt lgkmcnt(0)
	v_mfma_f32_16x16x32_bf16 v[128:131], v[132:135], v[182:185], v[128:131]
	v_mfma_f32_16x16x32_bf16 v[128:131], v[136:139], v[186:189], v[128:131]
	v_mfma_f32_16x16x32_bf16 v[120:123], v[132:135], v[190:193], v[120:123]
	v_mfma_f32_16x16x32_bf16 v[120:123], v[136:139], v[194:197], v[120:123]
	v_mfma_f32_16x16x32_bf16 v[104:107], v[132:135], v[198:201], v[104:107]
	v_mfma_f32_16x16x32_bf16 v[104:107], v[136:139], v[208:211], v[104:107]
	v_mfma_f32_16x16x32_bf16 v[88:91], v[132:135], v[212:215], v[88:91]
	v_mfma_f32_16x16x32_bf16 v[88:91], v[136:139], v[216:219], v[88:91]
	v_mfma_f32_16x16x32_bf16 v[116:119], v[156:159], v[182:185], v[116:119]
	v_mfma_f32_16x16x32_bf16 v[116:119], v[170:173], v[186:189], v[116:119]
	v_mfma_f32_16x16x32_bf16 v[100:103], v[156:159], v[190:193], v[100:103]
	v_mfma_f32_16x16x32_bf16 v[100:103], v[170:173], v[194:197], v[100:103]
	v_mfma_f32_16x16x32_bf16 v[84:87], v[156:159], v[198:201], v[84:87]
	v_mfma_f32_16x16x32_bf16 v[84:87], v[170:173], v[208:211], v[84:87]
	v_mfma_f32_16x16x32_bf16 v[72:75], v[156:159], v[212:215], v[72:75]
	v_mfma_f32_16x16x32_bf16 v[72:75], v[170:173], v[216:219], v[72:75]
	v_mfma_f32_16x16x32_bf16 v[124:127], v[148:151], v[182:185], v[124:127]
	v_mfma_f32_16x16x32_bf16 v[124:127], v[152:155], v[186:189], v[124:127]
	v_mfma_f32_16x16x32_bf16 v[112:115], v[148:151], v[190:193], v[112:115]
	v_mfma_f32_16x16x32_bf16 v[112:115], v[152:155], v[194:197], v[112:115]
	v_mfma_f32_16x16x32_bf16 v[96:99], v[148:151], v[198:201], v[96:99]
	v_mfma_f32_16x16x32_bf16 v[96:99], v[152:155], v[208:211], v[96:99]
	v_mfma_f32_16x16x32_bf16 v[80:83], v[148:151], v[212:215], v[80:83]
	v_mfma_f32_16x16x32_bf16 v[80:83], v[152:155], v[216:219], v[80:83]
	v_mfma_f32_16x16x32_bf16 v[108:111], v[174:177], v[182:185], v[108:111]
	v_mfma_f32_16x16x32_bf16 v[108:111], v[178:181], v[186:189], v[108:111]
	v_mfma_f32_16x16x32_bf16 v[92:95], v[174:177], v[190:193], v[92:95]
	v_mfma_f32_16x16x32_bf16 v[92:95], v[178:181], v[194:197], v[92:95]
	v_mfma_f32_16x16x32_bf16 v[76:79], v[174:177], v[198:201], v[76:79]
	v_mfma_f32_16x16x32_bf16 v[76:79], v[178:181], v[208:211], v[76:79]
	v_mfma_f32_16x16x32_bf16 v[68:71], v[174:177], v[212:215], v[68:71]
	v_mfma_f32_16x16x32_bf16 v[68:71], v[178:181], v[216:219], v[68:71]
	s_setprio 0
	s_barrier
	s_sleep 2
	s_add_i32 s42, s70, s0
	v_lshl_add_u64 v[160:161], v[160:161], 0, s[66:67]
	s_mov_b32 m0, s42
	ds_read_b128 v[182:185], v167 offset:49152
	ds_read_b128 v[186:189], v167 offset:50176
	ds_read_b128 v[190:193], v167 offset:51200
	ds_read_b128 v[194:197], v167 offset:52224
	ds_read_b128 v[198:201], v167 offset:53248
	ds_read_b128 v[208:211], v167 offset:54272
	ds_read_b128 v[212:215], v167 offset:55296
	ds_read_b128 v[216:219], v167 offset:56320
	global_load_lds_dwordx4 v[160:161], off
	s_add_i32 m0, s42, 0x2000
	s_add_u32 s30, s30, 0x80080
	v_lshl_add_u64 v[160:161], v[202:203], 0, s[66:67]
	s_addc_u32 s31, s31, 0
	s_add_i32 s42, s71, s0
	global_load_lds_dwordx4 v[160:161], off
	v_lshl_add_u64 v[160:161], s[30:31], 0, v[2:3]
	s_mov_b32 m0, s42
	s_nop 0
	global_load_lds_dwordx4 v[160:161], off
	v_lshl_add_u64 v[160:161], s[30:31], 0, v[142:143]
	s_add_i32 m0, s42, 0x2000
	s_nop 0
	global_load_lds_dwordx4 v[160:161], off
	v_lshl_add_u64 v[160:161], v[204:205], 0, s[66:67]
	s_mov_b32 m0, s60
	s_nop 0
	global_load_lds_dwordx4 v[160:161], off
	v_lshl_add_u64 v[160:161], v[206:207], 0, s[66:67]
	s_mov_b32 m0, s64
	s_nop 0
	global_load_lds_dwordx4 v[160:161], off
	s_waitcnt vmcnt(8)
	s_waitcnt lgkmcnt(0)
	s_barrier
	s_setprio 1
	s_waitcnt lgkmcnt(0)
	v_mfma_f32_16x16x32_bf16 v[64:67], v[132:135], v[182:185], v[64:67]
	v_mfma_f32_16x16x32_bf16 v[64:67], v[136:139], v[186:189], v[64:67]
	v_mfma_f32_16x16x32_bf16 v[56:59], v[132:135], v[190:193], v[56:59]
	v_mfma_f32_16x16x32_bf16 v[56:59], v[136:139], v[194:197], v[56:59]
	v_mfma_f32_16x16x32_bf16 v[40:43], v[132:135], v[198:201], v[40:43]
	v_mfma_f32_16x16x32_bf16 v[40:43], v[136:139], v[208:211], v[40:43]
	v_mfma_f32_16x16x32_bf16 v[24:27], v[132:135], v[212:215], v[24:27]
	v_mfma_f32_16x16x32_bf16 v[24:27], v[136:139], v[216:219], v[24:27]
	v_mfma_f32_16x16x32_bf16 v[52:55], v[156:159], v[182:185], v[52:55]
	v_mfma_f32_16x16x32_bf16 v[52:55], v[170:173], v[186:189], v[52:55]
	v_mfma_f32_16x16x32_bf16 v[36:39], v[156:159], v[190:193], v[36:39]
	v_mfma_f32_16x16x32_bf16 v[36:39], v[170:173], v[194:197], v[36:39]
	v_mfma_f32_16x16x32_bf16 v[20:23], v[156:159], v[198:201], v[20:23]
	v_mfma_f32_16x16x32_bf16 v[20:23], v[170:173], v[208:211], v[20:23]
	v_mfma_f32_16x16x32_bf16 v[8:11], v[156:159], v[212:215], v[8:11]
	v_mfma_f32_16x16x32_bf16 v[8:11], v[170:173], v[216:219], v[8:11]
	v_mfma_f32_16x16x32_bf16 v[60:63], v[148:151], v[182:185], v[60:63]
	v_mfma_f32_16x16x32_bf16 v[60:63], v[152:155], v[186:189], v[60:63]
	v_mfma_f32_16x16x32_bf16 v[48:51], v[148:151], v[190:193], v[48:51]
	v_mfma_f32_16x16x32_bf16 v[48:51], v[152:155], v[194:197], v[48:51]
	v_mfma_f32_16x16x32_bf16 v[32:35], v[148:151], v[198:201], v[32:35]
	v_mfma_f32_16x16x32_bf16 v[32:35], v[152:155], v[208:211], v[32:35]
	v_mfma_f32_16x16x32_bf16 v[16:19], v[148:151], v[212:215], v[16:19]
	v_mfma_f32_16x16x32_bf16 v[16:19], v[152:155], v[216:219], v[16:19]
	v_mfma_f32_16x16x32_bf16 v[44:47], v[174:177], v[182:185], v[44:47]
	v_mfma_f32_16x16x32_bf16 v[44:47], v[178:181], v[186:189], v[44:47]
	v_mfma_f32_16x16x32_bf16 v[28:31], v[174:177], v[190:193], v[28:31]
	v_mfma_f32_16x16x32_bf16 v[28:31], v[178:181], v[194:197], v[28:31]
	v_mfma_f32_16x16x32_bf16 v[12:15], v[174:177], v[198:201], v[12:15]
	v_mfma_f32_16x16x32_bf16 v[12:15], v[178:181], v[208:211], v[12:15]
	v_mfma_f32_16x16x32_bf16 v[4:7], v[174:177], v[212:215], v[4:7]
	v_mfma_f32_16x16x32_bf16 v[4:7], v[178:181], v[216:219], v[4:7]
	s_setprio 0
	s_barrier
	s_add_i32 s69, s69, 2
	s_add_u32 s28, s28, 0x100
	s_addc_u32 s29, s29, 0
	s_add_u32 s63, s63, 0x100
	s_addc_u32 s68, s68, 0
	s_cmp_gt_u32 s69, 29
.LBB0_430:
	s_sleep 1
	s_add_u32 s30, s28, 0xfff80080
	s_addc_u32 s31, s29, -1
	s_add_i32 s70, 0, 0x10000
	s_cmp_eq_u32 s69, 28
	s_cselect_b32 s43, s5, s31
	s_cselect_b32 s42, s23, s30
	s_cselect_b32 s31, s21, s68
	s_cselect_b32 s30, s62, s63
	s_add_i32 s73, 0, 0x14000
	s_waitcnt lgkmcnt(0)
	v_lshl_add_u64 v[160:161], s[28:29], 0, v[144:145]
	s_add_i32 m0, s15, 0xc000
	s_nop 0
	global_load_lds_dwordx4 v[160:161], off
	v_lshl_add_u64 v[160:161], s[28:29], 0, v[146:147]
	s_add_i32 m0, s15, 0xe000
	s_nop 0
	global_load_lds_dwordx4 v[160:161], off
	v_add_u32_e32 v152, s70, v163
	v_add_u32_e32 v160, s73, v163
	ds_read_b128 v[132:135], v152
	ds_read_b128 v[136:139], v152 offset:1024
	ds_read_b128 v[148:151], v152 offset:2048
	ds_read_b128 v[152:155], v152 offset:3072
	ds_read_b128 v[156:159], v160
	ds_read_b128 v[170:173], v160 offset:1024
	ds_read_b128 v[174:177], v160 offset:2048
	ds_read_b128 v[178:181], v160 offset:3072
	ds_read_b128 v[182:185], v167
	ds_read_b128 v[186:189], v167 offset:1024
	ds_read_b128 v[190:193], v167 offset:2048
	ds_read_b128 v[194:197], v167 offset:3072
	ds_read_b128 v[198:201], v167 offset:4096
	ds_read_b128 v[208:211], v167 offset:5120
	ds_read_b128 v[212:215], v167 offset:6144
	ds_read_b128 v[216:219], v167 offset:7168
	s_waitcnt vmcnt(8)
	s_waitcnt lgkmcnt(0)
	s_barrier
	s_setprio 1
	s_waitcnt lgkmcnt(0)
	v_mfma_f32_16x16x32_bf16 v[128:131], v[132:135], v[182:185], v[128:131]
	v_mfma_f32_16x16x32_bf16 v[128:131], v[136:139], v[186:189], v[128:131]
	v_mfma_f32_16x16x32_bf16 v[120:123], v[132:135], v[190:193], v[120:123]
	v_mfma_f32_16x16x32_bf16 v[120:123], v[136:139], v[194:197], v[120:123]
	v_mfma_f32_16x16x32_bf16 v[104:107], v[132:135], v[198:201], v[104:107]
	v_mfma_f32_16x16x32_bf16 v[104:107], v[136:139], v[208:211], v[104:107]
	v_mfma_f32_16x16x32_bf16 v[88:91], v[132:135], v[212:215], v[88:91]
	v_mfma_f32_16x16x32_bf16 v[88:91], v[136:139], v[216:219], v[88:91]
	v_mfma_f32_16x16x32_bf16 v[116:119], v[156:159], v[182:185], v[116:119]
	v_mfma_f32_16x16x32_bf16 v[116:119], v[170:173], v[186:189], v[116:119]
	v_mfma_f32_16x16x32_bf16 v[100:103], v[156:159], v[190:193], v[100:103]
	v_mfma_f32_16x16x32_bf16 v[100:103], v[170:173], v[194:197], v[100:103]
	v_mfma_f32_16x16x32_bf16 v[84:87], v[156:159], v[198:201], v[84:87]
	v_mfma_f32_16x16x32_bf16 v[84:87], v[170:173], v[208:211], v[84:87]
	v_mfma_f32_16x16x32_bf16 v[72:75], v[156:159], v[212:215], v[72:75]
	v_mfma_f32_16x16x32_bf16 v[72:75], v[170:173], v[216:219], v[72:75]
	v_mfma_f32_16x16x32_bf16 v[124:127], v[148:151], v[182:185], v[124:127]
	v_mfma_f32_16x16x32_bf16 v[124:127], v[152:155], v[186:189], v[124:127]
	v_mfma_f32_16x16x32_bf16 v[112:115], v[148:151], v[190:193], v[112:115]
	v_mfma_f32_16x16x32_bf16 v[112:115], v[152:155], v[194:197], v[112:115]
	v_mfma_f32_16x16x32_bf16 v[96:99], v[148:151], v[198:201], v[96:99]
	v_mfma_f32_16x16x32_bf16 v[96:99], v[152:155], v[208:211], v[96:99]
	v_mfma_f32_16x16x32_bf16 v[80:83], v[148:151], v[212:215], v[80:83]
	v_mfma_f32_16x16x32_bf16 v[80:83], v[152:155], v[216:219], v[80:83]
	v_mfma_f32_16x16x32_bf16 v[108:111], v[174:177], v[182:185], v[108:111]
	v_mfma_f32_16x16x32_bf16 v[108:111], v[178:181], v[186:189], v[108:111]
	v_mfma_f32_16x16x32_bf16 v[92:95], v[174:177], v[190:193], v[92:95]
	v_mfma_f32_16x16x32_bf16 v[92:95], v[178:181], v[194:197], v[92:95]
	v_mfma_f32_16x16x32_bf16 v[76:79], v[174:177], v[198:201], v[76:79]
	v_mfma_f32_16x16x32_bf16 v[76:79], v[178:181], v[208:211], v[76:79]
	v_mfma_f32_16x16x32_bf16 v[68:71], v[174:177], v[212:215], v[68:71]
	v_mfma_f32_16x16x32_bf16 v[68:71], v[178:181], v[216:219], v[68:71]
	s_setprio 0
	s_barrier
	s_sleep 2
	s_add_i32 s70, s70, s0
	v_lshl_add_u64 v[160:161], s[30:31], 0, v[2:3]
	s_mov_b32 m0, s70
	ds_read_b128 v[182:185], v167 offset:16384
	ds_read_b128 v[186:189], v167 offset:17408
	ds_read_b128 v[190:193], v167 offset:18432
	ds_read_b128 v[194:197], v167 offset:19456
	ds_read_b128 v[198:201], v167 offset:20480
	ds_read_b128 v[208:211], v167 offset:21504
	ds_read_b128 v[212:215], v167 offset:22528
	ds_read_b128 v[216:219], v167 offset:23552
	global_load_lds_dwordx4 v[160:161], off
	s_add_i32 m0, s70, 0x2000
	s_add_u32 s70, s30, 0x80000
	v_lshl_add_u64 v[202:203], s[30:31], 0, v[142:143]
	s_addc_u32 s71, s31, 0
	s_add_i32 s73, s73, s0
	global_load_lds_dwordx4 v[202:203], off
	v_lshl_add_u64 v[204:205], s[70:71], 0, v[2:3]
	s_mov_b32 m0, s73
	v_lshl_add_u64 v[206:207], s[42:43], 0, v[140:141]
	global_load_lds_dwordx4 v[204:205], off
	v_lshl_add_u64 v[204:205], s[70:71], 0, v[142:143]
	s_add_i32 m0, s73, 0x2000
	s_nop 0
	global_load_lds_dwordx4 v[204:205], off
	v_lshl_add_u64 v[204:205], s[42:43], 0, v[0:1]
	s_mov_b32 m0, s15
	s_nop 0
	global_load_lds_dwordx4 v[204:205], off
	s_mov_b32 m0, s53
	s_nop 0
	global_load_lds_dwordx4 v[206:207], off
	s_waitcnt vmcnt(8)
	s_waitcnt lgkmcnt(0)
	s_barrier
	s_setprio 1
	s_waitcnt lgkmcnt(0)
	v_mfma_f32_16x16x32_bf16 v[64:67], v[132:135], v[182:185], v[64:67]
	v_mfma_f32_16x16x32_bf16 v[64:67], v[136:139], v[186:189], v[64:67]
	v_mfma_f32_16x16x32_bf16 v[56:59], v[132:135], v[190:193], v[56:59]
	v_mfma_f32_16x16x32_bf16 v[56:59], v[136:139], v[194:197], v[56:59]
	v_mfma_f32_16x16x32_bf16 v[40:43], v[132:135], v[198:201], v[40:43]
	v_mfma_f32_16x16x32_bf16 v[40:43], v[136:139], v[208:211], v[40:43]
	v_mfma_f32_16x16x32_bf16 v[24:27], v[132:135], v[212:215], v[24:27]
	v_mfma_f32_16x16x32_bf16 v[24:27], v[136:139], v[216:219], v[24:27]
	v_mfma_f32_16x16x32_bf16 v[52:55], v[156:159], v[182:185], v[52:55]
	v_mfma_f32_16x16x32_bf16 v[52:55], v[170:173], v[186:189], v[52:55]
	v_mfma_f32_16x16x32_bf16 v[36:39], v[156:159], v[190:193], v[36:39]
	v_mfma_f32_16x16x32_bf16 v[36:39], v[170:173], v[194:197], v[36:39]
	v_mfma_f32_16x16x32_bf16 v[20:23], v[156:159], v[198:201], v[20:23]
	v_mfma_f32_16x16x32_bf16 v[20:23], v[170:173], v[208:211], v[20:23]
	v_mfma_f32_16x16x32_bf16 v[8:11], v[156:159], v[212:215], v[8:11]
	v_mfma_f32_16x16x32_bf16 v[8:11], v[170:173], v[216:219], v[8:11]
	v_mfma_f32_16x16x32_bf16 v[60:63], v[148:151], v[182:185], v[60:63]
	v_mfma_f32_16x16x32_bf16 v[60:63], v[152:155], v[186:189], v[60:63]
	v_mfma_f32_16x16x32_bf16 v[48:51], v[148:151], v[190:193], v[48:51]
	v_mfma_f32_16x16x32_bf16 v[48:51], v[152:155], v[194:197], v[48:51]
	v_mfma_f32_16x16x32_bf16 v[32:35], v[148:151], v[198:201], v[32:35]
	v_mfma_f32_16x16x32_bf16 v[32:35], v[152:155], v[208:211], v[32:35]
	v_mfma_f32_16x16x32_bf16 v[16:19], v[148:151], v[212:215], v[16:19]
	v_mfma_f32_16x16x32_bf16 v[16:19], v[152:155], v[216:219], v[16:19]
	v_mfma_f32_16x16x32_bf16 v[44:47], v[174:177], v[182:185], v[44:47]
	v_mfma_f32_16x16x32_bf16 v[44:47], v[178:181], v[186:189], v[44:47]
	v_mfma_f32_16x16x32_bf16 v[28:31], v[174:177], v[190:193], v[28:31]
	v_mfma_f32_16x16x32_bf16 v[28:31], v[178:181], v[194:197], v[28:31]
	v_mfma_f32_16x16x32_bf16 v[12:15], v[174:177], v[198:201], v[12:15]
	v_mfma_f32_16x16x32_bf16 v[12:15], v[178:181], v[208:211], v[12:15]
	v_mfma_f32_16x16x32_bf16 v[4:7], v[174:177], v[212:215], v[4:7]
	v_mfma_f32_16x16x32_bf16 v[4:7], v[178:181], v[216:219], v[4:7]
	s_setprio 0
	s_barrier
	s_sleep 1
	s_add_i32 s70, 0, 0x18000
	s_add_i32 s71, 0, 0x1c000
	s_add_u32 s42, s42, 0x80000
	s_addc_u32 s43, s43, 0
	s_mov_b32 m0, s54
	v_lshl_add_u64 v[220:221], s[42:43], 0, v[0:1]
	global_load_lds_dwordx4 v[220:221], off
	v_lshl_add_u64 v[220:221], s[42:43], 0, v[140:141]
	s_mov_b32 m0, s55
	s_nop 0
	global_load_lds_dwordx4 v[220:221], off
	v_add_u32_e32 v152, s70, v163
	v_add_u32_e32 v178, s71, v163
	ds_read_b128 v[132:135], v152
	ds_read_b128 v[136:139], v152 offset:1024
	ds_read_b128 v[148:151], v152 offset:2048
	ds_read_b128 v[152:155], v152 offset:3072
	ds_read_b128 v[156:159], v178
	ds_read_b128 v[170:173], v178 offset:1024
	ds_read_b128 v[174:177], v178 offset:2048
	ds_read_b128 v[178:181], v178 offset:3072
	ds_read_b128 v[182:185], v167 offset:32768
	ds_read_b128 v[186:189], v167 offset:33792
	ds_read_b128 v[190:193], v167 offset:34816
	ds_read_b128 v[194:197], v167 offset:35840
	ds_read_b128 v[198:201], v167 offset:36864
	ds_read_b128 v[208:211], v167 offset:37888
	ds_read_b128 v[212:215], v167 offset:38912
	ds_read_b128 v[216:219], v167 offset:39936
	s_waitcnt vmcnt(8)
	s_waitcnt lgkmcnt(0)
	s_barrier
	s_setprio 1
	s_waitcnt lgkmcnt(0)
	v_mfma_f32_16x16x32_bf16 v[128:131], v[132:135], v[182:185], v[128:131]
	v_mfma_f32_16x16x32_bf16 v[128:131], v[136:139], v[186:189], v[128:131]
	v_mfma_f32_16x16x32_bf16 v[120:123], v[132:135], v[190:193], v[120:123]
	v_mfma_f32_16x16x32_bf16 v[120:123], v[136:139], v[194:197], v[120:123]
	v_mfma_f32_16x16x32_bf16 v[104:107], v[132:135], v[198:201], v[104:107]
	v_mfma_f32_16x16x32_bf16 v[104:107], v[136:139], v[208:211], v[104:107]
	v_mfma_f32_16x16x32_bf16 v[88:91], v[132:135], v[212:215], v[88:91]
	v_mfma_f32_16x16x32_bf16 v[88:91], v[136:139], v[216:219], v[88:91]
	v_mfma_f32_16x16x32_bf16 v[116:119], v[156:159], v[182:185], v[116:119]
	v_mfma_f32_16x16x32_bf16 v[116:119], v[170:173], v[186:189], v[116:119]
	v_mfma_f32_16x16x32_bf16 v[100:103], v[156:159], v[190:193], v[100:103]
	v_mfma_f32_16x16x32_bf16 v[100:103], v[170:173], v[194:197], v[100:103]
	v_mfma_f32_16x16x32_bf16 v[84:87], v[156:159], v[198:201], v[84:87]
	v_mfma_f32_16x16x32_bf16 v[84:87], v[170:173], v[208:211], v[84:87]
	v_mfma_f32_16x16x32_bf16 v[72:75], v[156:159], v[212:215], v[72:75]
	v_mfma_f32_16x16x32_bf16 v[72:75], v[170:173], v[216:219], v[72:75]
	v_mfma_f32_16x16x32_bf16 v[124:127], v[148:151], v[182:185], v[124:127]
	v_mfma_f32_16x16x32_bf16 v[124:127], v[152:155], v[186:189], v[124:127]
	v_mfma_f32_16x16x32_bf16 v[112:115], v[148:151], v[190:193], v[112:115]
	v_mfma_f32_16x16x32_bf16 v[112:115], v[152:155], v[194:197], v[112:115]
	v_mfma_f32_16x16x32_bf16 v[96:99], v[148:151], v[198:201], v[96:99]
	v_mfma_f32_16x16x32_bf16 v[96:99], v[152:155], v[208:211], v[96:99]
	v_mfma_f32_16x16x32_bf16 v[80:83], v[148:151], v[212:215], v[80:83]
	v_mfma_f32_16x16x32_bf16 v[80:83], v[152:155], v[216:219], v[80:83]
	v_mfma_f32_16x16x32_bf16 v[108:111], v[174:177], v[182:185], v[108:111]
	v_mfma_f32_16x16x32_bf16 v[108:111], v[178:181], v[186:189], v[108:111]
	v_mfma_f32_16x16x32_bf16 v[92:95], v[174:177], v[190:193], v[92:95]
	v_mfma_f32_16x16x32_bf16 v[92:95], v[178:181], v[194:197], v[92:95]
	v_mfma_f32_16x16x32_bf16 v[76:79], v[174:177], v[198:201], v[76:79]
	v_mfma_f32_16x16x32_bf16 v[76:79], v[178:181], v[208:211], v[76:79]
	v_mfma_f32_16x16x32_bf16 v[68:71], v[174:177], v[212:215], v[68:71]
	v_mfma_f32_16x16x32_bf16 v[68:71], v[178:181], v[216:219], v[68:71]
	s_setprio 0
	s_barrier
	s_sleep 2
	s_add_i32 s42, s70, s0
	v_lshl_add_u64 v[160:161], v[160:161], 0, s[66:67]
	s_mov_b32 m0, s42
	ds_read_b128 v[182:185], v167 offset:49152
	ds_read_b128 v[186:189], v167 offset:50176
	ds_read_b128 v[190:193], v167 offset:51200
	ds_read_b128 v[194:197], v167 offset:52224
	ds_read_b128 v[198:201], v167 offset:53248
	ds_read_b128 v[208:211], v167 offset:54272
	ds_read_b128 v[212:215], v167 offset:55296
	ds_read_b128 v[216:219], v167 offset:56320
	global_load_lds_dwordx4 v[160:161], off
	s_add_i32 m0, s42, 0x2000
	s_add_u32 s30, s30, 0x80080
	v_lshl_add_u64 v[160:161], v[202:203], 0, s[66:67]
	s_addc_u32 s31, s31, 0
	s_add_i32 s42, s71, s0
	global_load_lds_dwordx4 v[160:161], off
	v_lshl_add_u64 v[160:161], s[30:31], 0, v[2:3]
	s_mov_b32 m0, s42
	s_nop 0
	global_load_lds_dwordx4 v[160:161], off
	v_lshl_add_u64 v[160:161], s[30:31], 0, v[142:143]
	s_add_i32 m0, s42, 0x2000
	s_nop 0
	global_load_lds_dwordx4 v[160:161], off
	v_lshl_add_u64 v[160:161], v[204:205], 0, s[66:67]
	s_mov_b32 m0, s60
	s_nop 0
	global_load_lds_dwordx4 v[160:161], off
	v_lshl_add_u64 v[160:161], v[206:207], 0, s[66:67]
	s_mov_b32 m0, s64
	s_nop 0
	global_load_lds_dwordx4 v[160:161], off
	s_waitcnt vmcnt(8)
	s_waitcnt lgkmcnt(0)
	s_barrier
	s_setprio 1
	s_waitcnt lgkmcnt(0)
	v_mfma_f32_16x16x32_bf16 v[64:67], v[132:135], v[182:185], v[64:67]
	v_mfma_f32_16x16x32_bf16 v[64:67], v[136:139], v[186:189], v[64:67]
	v_mfma_f32_16x16x32_bf16 v[56:59], v[132:135], v[190:193], v[56:59]
	v_mfma_f32_16x16x32_bf16 v[56:59], v[136:139], v[194:197], v[56:59]
	v_mfma_f32_16x16x32_bf16 v[40:43], v[132:135], v[198:201], v[40:43]
	v_mfma_f32_16x16x32_bf16 v[40:43], v[136:139], v[208:211], v[40:43]
	v_mfma_f32_16x16x32_bf16 v[24:27], v[132:135], v[212:215], v[24:27]
	v_mfma_f32_16x16x32_bf16 v[24:27], v[136:139], v[216:219], v[24:27]
	v_mfma_f32_16x16x32_bf16 v[52:55], v[156:159], v[182:185], v[52:55]
	v_mfma_f32_16x16x32_bf16 v[52:55], v[170:173], v[186:189], v[52:55]
	v_mfma_f32_16x16x32_bf16 v[36:39], v[156:159], v[190:193], v[36:39]
	v_mfma_f32_16x16x32_bf16 v[36:39], v[170:173], v[194:197], v[36:39]
	v_mfma_f32_16x16x32_bf16 v[20:23], v[156:159], v[198:201], v[20:23]
	v_mfma_f32_16x16x32_bf16 v[20:23], v[170:173], v[208:211], v[20:23]
	v_mfma_f32_16x16x32_bf16 v[8:11], v[156:159], v[212:215], v[8:11]
	v_mfma_f32_16x16x32_bf16 v[8:11], v[170:173], v[216:219], v[8:11]
	v_mfma_f32_16x16x32_bf16 v[60:63], v[148:151], v[182:185], v[60:63]
	v_mfma_f32_16x16x32_bf16 v[60:63], v[152:155], v[186:189], v[60:63]
	v_mfma_f32_16x16x32_bf16 v[48:51], v[148:151], v[190:193], v[48:51]
	v_mfma_f32_16x16x32_bf16 v[48:51], v[152:155], v[194:197], v[48:51]
	v_mfma_f32_16x16x32_bf16 v[32:35], v[148:151], v[198:201], v[32:35]
	v_mfma_f32_16x16x32_bf16 v[32:35], v[152:155], v[208:211], v[32:35]
	v_mfma_f32_16x16x32_bf16 v[16:19], v[148:151], v[212:215], v[16:19]
	v_mfma_f32_16x16x32_bf16 v[16:19], v[152:155], v[216:219], v[16:19]
	v_mfma_f32_16x16x32_bf16 v[44:47], v[174:177], v[182:185], v[44:47]
	v_mfma_f32_16x16x32_bf16 v[44:47], v[178:181], v[186:189], v[44:47]
	v_mfma_f32_16x16x32_bf16 v[28:31], v[174:177], v[190:193], v[28:31]
	v_mfma_f32_16x16x32_bf16 v[28:31], v[178:181], v[194:197], v[28:31]
	v_mfma_f32_16x16x32_bf16 v[12:15], v[174:177], v[198:201], v[12:15]
	v_mfma_f32_16x16x32_bf16 v[12:15], v[178:181], v[208:211], v[12:15]
	v_mfma_f32_16x16x32_bf16 v[4:7], v[174:177], v[212:215], v[4:7]
	v_mfma_f32_16x16x32_bf16 v[4:7], v[178:181], v[216:219], v[4:7]
	s_setprio 0
	s_barrier
	s_add_i32 s69, s69, 2
	s_add_u32 s28, s28, 0x100
	s_addc_u32 s29, s29, 0
	s_add_u32 s63, s63, 0x100
	s_addc_u32 s68, s68, 0
	s_cmp_gt_u32 s69, 29
	s_cbranch_scc0 .LBB0_430
	s_and_b64 vcc, exec, s[8:9]
	s_cbranch_vccz .LBB0_433
	s_barrier

.LBB0_494:
	s_ashr_i32 s15, s14, 31
	s_lshl_b64 s[16:17], s[14:15], 20
	s_add_u32 s16, s27, s16
	s_addc_u32 s17, s28, s17
	s_and_b64 s[18:19], s[38:39], exec
	s_cselect_b32 s15, s17, s21
	s_cselect_b32 s43, s16, s20
	s_ashr_i32 s11, s10, 31
	s_lshl_b64 s[18:19], s[10:11], 20
	s_add_u32 s18, s29, s18
	s_addc_u32 s19, s30, s19
	s_and_b64 s[24:25], s[38:39], exec
	s_cselect_b32 s11, s19, s23
	s_cselect_b32 s44, s18, s22
	s_add_u32 s20, s20, 0x80080
	s_addc_u32 s21, s21, 0
	s_add_u32 s45, s22, 0x100
	s_addc_u32 s46, s23, 0
	s_mov_b32 s47, -2
	s_sleep 1
	s_add_u32 s22, s20, 0xfff80080
	s_addc_u32 s23, s21, -1
	s_add_i32 s48, 0, 0x10000
	s_cmp_eq_u32 s47, 28
	s_cselect_b32 s25, s15, s23
	s_cselect_b32 s24, s43, s22
	s_cselect_b32 s23, s11, s46
	s_cselect_b32 s22, s44, s45
	s_add_i32 s50, 0, 0x14000
	s_waitcnt lgkmcnt(0)
	v_lshl_add_u64 v[204:205], s[20:21], 0, v[132:133]
	s_add_i32 m0, s31, 0xc000
	s_nop 0
	global_load_lds_dwordx4 v[204:205], off
	v_lshl_add_u64 v[204:205], s[20:21], 0, v[134:135]
	s_add_i32 m0, s31, 0xe000
	s_nop 0
	global_load_lds_dwordx4 v[204:205], off
	v_add_u32_e32 v152, s48, v137
	v_add_u32_e32 v168, s50, v137
	ds_read_b128 v[140:143], v152
	ds_read_b128 v[144:147], v152 offset:1024
	ds_read_b128 v[148:151], v152 offset:2048
	ds_read_b128 v[152:155], v152 offset:3072
	ds_read_b128 v[156:159], v168
	ds_read_b128 v[160:163], v168 offset:1024
	ds_read_b128 v[164:167], v168 offset:2048
	ds_read_b128 v[168:171], v168 offset:3072
	ds_read_b128 v[172:175], v139
	ds_read_b128 v[176:179], v139 offset:1024
	ds_read_b128 v[180:183], v139 offset:2048
	ds_read_b128 v[184:187], v139 offset:3072
	ds_read_b128 v[188:191], v139 offset:4096
	ds_read_b128 v[192:195], v139 offset:5120
	ds_read_b128 v[196:199], v139 offset:6144
	ds_read_b128 v[200:203], v139 offset:7168
	s_waitcnt vmcnt(8)
	s_waitcnt lgkmcnt(0)
	s_barrier
	s_setprio 1
	s_waitcnt lgkmcnt(0)
	v_mfma_f32_16x16x32_bf16 v[128:131], v[140:143], v[172:175], 0
	v_mfma_f32_16x16x32_bf16 v[128:131], v[144:147], v[176:179], v[128:131]
	v_mfma_f32_16x16x32_bf16 v[120:123], v[140:143], v[180:183], 0
	v_mfma_f32_16x16x32_bf16 v[120:123], v[144:147], v[184:187], v[120:123]
	v_mfma_f32_16x16x32_bf16 v[108:111], v[140:143], v[188:191], 0
	v_mfma_f32_16x16x32_bf16 v[108:111], v[144:147], v[192:195], v[108:111]
	v_mfma_f32_16x16x32_bf16 v[92:95], v[140:143], v[196:199], 0
	v_mfma_f32_16x16x32_bf16 v[92:95], v[144:147], v[200:203], v[92:95]
	v_mfma_f32_16x16x32_bf16 v[112:115], v[156:159], v[172:175], 0
	v_mfma_f32_16x16x32_bf16 v[112:115], v[160:163], v[176:179], v[112:115]
	v_mfma_f32_16x16x32_bf16 v[96:99], v[156:159], v[180:183], 0
	v_mfma_f32_16x16x32_bf16 v[96:99], v[160:163], v[184:187], v[96:99]
	v_mfma_f32_16x16x32_bf16 v[80:83], v[156:159], v[188:191], 0
	v_mfma_f32_16x16x32_bf16 v[80:83], v[160:163], v[192:195], v[80:83]
	v_mfma_f32_16x16x32_bf16 v[72:75], v[156:159], v[196:199], 0
	v_mfma_f32_16x16x32_bf16 v[72:75], v[160:163], v[200:203], v[72:75]
	v_mfma_f32_16x16x32_bf16 v[124:127], v[148:151], v[172:175], 0
	v_mfma_f32_16x16x32_bf16 v[124:127], v[152:155], v[176:179], v[124:127]
	v_mfma_f32_16x16x32_bf16 v[116:119], v[148:151], v[180:183], 0
	v_mfma_f32_16x16x32_bf16 v[116:119], v[152:155], v[184:187], v[116:119]
	v_mfma_f32_16x16x32_bf16 v[100:103], v[148:151], v[188:191], 0
	v_mfma_f32_16x16x32_bf16 v[100:103], v[152:155], v[192:195], v[100:103]
	v_mfma_f32_16x16x32_bf16 v[84:87], v[148:151], v[196:199], 0
	v_mfma_f32_16x16x32_bf16 v[84:87], v[152:155], v[200:203], v[84:87]
	v_mfma_f32_16x16x32_bf16 v[104:107], v[164:167], v[172:175], 0
	v_mfma_f32_16x16x32_bf16 v[104:107], v[168:171], v[176:179], v[104:107]
	v_mfma_f32_16x16x32_bf16 v[88:91], v[164:167], v[180:183], 0
	v_mfma_f32_16x16x32_bf16 v[88:91], v[168:171], v[184:187], v[88:91]
	v_mfma_f32_16x16x32_bf16 v[76:79], v[164:167], v[188:191], 0
	v_mfma_f32_16x16x32_bf16 v[76:79], v[168:171], v[192:195], v[76:79]
	v_mfma_f32_16x16x32_bf16 v[68:71], v[164:167], v[196:199], 0
	v_mfma_f32_16x16x32_bf16 v[68:71], v[168:171], v[200:203], v[68:71]
	s_setprio 0
	s_barrier
	s_sleep 2
	s_add_i32 s48, s48, s0
	v_lshl_add_u64 v[204:205], s[22:23], 0, v[2:3]
	s_mov_b32 m0, s48
	ds_read_b128 v[172:175], v139 offset:16384
	ds_read_b128 v[176:179], v139 offset:17408
	ds_read_b128 v[180:183], v139 offset:18432
	ds_read_b128 v[184:187], v139 offset:19456
	ds_read_b128 v[188:191], v139 offset:20480
	ds_read_b128 v[192:195], v139 offset:21504
	ds_read_b128 v[196:199], v139 offset:22528
	ds_read_b128 v[200:203], v139 offset:23552
	global_load_lds_dwordx4 v[204:205], off
	s_add_i32 m0, s48, 0x2000
	s_add_u32 s48, s22, 0x80000
	v_lshl_add_u64 v[206:207], s[22:23], 0, v[0:1]
	s_addc_u32 s49, s23, 0
	s_add_i32 s50, s50, s0
	global_load_lds_dwordx4 v[206:207], off
	v_lshl_add_u64 v[208:209], s[48:49], 0, v[2:3]
	s_mov_b32 m0, s50
	v_lshl_add_u64 v[210:211], s[24:25], 0, v[0:1]
	global_load_lds_dwordx4 v[208:209], off
	v_lshl_add_u64 v[208:209], s[48:49], 0, v[0:1]
	s_add_i32 m0, s50, 0x2000
	s_nop 0
	global_load_lds_dwordx4 v[208:209], off
	v_lshl_add_u64 v[208:209], s[24:25], 0, v[2:3]
	s_mov_b32 m0, s31
	s_nop 0
	global_load_lds_dwordx4 v[208:209], off
	s_mov_b32 m0, s40
	s_nop 0
	global_load_lds_dwordx4 v[210:211], off
	s_waitcnt vmcnt(8)
	s_waitcnt lgkmcnt(0)
	s_barrier
	s_setprio 1
	s_waitcnt lgkmcnt(0)
	v_mfma_f32_16x16x32_bf16 v[64:67], v[140:143], v[172:175], 0
	v_mfma_f32_16x16x32_bf16 v[64:67], v[144:147], v[176:179], v[64:67]
	v_mfma_f32_16x16x32_bf16 v[56:59], v[140:143], v[180:183], 0
	v_mfma_f32_16x16x32_bf16 v[56:59], v[144:147], v[184:187], v[56:59]
	v_mfma_f32_16x16x32_bf16 v[40:43], v[140:143], v[188:191], 0
	v_mfma_f32_16x16x32_bf16 v[40:43], v[144:147], v[192:195], v[40:43]
	v_mfma_f32_16x16x32_bf16 v[24:27], v[140:143], v[196:199], 0
	v_mfma_f32_16x16x32_bf16 v[24:27], v[144:147], v[200:203], v[24:27]
	v_mfma_f32_16x16x32_bf16 v[48:51], v[156:159], v[172:175], 0
	v_mfma_f32_16x16x32_bf16 v[48:51], v[160:163], v[176:179], v[48:51]
	v_mfma_f32_16x16x32_bf16 v[32:35], v[156:159], v[180:183], 0
	v_mfma_f32_16x16x32_bf16 v[32:35], v[160:163], v[184:187], v[32:35]
	v_mfma_f32_16x16x32_bf16 v[16:19], v[156:159], v[188:191], 0
	v_mfma_f32_16x16x32_bf16 v[16:19], v[160:163], v[192:195], v[16:19]
	v_mfma_f32_16x16x32_bf16 v[8:11], v[156:159], v[196:199], 0
	v_mfma_f32_16x16x32_bf16 v[8:11], v[160:163], v[200:203], v[8:11]
	v_mfma_f32_16x16x32_bf16 v[60:63], v[148:151], v[172:175], 0
	v_mfma_f32_16x16x32_bf16 v[60:63], v[152:155], v[176:179], v[60:63]
	v_mfma_f32_16x16x32_bf16 v[52:55], v[148:151], v[180:183], 0
	v_mfma_f32_16x16x32_bf16 v[52:55], v[152:155], v[184:187], v[52:55]
	v_mfma_f32_16x16x32_bf16 v[36:39], v[148:151], v[188:191], 0
	v_mfma_f32_16x16x32_bf16 v[36:39], v[152:155], v[192:195], v[36:39]
	v_mfma_f32_16x16x32_bf16 v[20:23], v[148:151], v[196:199], 0
	v_mfma_f32_16x16x32_bf16 v[20:23], v[152:155], v[200:203], v[20:23]
	v_mfma_f32_16x16x32_bf16 v[44:47], v[164:167], v[172:175], 0
	v_mfma_f32_16x16x32_bf16 v[44:47], v[168:171], v[176:179], v[44:47]
	v_mfma_f32_16x16x32_bf16 v[28:31], v[164:167], v[180:183], 0
	v_mfma_f32_16x16x32_bf16 v[28:31], v[168:171], v[184:187], v[28:31]
	v_mfma_f32_16x16x32_bf16 v[12:15], v[164:167], v[188:191], 0
	v_mfma_f32_16x16x32_bf16 v[12:15], v[168:171], v[192:195], v[12:15]
	v_mfma_f32_16x16x32_bf16 v[4:7], v[164:167], v[196:199], 0
	v_mfma_f32_16x16x32_bf16 v[4:7], v[168:171], v[200:203], v[4:7]
	s_setprio 0
	s_barrier
	s_sleep 1
	s_add_i32 s48, 0, 0x18000
	s_add_i32 s49, 0, 0x1c000
	s_add_u32 s24, s24, 0x80000
	s_addc_u32 s25, s25, 0
	s_mov_b32 m0, s41
	v_lshl_add_u64 v[212:213], s[24:25], 0, v[2:3]
	global_load_lds_dwordx4 v[212:213], off
	v_lshl_add_u64 v[212:213], s[24:25], 0, v[0:1]
	s_mov_b32 m0, s42
	s_nop 0
	global_load_lds_dwordx4 v[212:213], off
	v_add_u32_e32 v152, s48, v137
	v_add_u32_e32 v168, s49, v137
	ds_read_b128 v[140:143], v152
	ds_read_b128 v[144:147], v152 offset:1024
	ds_read_b128 v[148:151], v152 offset:2048
	ds_read_b128 v[152:155], v152 offset:3072
	ds_read_b128 v[156:159], v168
	ds_read_b128 v[160:163], v168 offset:1024
	ds_read_b128 v[164:167], v168 offset:2048
	ds_read_b128 v[168:171], v168 offset:3072
	ds_read_b128 v[172:175], v139 offset:32768
	ds_read_b128 v[176:179], v139 offset:33792
	ds_read_b128 v[180:183], v139 offset:34816
	ds_read_b128 v[184:187], v139 offset:35840
	ds_read_b128 v[188:191], v139 offset:36864
	ds_read_b128 v[192:195], v139 offset:37888
	ds_read_b128 v[196:199], v139 offset:38912
	ds_read_b128 v[200:203], v139 offset:39936
	s_waitcnt vmcnt(8)
	s_waitcnt lgkmcnt(0)
	s_barrier
	s_setprio 1
	s_waitcnt lgkmcnt(0)
	v_mfma_f32_16x16x32_bf16 v[128:131], v[140:143], v[172:175], v[128:131]
	v_mfma_f32_16x16x32_bf16 v[128:131], v[144:147], v[176:179], v[128:131]
	v_mfma_f32_16x16x32_bf16 v[120:123], v[140:143], v[180:183], v[120:123]
	v_mfma_f32_16x16x32_bf16 v[120:123], v[144:147], v[184:187], v[120:123]
	v_mfma_f32_16x16x32_bf16 v[108:111], v[140:143], v[188:191], v[108:111]
	v_mfma_f32_16x16x32_bf16 v[108:111], v[144:147], v[192:195], v[108:111]
	v_mfma_f32_16x16x32_bf16 v[92:95], v[140:143], v[196:199], v[92:95]
	v_mfma_f32_16x16x32_bf16 v[92:95], v[144:147], v[200:203], v[92:95]
	v_mfma_f32_16x16x32_bf16 v[112:115], v[156:159], v[172:175], v[112:115]
	v_mfma_f32_16x16x32_bf16 v[112:115], v[160:163], v[176:179], v[112:115]
	v_mfma_f32_16x16x32_bf16 v[96:99], v[156:159], v[180:183], v[96:99]
	v_mfma_f32_16x16x32_bf16 v[96:99], v[160:163], v[184:187], v[96:99]
	v_mfma_f32_16x16x32_bf16 v[80:83], v[156:159], v[188:191], v[80:83]
	v_mfma_f32_16x16x32_bf16 v[80:83], v[160:163], v[192:195], v[80:83]
	v_mfma_f32_16x16x32_bf16 v[72:75], v[156:159], v[196:199], v[72:75]
	v_mfma_f32_16x16x32_bf16 v[72:75], v[160:163], v[200:203], v[72:75]
	v_mfma_f32_16x16x32_bf16 v[124:127], v[148:151], v[172:175], v[124:127]
	v_mfma_f32_16x16x32_bf16 v[124:127], v[152:155], v[176:179], v[124:127]
	v_mfma_f32_16x16x32_bf16 v[116:119], v[148:151], v[180:183], v[116:119]
	v_mfma_f32_16x16x32_bf16 v[116:119], v[152:155], v[184:187], v[116:119]
	v_mfma_f32_16x16x32_bf16 v[100:103], v[148:151], v[188:191], v[100:103]
	v_mfma_f32_16x16x32_bf16 v[100:103], v[152:155], v[192:195], v[100:103]
	v_mfma_f32_16x16x32_bf16 v[84:87], v[148:151], v[196:199], v[84:87]
	v_mfma_f32_16x16x32_bf16 v[84:87], v[152:155], v[200:203], v[84:87]
	v_mfma_f32_16x16x32_bf16 v[104:107], v[164:167], v[172:175], v[104:107]
	v_mfma_f32_16x16x32_bf16 v[104:107], v[168:171], v[176:179], v[104:107]
	v_mfma_f32_16x16x32_bf16 v[88:91], v[164:167], v[180:183], v[88:91]
	v_mfma_f32_16x16x32_bf16 v[88:91], v[168:171], v[184:187], v[88:91]
	v_mfma_f32_16x16x32_bf16 v[76:79], v[164:167], v[188:191], v[76:79]
	v_mfma_f32_16x16x32_bf16 v[76:79], v[168:171], v[192:195], v[76:79]
	v_mfma_f32_16x16x32_bf16 v[68:71], v[164:167], v[196:199], v[68:71]
	v_mfma_f32_16x16x32_bf16 v[68:71], v[168:171], v[200:203], v[68:71]
	s_setprio 0
	s_barrier
	s_sleep 2
	s_add_i32 s24, s48, s0
	v_lshl_add_u64 v[204:205], v[204:205], 0, s[66:67]
	s_mov_b32 m0, s24
	ds_read_b128 v[172:175], v139 offset:49152
	ds_read_b128 v[176:179], v139 offset:50176
	ds_read_b128 v[180:183], v139 offset:51200
	ds_read_b128 v[184:187], v139 offset:52224
	ds_read_b128 v[188:191], v139 offset:53248
	ds_read_b128 v[192:195], v139 offset:54272
	ds_read_b128 v[196:199], v139 offset:55296
	ds_read_b128 v[200:203], v139 offset:56320
	global_load_lds_dwordx4 v[204:205], off
	s_add_i32 m0, s24, 0x2000
	s_add_u32 s22, s22, 0x80080
	v_lshl_add_u64 v[204:205], v[206:207], 0, s[66:67]
	s_addc_u32 s23, s23, 0
	s_add_i32 s24, s49, s0
	global_load_lds_dwordx4 v[204:205], off
	v_lshl_add_u64 v[204:205], s[22:23], 0, v[2:3]
	s_mov_b32 m0, s24
	s_nop 0
	global_load_lds_dwordx4 v[204:205], off
	v_lshl_add_u64 v[204:205], s[22:23], 0, v[0:1]
	s_add_i32 m0, s24, 0x2000
	s_nop 0
	global_load_lds_dwordx4 v[204:205], off
	v_lshl_add_u64 v[204:205], v[208:209], 0, s[66:67]
	s_mov_b32 m0, s1
	s_nop 0
	global_load_lds_dwordx4 v[204:205], off
	v_lshl_add_u64 v[204:205], v[210:211], 0, s[66:67]
	s_mov_b32 m0, s34
	s_nop 0
	global_load_lds_dwordx4 v[204:205], off
	s_waitcnt vmcnt(8)
	s_waitcnt lgkmcnt(0)
	s_barrier
	s_setprio 1
	s_waitcnt lgkmcnt(0)
	v_mfma_f32_16x16x32_bf16 v[64:67], v[140:143], v[172:175], v[64:67]
	v_mfma_f32_16x16x32_bf16 v[64:67], v[144:147], v[176:179], v[64:67]
	v_mfma_f32_16x16x32_bf16 v[56:59], v[140:143], v[180:183], v[56:59]
	v_mfma_f32_16x16x32_bf16 v[56:59], v[144:147], v[184:187], v[56:59]
	v_mfma_f32_16x16x32_bf16 v[40:43], v[140:143], v[188:191], v[40:43]
	v_mfma_f32_16x16x32_bf16 v[40:43], v[144:147], v[192:195], v[40:43]
	v_mfma_f32_16x16x32_bf16 v[24:27], v[140:143], v[196:199], v[24:27]
	v_mfma_f32_16x16x32_bf16 v[24:27], v[144:147], v[200:203], v[24:27]
	v_mfma_f32_16x16x32_bf16 v[48:51], v[156:159], v[172:175], v[48:51]
	v_mfma_f32_16x16x32_bf16 v[48:51], v[160:163], v[176:179], v[48:51]
	v_mfma_f32_16x16x32_bf16 v[32:35], v[156:159], v[180:183], v[32:35]
	v_mfma_f32_16x16x32_bf16 v[32:35], v[160:163], v[184:187], v[32:35]
	v_mfma_f32_16x16x32_bf16 v[16:19], v[156:159], v[188:191], v[16:19]
	v_mfma_f32_16x16x32_bf16 v[16:19], v[160:163], v[192:195], v[16:19]
	v_mfma_f32_16x16x32_bf16 v[8:11], v[156:159], v[196:199], v[8:11]
	v_mfma_f32_16x16x32_bf16 v[8:11], v[160:163], v[200:203], v[8:11]
	v_mfma_f32_16x16x32_bf16 v[60:63], v[148:151], v[172:175], v[60:63]
	v_mfma_f32_16x16x32_bf16 v[60:63], v[152:155], v[176:179], v[60:63]
	v_mfma_f32_16x16x32_bf16 v[52:55], v[148:151], v[180:183], v[52:55]
	v_mfma_f32_16x16x32_bf16 v[52:55], v[152:155], v[184:187], v[52:55]
	v_mfma_f32_16x16x32_bf16 v[36:39], v[148:151], v[188:191], v[36:39]
	v_mfma_f32_16x16x32_bf16 v[36:39], v[152:155], v[192:195], v[36:39]
	v_mfma_f32_16x16x32_bf16 v[20:23], v[148:151], v[196:199], v[20:23]
	v_mfma_f32_16x16x32_bf16 v[20:23], v[152:155], v[200:203], v[20:23]
	v_mfma_f32_16x16x32_bf16 v[44:47], v[164:167], v[172:175], v[44:47]
	v_mfma_f32_16x16x32_bf16 v[44:47], v[168:171], v[176:179], v[44:47]
	v_mfma_f32_16x16x32_bf16 v[28:31], v[164:167], v[180:183], v[28:31]
	v_mfma_f32_16x16x32_bf16 v[28:31], v[168:171], v[184:187], v[28:31]
	v_mfma_f32_16x16x32_bf16 v[12:15], v[164:167], v[188:191], v[12:15]
	v_mfma_f32_16x16x32_bf16 v[12:15], v[168:171], v[192:195], v[12:15]
	v_mfma_f32_16x16x32_bf16 v[4:7], v[164:167], v[196:199], v[4:7]
	v_mfma_f32_16x16x32_bf16 v[4:7], v[168:171], v[200:203], v[4:7]
	s_setprio 0
	s_barrier
	s_add_i32 s47, s47, 2
	s_add_u32 s20, s20, 0x100
	s_addc_u32 s21, s21, 0
	s_add_u32 s45, s45, 0x100
	s_addc_u32 s46, s46, 0
	s_cmp_gt_u32 s47, 29
.LBB0_495:
	s_sleep 1
	s_add_u32 s22, s20, 0xfff80080
	s_addc_u32 s23, s21, -1
	s_add_i32 s48, 0, 0x10000
	s_cmp_eq_u32 s47, 28
	s_cselect_b32 s25, s15, s23
	s_cselect_b32 s24, s43, s22
	s_cselect_b32 s23, s11, s46
	s_cselect_b32 s22, s44, s45
	s_add_i32 s50, 0, 0x14000
	s_waitcnt lgkmcnt(0)
	v_lshl_add_u64 v[204:205], s[20:21], 0, v[132:133]
	s_add_i32 m0, s31, 0xc000
	s_nop 0
	global_load_lds_dwordx4 v[204:205], off
	v_lshl_add_u64 v[204:205], s[20:21], 0, v[134:135]
	s_add_i32 m0, s31, 0xe000
	s_nop 0
	global_load_lds_dwordx4 v[204:205], off
	v_add_u32_e32 v152, s48, v137
	v_add_u32_e32 v168, s50, v137
	ds_read_b128 v[140:143], v152
	ds_read_b128 v[144:147], v152 offset:1024
	ds_read_b128 v[148:151], v152 offset:2048
	ds_read_b128 v[152:155], v152 offset:3072
	ds_read_b128 v[156:159], v168
	ds_read_b128 v[160:163], v168 offset:1024
	ds_read_b128 v[164:167], v168 offset:2048
	ds_read_b128 v[168:171], v168 offset:3072
	ds_read_b128 v[172:175], v139
	ds_read_b128 v[176:179], v139 offset:1024
	ds_read_b128 v[180:183], v139 offset:2048
	ds_read_b128 v[184:187], v139 offset:3072
	ds_read_b128 v[188:191], v139 offset:4096
	ds_read_b128 v[192:195], v139 offset:5120
	ds_read_b128 v[196:199], v139 offset:6144
	ds_read_b128 v[200:203], v139 offset:7168
	s_waitcnt vmcnt(8)
	s_waitcnt lgkmcnt(0)
	s_barrier
	s_setprio 1
	s_waitcnt lgkmcnt(0)
	v_mfma_f32_16x16x32_bf16 v[128:131], v[140:143], v[172:175], v[128:131]
	v_mfma_f32_16x16x32_bf16 v[128:131], v[144:147], v[176:179], v[128:131]
	v_mfma_f32_16x16x32_bf16 v[120:123], v[140:143], v[180:183], v[120:123]
	v_mfma_f32_16x16x32_bf16 v[120:123], v[144:147], v[184:187], v[120:123]
	v_mfma_f32_16x16x32_bf16 v[108:111], v[140:143], v[188:191], v[108:111]
	v_mfma_f32_16x16x32_bf16 v[108:111], v[144:147], v[192:195], v[108:111]
	v_mfma_f32_16x16x32_bf16 v[92:95], v[140:143], v[196:199], v[92:95]
	v_mfma_f32_16x16x32_bf16 v[92:95], v[144:147], v[200:203], v[92:95]
	v_mfma_f32_16x16x32_bf16 v[112:115], v[156:159], v[172:175], v[112:115]
	v_mfma_f32_16x16x32_bf16 v[112:115], v[160:163], v[176:179], v[112:115]
	v_mfma_f32_16x16x32_bf16 v[96:99], v[156:159], v[180:183], v[96:99]
	v_mfma_f32_16x16x32_bf16 v[96:99], v[160:163], v[184:187], v[96:99]
	v_mfma_f32_16x16x32_bf16 v[80:83], v[156:159], v[188:191], v[80:83]
	v_mfma_f32_16x16x32_bf16 v[80:83], v[160:163], v[192:195], v[80:83]
	v_mfma_f32_16x16x32_bf16 v[72:75], v[156:159], v[196:199], v[72:75]
	v_mfma_f32_16x16x32_bf16 v[72:75], v[160:163], v[200:203], v[72:75]
	v_mfma_f32_16x16x32_bf16 v[124:127], v[148:151], v[172:175], v[124:127]
	v_mfma_f32_16x16x32_bf16 v[124:127], v[152:155], v[176:179], v[124:127]
	v_mfma_f32_16x16x32_bf16 v[116:119], v[148:151], v[180:183], v[116:119]
	v_mfma_f32_16x16x32_bf16 v[116:119], v[152:155], v[184:187], v[116:119]
	v_mfma_f32_16x16x32_bf16 v[100:103], v[148:151], v[188:191], v[100:103]
	v_mfma_f32_16x16x32_bf16 v[100:103], v[152:155], v[192:195], v[100:103]
	v_mfma_f32_16x16x32_bf16 v[84:87], v[148:151], v[196:199], v[84:87]
	v_mfma_f32_16x16x32_bf16 v[84:87], v[152:155], v[200:203], v[84:87]
	v_mfma_f32_16x16x32_bf16 v[104:107], v[164:167], v[172:175], v[104:107]
	v_mfma_f32_16x16x32_bf16 v[104:107], v[168:171], v[176:179], v[104:107]
	v_mfma_f32_16x16x32_bf16 v[88:91], v[164:167], v[180:183], v[88:91]
	v_mfma_f32_16x16x32_bf16 v[88:91], v[168:171], v[184:187], v[88:91]
	v_mfma_f32_16x16x32_bf16 v[76:79], v[164:167], v[188:191], v[76:79]
	v_mfma_f32_16x16x32_bf16 v[76:79], v[168:171], v[192:195], v[76:79]
	v_mfma_f32_16x16x32_bf16 v[68:71], v[164:167], v[196:199], v[68:71]
	v_mfma_f32_16x16x32_bf16 v[68:71], v[168:171], v[200:203], v[68:71]
	s_setprio 0
	s_barrier
	s_sleep 2
	s_add_i32 s48, s48, s0
	v_lshl_add_u64 v[204:205], s[22:23], 0, v[2:3]
	s_mov_b32 m0, s48
	ds_read_b128 v[172:175], v139 offset:16384
	ds_read_b128 v[176:179], v139 offset:17408
	ds_read_b128 v[180:183], v139 offset:18432
	ds_read_b128 v[184:187], v139 offset:19456
	ds_read_b128 v[188:191], v139 offset:20480
	ds_read_b128 v[192:195], v139 offset:21504
	ds_read_b128 v[196:199], v139 offset:22528
	ds_read_b128 v[200:203], v139 offset:23552
	global_load_lds_dwordx4 v[204:205], off
	s_add_i32 m0, s48, 0x2000
	s_add_u32 s48, s22, 0x80000
	v_lshl_add_u64 v[206:207], s[22:23], 0, v[0:1]
	s_addc_u32 s49, s23, 0
	s_add_i32 s50, s50, s0
	global_load_lds_dwordx4 v[206:207], off
	v_lshl_add_u64 v[208:209], s[48:49], 0, v[2:3]
	s_mov_b32 m0, s50
	v_lshl_add_u64 v[210:211], s[24:25], 0, v[0:1]
	global_load_lds_dwordx4 v[208:209], off
	v_lshl_add_u64 v[208:209], s[48:49], 0, v[0:1]
	s_add_i32 m0, s50, 0x2000
	s_nop 0
	global_load_lds_dwordx4 v[208:209], off
	v_lshl_add_u64 v[208:209], s[24:25], 0, v[2:3]
	s_mov_b32 m0, s31
	s_nop 0
	global_load_lds_dwordx4 v[208:209], off
	s_mov_b32 m0, s40
	s_nop 0
	global_load_lds_dwordx4 v[210:211], off
	s_waitcnt vmcnt(8)
	s_waitcnt lgkmcnt(0)
	s_barrier
	s_setprio 1
	s_waitcnt lgkmcnt(0)
	v_mfma_f32_16x16x32_bf16 v[64:67], v[140:143], v[172:175], v[64:67]
	v_mfma_f32_16x16x32_bf16 v[64:67], v[144:147], v[176:179], v[64:67]
	v_mfma_f32_16x16x32_bf16 v[56:59], v[140:143], v[180:183], v[56:59]
	v_mfma_f32_16x16x32_bf16 v[56:59], v[144:147], v[184:187], v[56:59]
	v_mfma_f32_16x16x32_bf16 v[40:43], v[140:143], v[188:191], v[40:43]
	v_mfma_f32_16x16x32_bf16 v[40:43], v[144:147], v[192:195], v[40:43]
	v_mfma_f32_16x16x32_bf16 v[24:27], v[140:143], v[196:199], v[24:27]
	v_mfma_f32_16x16x32_bf16 v[24:27], v[144:147], v[200:203], v[24:27]
	v_mfma_f32_16x16x32_bf16 v[48:51], v[156:159], v[172:175], v[48:51]
	v_mfma_f32_16x16x32_bf16 v[48:51], v[160:163], v[176:179], v[48:51]
	v_mfma_f32_16x16x32_bf16 v[32:35], v[156:159], v[180:183], v[32:35]
	v_mfma_f32_16x16x32_bf16 v[32:35], v[160:163], v[184:187], v[32:35]
	v_mfma_f32_16x16x32_bf16 v[16:19], v[156:159], v[188:191], v[16:19]
	v_mfma_f32_16x16x32_bf16 v[16:19], v[160:163], v[192:195], v[16:19]
	v_mfma_f32_16x16x32_bf16 v[8:11], v[156:159], v[196:199], v[8:11]
	v_mfma_f32_16x16x32_bf16 v[8:11], v[160:163], v[200:203], v[8:11]
	v_mfma_f32_16x16x32_bf16 v[60:63], v[148:151], v[172:175], v[60:63]
	v_mfma_f32_16x16x32_bf16 v[60:63], v[152:155], v[176:179], v[60:63]
	v_mfma_f32_16x16x32_bf16 v[52:55], v[148:151], v[180:183], v[52:55]
	v_mfma_f32_16x16x32_bf16 v[52:55], v[152:155], v[184:187], v[52:55]
	v_mfma_f32_16x16x32_bf16 v[36:39], v[148:151], v[188:191], v[36:39]
	v_mfma_f32_16x16x32_bf16 v[36:39], v[152:155], v[192:195], v[36:39]
	v_mfma_f32_16x16x32_bf16 v[20:23], v[148:151], v[196:199], v[20:23]
	v_mfma_f32_16x16x32_bf16 v[20:23], v[152:155], v[200:203], v[20:23]
	v_mfma_f32_16x16x32_bf16 v[44:47], v[164:167], v[172:175], v[44:47]
	v_mfma_f32_16x16x32_bf16 v[44:47], v[168:171], v[176:179], v[44:47]
	v_mfma_f32_16x16x32_bf16 v[28:31], v[164:167], v[180:183], v[28:31]
	v_mfma_f32_16x16x32_bf16 v[28:31], v[168:171], v[184:187], v[28:31]
	v_mfma_f32_16x16x32_bf16 v[12:15], v[164:167], v[188:191], v[12:15]
	v_mfma_f32_16x16x32_bf16 v[12:15], v[168:171], v[192:195], v[12:15]
	v_mfma_f32_16x16x32_bf16 v[4:7], v[164:167], v[196:199], v[4:7]
	v_mfma_f32_16x16x32_bf16 v[4:7], v[168:171], v[200:203], v[4:7]
	s_setprio 0
	s_barrier
	s_sleep 1
	s_add_i32 s48, 0, 0x18000
	s_add_i32 s49, 0, 0x1c000
	s_add_u32 s24, s24, 0x80000
	s_addc_u32 s25, s25, 0
	s_mov_b32 m0, s41
	v_lshl_add_u64 v[212:213], s[24:25], 0, v[2:3]
	global_load_lds_dwordx4 v[212:213], off
	v_lshl_add_u64 v[212:213], s[24:25], 0, v[0:1]
	s_mov_b32 m0, s42
	s_nop 0
	global_load_lds_dwordx4 v[212:213], off
	v_add_u32_e32 v152, s48, v137
	v_add_u32_e32 v168, s49, v137
	ds_read_b128 v[140:143], v152
	ds_read_b128 v[144:147], v152 offset:1024
	ds_read_b128 v[148:151], v152 offset:2048
	ds_read_b128 v[152:155], v152 offset:3072
	ds_read_b128 v[156:159], v168
	ds_read_b128 v[160:163], v168 offset:1024
	ds_read_b128 v[164:167], v168 offset:2048
	ds_read_b128 v[168:171], v168 offset:3072
	ds_read_b128 v[172:175], v139 offset:32768
	ds_read_b128 v[176:179], v139 offset:33792
	ds_read_b128 v[180:183], v139 offset:34816
	ds_read_b128 v[184:187], v139 offset:35840
	ds_read_b128 v[188:191], v139 offset:36864
	ds_read_b128 v[192:195], v139 offset:37888
	ds_read_b128 v[196:199], v139 offset:38912
	ds_read_b128 v[200:203], v139 offset:39936
	s_waitcnt vmcnt(8)
	s_waitcnt lgkmcnt(0)
	s_barrier
	s_setprio 1
	s_waitcnt lgkmcnt(0)
	v_mfma_f32_16x16x32_bf16 v[128:131], v[140:143], v[172:175], v[128:131]
	v_mfma_f32_16x16x32_bf16 v[128:131], v[144:147], v[176:179], v[128:131]
	v_mfma_f32_16x16x32_bf16 v[120:123], v[140:143], v[180:183], v[120:123]
	v_mfma_f32_16x16x32_bf16 v[120:123], v[144:147], v[184:187], v[120:123]
	v_mfma_f32_16x16x32_bf16 v[108:111], v[140:143], v[188:191], v[108:111]
	v_mfma_f32_16x16x32_bf16 v[108:111], v[144:147], v[192:195], v[108:111]
	v_mfma_f32_16x16x32_bf16 v[92:95], v[140:143], v[196:199], v[92:95]
	v_mfma_f32_16x16x32_bf16 v[92:95], v[144:147], v[200:203], v[92:95]
	v_mfma_f32_16x16x32_bf16 v[112:115], v[156:159], v[172:175], v[112:115]
	v_mfma_f32_16x16x32_bf16 v[112:115], v[160:163], v[176:179], v[112:115]
	v_mfma_f32_16x16x32_bf16 v[96:99], v[156:159], v[180:183], v[96:99]
	v_mfma_f32_16x16x32_bf16 v[96:99], v[160:163], v[184:187], v[96:99]
	v_mfma_f32_16x16x32_bf16 v[80:83], v[156:159], v[188:191], v[80:83]
	v_mfma_f32_16x16x32_bf16 v[80:83], v[160:163], v[192:195], v[80:83]
	v_mfma_f32_16x16x32_bf16 v[72:75], v[156:159], v[196:199], v[72:75]
	v_mfma_f32_16x16x32_bf16 v[72:75], v[160:163], v[200:203], v[72:75]
	v_mfma_f32_16x16x32_bf16 v[124:127], v[148:151], v[172:175], v[124:127]
	v_mfma_f32_16x16x32_bf16 v[124:127], v[152:155], v[176:179], v[124:127]
	v_mfma_f32_16x16x32_bf16 v[116:119], v[148:151], v[180:183], v[116:119]
	v_mfma_f32_16x16x32_bf16 v[116:119], v[152:155], v[184:187], v[116:119]
	v_mfma_f32_16x16x32_bf16 v[100:103], v[148:151], v[188:191], v[100:103]
	v_mfma_f32_16x16x32_bf16 v[100:103], v[152:155], v[192:195], v[100:103]
	v_mfma_f32_16x16x32_bf16 v[84:87], v[148:151], v[196:199], v[84:87]
	v_mfma_f32_16x16x32_bf16 v[84:87], v[152:155], v[200:203], v[84:87]
	v_mfma_f32_16x16x32_bf16 v[104:107], v[164:167], v[172:175], v[104:107]
	v_mfma_f32_16x16x32_bf16 v[104:107], v[168:171], v[176:179], v[104:107]
	v_mfma_f32_16x16x32_bf16 v[88:91], v[164:167], v[180:183], v[88:91]
	v_mfma_f32_16x16x32_bf16 v[88:91], v[168:171], v[184:187], v[88:91]
	v_mfma_f32_16x16x32_bf16 v[76:79], v[164:167], v[188:191], v[76:79]
	v_mfma_f32_16x16x32_bf16 v[76:79], v[168:171], v[192:195], v[76:79]
	v_mfma_f32_16x16x32_bf16 v[68:71], v[164:167], v[196:199], v[68:71]
	v_mfma_f32_16x16x32_bf16 v[68:71], v[168:171], v[200:203], v[68:71]
	s_setprio 0
	s_barrier
	s_sleep 2
	s_add_i32 s24, s48, s0
	v_lshl_add_u64 v[204:205], v[204:205], 0, s[66:67]
	s_mov_b32 m0, s24
	ds_read_b128 v[172:175], v139 offset:49152
	ds_read_b128 v[176:179], v139 offset:50176
	ds_read_b128 v[180:183], v139 offset:51200
	ds_read_b128 v[184:187], v139 offset:52224
	ds_read_b128 v[188:191], v139 offset:53248
	ds_read_b128 v[192:195], v139 offset:54272
	ds_read_b128 v[196:199], v139 offset:55296
	ds_read_b128 v[200:203], v139 offset:56320
	global_load_lds_dwordx4 v[204:205], off
	s_add_i32 m0, s24, 0x2000
	s_add_u32 s22, s22, 0x80080
	v_lshl_add_u64 v[204:205], v[206:207], 0, s[66:67]
	s_addc_u32 s23, s23, 0
	s_add_i32 s24, s49, s0
	global_load_lds_dwordx4 v[204:205], off
	v_lshl_add_u64 v[204:205], s[22:23], 0, v[2:3]
	s_mov_b32 m0, s24
	s_nop 0
	global_load_lds_dwordx4 v[204:205], off
	v_lshl_add_u64 v[204:205], s[22:23], 0, v[0:1]
	s_add_i32 m0, s24, 0x2000
	s_nop 0
	global_load_lds_dwordx4 v[204:205], off
	v_lshl_add_u64 v[204:205], v[208:209], 0, s[66:67]
	s_mov_b32 m0, s1
	s_nop 0
	global_load_lds_dwordx4 v[204:205], off
	v_lshl_add_u64 v[204:205], v[210:211], 0, s[66:67]
	s_mov_b32 m0, s34
	s_nop 0
	global_load_lds_dwordx4 v[204:205], off
	s_waitcnt vmcnt(8)
	s_waitcnt lgkmcnt(0)
	s_barrier
	s_setprio 1
	s_waitcnt lgkmcnt(0)
	v_mfma_f32_16x16x32_bf16 v[64:67], v[140:143], v[172:175], v[64:67]
	v_mfma_f32_16x16x32_bf16 v[64:67], v[144:147], v[176:179], v[64:67]
	v_mfma_f32_16x16x32_bf16 v[56:59], v[140:143], v[180:183], v[56:59]
	v_mfma_f32_16x16x32_bf16 v[56:59], v[144:147], v[184:187], v[56:59]
	v_mfma_f32_16x16x32_bf16 v[40:43], v[140:143], v[188:191], v[40:43]
	v_mfma_f32_16x16x32_bf16 v[40:43], v[144:147], v[192:195], v[40:43]
	v_mfma_f32_16x16x32_bf16 v[24:27], v[140:143], v[196:199], v[24:27]
	v_mfma_f32_16x16x32_bf16 v[24:27], v[144:147], v[200:203], v[24:27]
	v_mfma_f32_16x16x32_bf16 v[48:51], v[156:159], v[172:175], v[48:51]
	v_mfma_f32_16x16x32_bf16 v[48:51], v[160:163], v[176:179], v[48:51]
	v_mfma_f32_16x16x32_bf16 v[32:35], v[156:159], v[180:183], v[32:35]
	v_mfma_f32_16x16x32_bf16 v[32:35], v[160:163], v[184:187], v[32:35]
	v_mfma_f32_16x16x32_bf16 v[16:19], v[156:159], v[188:191], v[16:19]
	v_mfma_f32_16x16x32_bf16 v[16:19], v[160:163], v[192:195], v[16:19]
	v_mfma_f32_16x16x32_bf16 v[8:11], v[156:159], v[196:199], v[8:11]
	v_mfma_f32_16x16x32_bf16 v[8:11], v[160:163], v[200:203], v[8:11]
	v_mfma_f32_16x16x32_bf16 v[60:63], v[148:151], v[172:175], v[60:63]
	v_mfma_f32_16x16x32_bf16 v[60:63], v[152:155], v[176:179], v[60:63]
	v_mfma_f32_16x16x32_bf16 v[52:55], v[148:151], v[180:183], v[52:55]
	v_mfma_f32_16x16x32_bf16 v[52:55], v[152:155], v[184:187], v[52:55]
	v_mfma_f32_16x16x32_bf16 v[36:39], v[148:151], v[188:191], v[36:39]
	v_mfma_f32_16x16x32_bf16 v[36:39], v[152:155], v[192:195], v[36:39]
	v_mfma_f32_16x16x32_bf16 v[20:23], v[148:151], v[196:199], v[20:23]
	v_mfma_f32_16x16x32_bf16 v[20:23], v[152:155], v[200:203], v[20:23]
	v_mfma_f32_16x16x32_bf16 v[44:47], v[164:167], v[172:175], v[44:47]
	v_mfma_f32_16x16x32_bf16 v[44:47], v[168:171], v[176:179], v[44:47]
	v_mfma_f32_16x16x32_bf16 v[28:31], v[164:167], v[180:183], v[28:31]
	v_mfma_f32_16x16x32_bf16 v[28:31], v[168:171], v[184:187], v[28:31]
	v_mfma_f32_16x16x32_bf16 v[12:15], v[164:167], v[188:191], v[12:15]
	v_mfma_f32_16x16x32_bf16 v[12:15], v[168:171], v[192:195], v[12:15]
	v_mfma_f32_16x16x32_bf16 v[4:7], v[164:167], v[196:199], v[4:7]
	v_mfma_f32_16x16x32_bf16 v[4:7], v[168:171], v[200:203], v[4:7]
	s_setprio 0
	s_barrier
	s_add_i32 s47, s47, 2
	s_add_u32 s20, s20, 0x100
	s_addc_u32 s21, s21, 0
	s_add_u32 s45, s45, 0x100
	s_addc_u32 s46, s46, 0
	s_cmp_gt_u32 s47, 29
	s_cbranch_scc0 .LBB0_495
	s_and_b64 vcc, exec, s[8:9]
	s_cbranch_vccz .LBB0_498
	s_barrier

.LBB0_1009:
	s_ashr_i32 s13, s12, 31
	s_lshl_b64 s[14:15], s[12:13], 20
	s_add_u32 s14, s1, s14
	s_addc_u32 s15, s2, s15
	s_and_b64 s[16:17], s[38:39], exec
	s_cselect_b32 s13, s15, s23
	s_cselect_b32 s19, s14, s22
	s_ashr_i32 s11, s10, 31
	s_lshl_b64 s[16:17], s[10:11], 20
	s_add_u32 s16, s28, s16
	s_addc_u32 s17, s29, s17
	s_and_b64 s[26:27], s[38:39], exec
	s_cselect_b32 s11, s17, s25
	s_cselect_b32 s45, s16, s24
	s_add_u32 s22, s22, 0x80080
	s_addc_u32 s23, s23, 0
	s_add_u32 s46, s24, 0x100
	s_addc_u32 s47, s25, 0
	s_mov_b32 s48, -2
	s_sleep 1
	s_add_u32 s24, s22, 0xfff80080
	s_addc_u32 s25, s23, -1
	s_add_i32 s49, 0, 0x10000
	s_cmp_eq_u32 s48, 28
	s_cselect_b32 s27, s13, s25
	s_cselect_b32 s26, s19, s24
	s_cselect_b32 s25, s11, s47
	s_cselect_b32 s24, s45, s46
	s_add_i32 s52, 0, 0x14000
	v_lshl_add_u64 v[204:205], s[22:23], 0, v[192:193]
	s_add_i32 m0, s21, 0xc000
	s_nop 0
	global_load_lds_dwordx4 v[204:205], off
	v_lshl_add_u64 v[204:205], s[22:23], 0, v[194:195]
	s_add_i32 m0, s21, 0xe000
	s_nop 0
	global_load_lds_dwordx4 v[204:205], off
	v_add_u32_e32 v144, s49, v219
	v_add_u32_e32 v160, s52, v219
	ds_read_b128 v[116:119], v144
	ds_read_b128 v[124:127], v144 offset:1024
	ds_read_b128 v[132:135], v144 offset:2048
	ds_read_b128 v[144:147], v144 offset:3072
	ds_read_b128 v[148:151], v160
	ds_read_b128 v[152:155], v160 offset:1024
	ds_read_b128 v[156:159], v160 offset:2048
	ds_read_b128 v[160:163], v160 offset:3072
	ds_read_b128 v[164:167], v221
	ds_read_b128 v[168:171], v221 offset:1024
	ds_read_b128 v[172:175], v221 offset:2048
	ds_read_b128 v[176:179], v221 offset:3072
	ds_read_b128 v[180:183], v221 offset:4096
	ds_read_b128 v[184:187], v221 offset:5120
	ds_read_b128 v[196:199], v221 offset:6144
	ds_read_b128 v[200:203], v221 offset:7168
	s_waitcnt vmcnt(8)
	s_waitcnt lgkmcnt(0)
	s_barrier
	s_setprio 1
	s_waitcnt lgkmcnt(0)
	v_mfma_f32_16x16x32_bf16 v[140:143], v[116:119], v[164:167], 0
	v_mfma_f32_16x16x32_bf16 v[140:143], v[124:127], v[168:171], v[140:143]
	v_mfma_f32_16x16x32_bf16 v[112:115], v[116:119], v[172:175], 0
	v_mfma_f32_16x16x32_bf16 v[112:115], v[124:127], v[176:179], v[112:115]
	v_mfma_f32_16x16x32_bf16 v[96:99], v[116:119], v[180:183], 0
	v_mfma_f32_16x16x32_bf16 v[96:99], v[124:127], v[184:187], v[96:99]
	v_mfma_f32_16x16x32_bf16 v[80:83], v[116:119], v[196:199], 0
	v_mfma_f32_16x16x32_bf16 v[80:83], v[124:127], v[200:203], v[80:83]
	v_mfma_f32_16x16x32_bf16 v[128:131], v[148:151], v[164:167], 0
	v_mfma_f32_16x16x32_bf16 v[128:131], v[152:155], v[168:171], v[128:131]
	v_mfma_f32_16x16x32_bf16 v[104:107], v[148:151], v[172:175], 0
	v_mfma_f32_16x16x32_bf16 v[104:107], v[152:155], v[176:179], v[104:107]
	v_mfma_f32_16x16x32_bf16 v[88:91], v[148:151], v[180:183], 0
	v_mfma_f32_16x16x32_bf16 v[88:91], v[152:155], v[184:187], v[88:91]
	v_mfma_f32_16x16x32_bf16 v[72:75], v[148:151], v[196:199], 0
	v_mfma_f32_16x16x32_bf16 v[72:75], v[152:155], v[200:203], v[72:75]
	v_mfma_f32_16x16x32_bf16 v[136:139], v[132:135], v[164:167], 0
	v_mfma_f32_16x16x32_bf16 v[136:139], v[144:147], v[168:171], v[136:139]
	v_mfma_f32_16x16x32_bf16 v[108:111], v[132:135], v[172:175], 0
	v_mfma_f32_16x16x32_bf16 v[108:111], v[144:147], v[176:179], v[108:111]
	v_mfma_f32_16x16x32_bf16 v[92:95], v[132:135], v[180:183], 0
	v_mfma_f32_16x16x32_bf16 v[92:95], v[144:147], v[184:187], v[92:95]
	v_mfma_f32_16x16x32_bf16 v[76:79], v[132:135], v[196:199], 0
	v_mfma_f32_16x16x32_bf16 v[76:79], v[144:147], v[200:203], v[76:79]
	v_mfma_f32_16x16x32_bf16 v[120:123], v[156:159], v[164:167], 0
	v_mfma_f32_16x16x32_bf16 v[120:123], v[160:163], v[168:171], v[120:123]
	v_mfma_f32_16x16x32_bf16 v[100:103], v[156:159], v[172:175], 0
	v_mfma_f32_16x16x32_bf16 v[100:103], v[160:163], v[176:179], v[100:103]
	v_mfma_f32_16x16x32_bf16 v[84:87], v[156:159], v[180:183], 0
	v_mfma_f32_16x16x32_bf16 v[84:87], v[160:163], v[184:187], v[84:87]
	v_mfma_f32_16x16x32_bf16 v[68:71], v[156:159], v[196:199], 0
	v_mfma_f32_16x16x32_bf16 v[68:71], v[160:163], v[200:203], v[68:71]
	s_setprio 0
	s_barrier
	s_sleep 2
	s_add_i32 s49, s49, s30
	v_lshl_add_u64 v[204:205], s[24:25], 0, v[2:3]
	s_mov_b32 m0, s49
	ds_read_b128 v[164:167], v221 offset:16384
	ds_read_b128 v[168:171], v221 offset:17408
	ds_read_b128 v[172:175], v221 offset:18432
	ds_read_b128 v[176:179], v221 offset:19456
	ds_read_b128 v[180:183], v221 offset:20480
	ds_read_b128 v[184:187], v221 offset:21504
	ds_read_b128 v[196:199], v221 offset:22528
	ds_read_b128 v[200:203], v221 offset:23552
	global_load_lds_dwordx4 v[204:205], off
	s_add_i32 m0, s49, 0x2000
	s_add_u32 s50, s24, 0x80000
	v_lshl_add_u64 v[206:207], s[24:25], 0, v[190:191]
	s_addc_u32 s51, s25, 0
	s_add_i32 s49, s52, s30
	global_load_lds_dwordx4 v[206:207], off
	v_lshl_add_u64 v[208:209], s[50:51], 0, v[2:3]
	s_mov_b32 m0, s49
	v_lshl_add_u64 v[210:211], s[26:27], 0, v[188:189]
	global_load_lds_dwordx4 v[208:209], off
	v_lshl_add_u64 v[208:209], s[50:51], 0, v[190:191]
	s_add_i32 m0, s49, 0x2000
	s_nop 0
	global_load_lds_dwordx4 v[208:209], off
	v_lshl_add_u64 v[208:209], s[26:27], 0, v[0:1]
	s_mov_b32 m0, s21
	s_nop 0
	global_load_lds_dwordx4 v[208:209], off
	s_mov_b32 m0, s31
	s_nop 0
	global_load_lds_dwordx4 v[210:211], off
	s_waitcnt vmcnt(8)
	s_waitcnt lgkmcnt(0)
	s_barrier
	s_setprio 1
	s_waitcnt lgkmcnt(0)
	v_mfma_f32_16x16x32_bf16 v[64:67], v[116:119], v[164:167], 0
	v_mfma_f32_16x16x32_bf16 v[64:67], v[124:127], v[168:171], v[64:67]
	v_mfma_f32_16x16x32_bf16 v[48:51], v[116:119], v[172:175], 0
	v_mfma_f32_16x16x32_bf16 v[48:51], v[124:127], v[176:179], v[48:51]
	v_mfma_f32_16x16x32_bf16 v[32:35], v[116:119], v[180:183], 0
	v_mfma_f32_16x16x32_bf16 v[32:35], v[124:127], v[184:187], v[32:35]
	v_mfma_f32_16x16x32_bf16 v[16:19], v[116:119], v[196:199], 0
	v_mfma_f32_16x16x32_bf16 v[16:19], v[124:127], v[200:203], v[16:19]
	v_mfma_f32_16x16x32_bf16 v[56:59], v[148:151], v[164:167], 0
	v_mfma_f32_16x16x32_bf16 v[56:59], v[152:155], v[168:171], v[56:59]
	v_mfma_f32_16x16x32_bf16 v[40:43], v[148:151], v[172:175], 0
	v_mfma_f32_16x16x32_bf16 v[40:43], v[152:155], v[176:179], v[40:43]
	v_mfma_f32_16x16x32_bf16 v[24:27], v[148:151], v[180:183], 0
	v_mfma_f32_16x16x32_bf16 v[24:27], v[152:155], v[184:187], v[24:27]
	v_mfma_f32_16x16x32_bf16 v[8:11], v[148:151], v[196:199], 0
	v_mfma_f32_16x16x32_bf16 v[8:11], v[152:155], v[200:203], v[8:11]
	v_mfma_f32_16x16x32_bf16 v[60:63], v[132:135], v[164:167], 0
	v_mfma_f32_16x16x32_bf16 v[60:63], v[144:147], v[168:171], v[60:63]
	v_mfma_f32_16x16x32_bf16 v[44:47], v[132:135], v[172:175], 0
	v_mfma_f32_16x16x32_bf16 v[44:47], v[144:147], v[176:179], v[44:47]
	v_mfma_f32_16x16x32_bf16 v[28:31], v[132:135], v[180:183], 0
	v_mfma_f32_16x16x32_bf16 v[28:31], v[144:147], v[184:187], v[28:31]
	v_mfma_f32_16x16x32_bf16 v[12:15], v[132:135], v[196:199], 0
	v_mfma_f32_16x16x32_bf16 v[12:15], v[144:147], v[200:203], v[12:15]
	v_mfma_f32_16x16x32_bf16 v[52:55], v[156:159], v[164:167], 0
	v_mfma_f32_16x16x32_bf16 v[52:55], v[160:163], v[168:171], v[52:55]
	v_mfma_f32_16x16x32_bf16 v[36:39], v[156:159], v[172:175], 0
	v_mfma_f32_16x16x32_bf16 v[36:39], v[160:163], v[176:179], v[36:39]
	v_mfma_f32_16x16x32_bf16 v[20:23], v[156:159], v[180:183], 0
	v_mfma_f32_16x16x32_bf16 v[20:23], v[160:163], v[184:187], v[20:23]
	v_mfma_f32_16x16x32_bf16 v[4:7], v[156:159], v[196:199], 0
	v_mfma_f32_16x16x32_bf16 v[4:7], v[160:163], v[200:203], v[4:7]
	s_setprio 0
	s_barrier
	s_sleep 1
	s_add_i32 s49, 0, 0x18000
	s_add_i32 s50, 0, 0x1c000
	s_add_u32 s26, s26, 0x80000
	s_addc_u32 s27, s27, 0
	s_mov_b32 m0, s35
	v_lshl_add_u64 v[212:213], s[26:27], 0, v[0:1]
	global_load_lds_dwordx4 v[212:213], off
	v_lshl_add_u64 v[212:213], s[26:27], 0, v[188:189]
	s_mov_b32 m0, s40
	s_nop 0
	global_load_lds_dwordx4 v[212:213], off
	v_add_u32_e32 v144, s49, v219
	v_add_u32_e32 v160, s50, v219
	ds_read_b128 v[116:119], v144
	ds_read_b128 v[124:127], v144 offset:1024
	ds_read_b128 v[132:135], v144 offset:2048
	ds_read_b128 v[144:147], v144 offset:3072
	ds_read_b128 v[148:151], v160
	ds_read_b128 v[152:155], v160 offset:1024
	ds_read_b128 v[156:159], v160 offset:2048
	ds_read_b128 v[160:163], v160 offset:3072
	ds_read_b128 v[164:167], v221 offset:32768
	ds_read_b128 v[168:171], v221 offset:33792
	ds_read_b128 v[172:175], v221 offset:34816
	ds_read_b128 v[176:179], v221 offset:35840
	ds_read_b128 v[180:183], v221 offset:36864
	ds_read_b128 v[184:187], v221 offset:37888
	ds_read_b128 v[196:199], v221 offset:38912
	ds_read_b128 v[200:203], v221 offset:39936
	s_waitcnt vmcnt(8)
	s_waitcnt lgkmcnt(0)
	s_barrier
	s_setprio 1
	s_waitcnt lgkmcnt(0)
	v_mfma_f32_16x16x32_bf16 v[140:143], v[116:119], v[164:167], v[140:143]
	v_mfma_f32_16x16x32_bf16 v[140:143], v[124:127], v[168:171], v[140:143]
	v_mfma_f32_16x16x32_bf16 v[112:115], v[116:119], v[172:175], v[112:115]
	v_mfma_f32_16x16x32_bf16 v[112:115], v[124:127], v[176:179], v[112:115]
	v_mfma_f32_16x16x32_bf16 v[96:99], v[116:119], v[180:183], v[96:99]
	v_mfma_f32_16x16x32_bf16 v[96:99], v[124:127], v[184:187], v[96:99]
	v_mfma_f32_16x16x32_bf16 v[80:83], v[116:119], v[196:199], v[80:83]
	v_mfma_f32_16x16x32_bf16 v[80:83], v[124:127], v[200:203], v[80:83]
	v_mfma_f32_16x16x32_bf16 v[128:131], v[148:151], v[164:167], v[128:131]
	v_mfma_f32_16x16x32_bf16 v[128:131], v[152:155], v[168:171], v[128:131]
	v_mfma_f32_16x16x32_bf16 v[104:107], v[148:151], v[172:175], v[104:107]
	v_mfma_f32_16x16x32_bf16 v[104:107], v[152:155], v[176:179], v[104:107]
	v_mfma_f32_16x16x32_bf16 v[88:91], v[148:151], v[180:183], v[88:91]
	v_mfma_f32_16x16x32_bf16 v[88:91], v[152:155], v[184:187], v[88:91]
	v_mfma_f32_16x16x32_bf16 v[72:75], v[148:151], v[196:199], v[72:75]
	v_mfma_f32_16x16x32_bf16 v[72:75], v[152:155], v[200:203], v[72:75]
	v_mfma_f32_16x16x32_bf16 v[136:139], v[132:135], v[164:167], v[136:139]
	v_mfma_f32_16x16x32_bf16 v[136:139], v[144:147], v[168:171], v[136:139]
	v_mfma_f32_16x16x32_bf16 v[108:111], v[132:135], v[172:175], v[108:111]
	v_mfma_f32_16x16x32_bf16 v[108:111], v[144:147], v[176:179], v[108:111]
	v_mfma_f32_16x16x32_bf16 v[92:95], v[132:135], v[180:183], v[92:95]
	v_mfma_f32_16x16x32_bf16 v[92:95], v[144:147], v[184:187], v[92:95]
	v_mfma_f32_16x16x32_bf16 v[76:79], v[132:135], v[196:199], v[76:79]
	v_mfma_f32_16x16x32_bf16 v[76:79], v[144:147], v[200:203], v[76:79]
	v_mfma_f32_16x16x32_bf16 v[120:123], v[156:159], v[164:167], v[120:123]
	v_mfma_f32_16x16x32_bf16 v[120:123], v[160:163], v[168:171], v[120:123]
	v_mfma_f32_16x16x32_bf16 v[100:103], v[156:159], v[172:175], v[100:103]
	v_mfma_f32_16x16x32_bf16 v[100:103], v[160:163], v[176:179], v[100:103]
	v_mfma_f32_16x16x32_bf16 v[84:87], v[156:159], v[180:183], v[84:87]
	v_mfma_f32_16x16x32_bf16 v[84:87], v[160:163], v[184:187], v[84:87]
	v_mfma_f32_16x16x32_bf16 v[68:71], v[156:159], v[196:199], v[68:71]
	v_mfma_f32_16x16x32_bf16 v[68:71], v[160:163], v[200:203], v[68:71]
	s_setprio 0
	s_barrier
	s_sleep 2
	s_add_i32 s26, s49, s30
	v_lshl_add_u64 v[204:205], v[204:205], 0, s[66:67]
	s_mov_b32 m0, s26
	ds_read_b128 v[164:167], v221 offset:49152
	ds_read_b128 v[168:171], v221 offset:50176
	ds_read_b128 v[172:175], v221 offset:51200
	ds_read_b128 v[176:179], v221 offset:52224
	ds_read_b128 v[180:183], v221 offset:53248
	ds_read_b128 v[184:187], v221 offset:54272
	ds_read_b128 v[196:199], v221 offset:55296
	ds_read_b128 v[200:203], v221 offset:56320
	global_load_lds_dwordx4 v[204:205], off
	s_add_i32 m0, s26, 0x2000
	s_add_u32 s24, s24, 0x80080
	v_lshl_add_u64 v[204:205], v[206:207], 0, s[66:67]
	s_addc_u32 s25, s25, 0
	s_add_i32 s26, s50, s30
	global_load_lds_dwordx4 v[204:205], off
	v_lshl_add_u64 v[204:205], s[24:25], 0, v[2:3]
	s_mov_b32 m0, s26
	s_nop 0
	global_load_lds_dwordx4 v[204:205], off
	v_lshl_add_u64 v[204:205], s[24:25], 0, v[190:191]
	s_add_i32 m0, s26, 0x2000
	s_nop 0
	global_load_lds_dwordx4 v[204:205], off
	v_lshl_add_u64 v[204:205], v[208:209], 0, s[66:67]
	s_mov_b32 m0, s41
	s_nop 0
	global_load_lds_dwordx4 v[204:205], off
	v_lshl_add_u64 v[204:205], v[210:211], 0, s[66:67]
	s_mov_b32 m0, s42
	s_nop 0
	global_load_lds_dwordx4 v[204:205], off
	s_waitcnt vmcnt(8)
	s_waitcnt lgkmcnt(0)
	s_barrier
	s_setprio 1
	s_waitcnt lgkmcnt(0)
	v_mfma_f32_16x16x32_bf16 v[64:67], v[116:119], v[164:167], v[64:67]
	v_mfma_f32_16x16x32_bf16 v[64:67], v[124:127], v[168:171], v[64:67]
	v_mfma_f32_16x16x32_bf16 v[48:51], v[116:119], v[172:175], v[48:51]
	v_mfma_f32_16x16x32_bf16 v[48:51], v[124:127], v[176:179], v[48:51]
	v_mfma_f32_16x16x32_bf16 v[32:35], v[116:119], v[180:183], v[32:35]
	v_mfma_f32_16x16x32_bf16 v[32:35], v[124:127], v[184:187], v[32:35]
	v_mfma_f32_16x16x32_bf16 v[16:19], v[116:119], v[196:199], v[16:19]
	v_mfma_f32_16x16x32_bf16 v[16:19], v[124:127], v[200:203], v[16:19]
	v_mfma_f32_16x16x32_bf16 v[56:59], v[148:151], v[164:167], v[56:59]
	v_mfma_f32_16x16x32_bf16 v[56:59], v[152:155], v[168:171], v[56:59]
	v_mfma_f32_16x16x32_bf16 v[40:43], v[148:151], v[172:175], v[40:43]
	v_mfma_f32_16x16x32_bf16 v[40:43], v[152:155], v[176:179], v[40:43]
	v_mfma_f32_16x16x32_bf16 v[24:27], v[148:151], v[180:183], v[24:27]
	v_mfma_f32_16x16x32_bf16 v[24:27], v[152:155], v[184:187], v[24:27]
	v_mfma_f32_16x16x32_bf16 v[8:11], v[148:151], v[196:199], v[8:11]
	v_mfma_f32_16x16x32_bf16 v[8:11], v[152:155], v[200:203], v[8:11]
	v_mfma_f32_16x16x32_bf16 v[60:63], v[132:135], v[164:167], v[60:63]
	v_mfma_f32_16x16x32_bf16 v[60:63], v[144:147], v[168:171], v[60:63]
	v_mfma_f32_16x16x32_bf16 v[44:47], v[132:135], v[172:175], v[44:47]
	v_mfma_f32_16x16x32_bf16 v[44:47], v[144:147], v[176:179], v[44:47]
	v_mfma_f32_16x16x32_bf16 v[28:31], v[132:135], v[180:183], v[28:31]
	v_mfma_f32_16x16x32_bf16 v[28:31], v[144:147], v[184:187], v[28:31]
	v_mfma_f32_16x16x32_bf16 v[12:15], v[132:135], v[196:199], v[12:15]
	v_mfma_f32_16x16x32_bf16 v[12:15], v[144:147], v[200:203], v[12:15]
	v_mfma_f32_16x16x32_bf16 v[52:55], v[156:159], v[164:167], v[52:55]
	v_mfma_f32_16x16x32_bf16 v[52:55], v[160:163], v[168:171], v[52:55]
	v_mfma_f32_16x16x32_bf16 v[36:39], v[156:159], v[172:175], v[36:39]
	v_mfma_f32_16x16x32_bf16 v[36:39], v[160:163], v[176:179], v[36:39]
	v_mfma_f32_16x16x32_bf16 v[20:23], v[156:159], v[180:183], v[20:23]
	v_mfma_f32_16x16x32_bf16 v[20:23], v[160:163], v[184:187], v[20:23]
	v_mfma_f32_16x16x32_bf16 v[4:7], v[156:159], v[196:199], v[4:7]
	v_mfma_f32_16x16x32_bf16 v[4:7], v[160:163], v[200:203], v[4:7]
	s_setprio 0
	s_barrier
	s_add_i32 s48, s48, 2
	s_add_u32 s22, s22, 0x100
	s_addc_u32 s23, s23, 0
	s_add_u32 s46, s46, 0x100
	s_addc_u32 s47, s47, 0
	s_cmp_gt_u32 s48, 29
.LBB0_1010:
	s_sleep 1
	s_add_u32 s24, s22, 0xfff80080
	s_addc_u32 s25, s23, -1
	s_add_i32 s49, 0, 0x10000
	s_cmp_eq_u32 s48, 28
	s_cselect_b32 s27, s13, s25
	s_cselect_b32 s26, s19, s24
	s_cselect_b32 s25, s11, s47
	s_cselect_b32 s24, s45, s46
	s_add_i32 s52, 0, 0x14000
	v_lshl_add_u64 v[204:205], s[22:23], 0, v[192:193]
	s_add_i32 m0, s21, 0xc000
	s_nop 0
	global_load_lds_dwordx4 v[204:205], off
	v_lshl_add_u64 v[204:205], s[22:23], 0, v[194:195]
	s_add_i32 m0, s21, 0xe000
	s_nop 0
	global_load_lds_dwordx4 v[204:205], off
	v_add_u32_e32 v144, s49, v219
	v_add_u32_e32 v160, s52, v219
	ds_read_b128 v[116:119], v144
	ds_read_b128 v[124:127], v144 offset:1024
	ds_read_b128 v[132:135], v144 offset:2048
	ds_read_b128 v[144:147], v144 offset:3072
	ds_read_b128 v[148:151], v160
	ds_read_b128 v[152:155], v160 offset:1024
	ds_read_b128 v[156:159], v160 offset:2048
	ds_read_b128 v[160:163], v160 offset:3072
	ds_read_b128 v[164:167], v221
	ds_read_b128 v[168:171], v221 offset:1024
	ds_read_b128 v[172:175], v221 offset:2048
	ds_read_b128 v[176:179], v221 offset:3072
	ds_read_b128 v[180:183], v221 offset:4096
	ds_read_b128 v[184:187], v221 offset:5120
	ds_read_b128 v[196:199], v221 offset:6144
	ds_read_b128 v[200:203], v221 offset:7168
	s_waitcnt vmcnt(8)
	s_waitcnt lgkmcnt(0)
	s_barrier
	s_setprio 1
	s_waitcnt lgkmcnt(0)
	v_mfma_f32_16x16x32_bf16 v[140:143], v[116:119], v[164:167], v[140:143]
	v_mfma_f32_16x16x32_bf16 v[140:143], v[124:127], v[168:171], v[140:143]
	v_mfma_f32_16x16x32_bf16 v[112:115], v[116:119], v[172:175], v[112:115]
	v_mfma_f32_16x16x32_bf16 v[112:115], v[124:127], v[176:179], v[112:115]
	v_mfma_f32_16x16x32_bf16 v[96:99], v[116:119], v[180:183], v[96:99]
	v_mfma_f32_16x16x32_bf16 v[96:99], v[124:127], v[184:187], v[96:99]
	v_mfma_f32_16x16x32_bf16 v[80:83], v[116:119], v[196:199], v[80:83]
	v_mfma_f32_16x16x32_bf16 v[80:83], v[124:127], v[200:203], v[80:83]
	v_mfma_f32_16x16x32_bf16 v[128:131], v[148:151], v[164:167], v[128:131]
	v_mfma_f32_16x16x32_bf16 v[128:131], v[152:155], v[168:171], v[128:131]
	v_mfma_f32_16x16x32_bf16 v[104:107], v[148:151], v[172:175], v[104:107]
	v_mfma_f32_16x16x32_bf16 v[104:107], v[152:155], v[176:179], v[104:107]
	v_mfma_f32_16x16x32_bf16 v[88:91], v[148:151], v[180:183], v[88:91]
	v_mfma_f32_16x16x32_bf16 v[88:91], v[152:155], v[184:187], v[88:91]
	v_mfma_f32_16x16x32_bf16 v[72:75], v[148:151], v[196:199], v[72:75]
	v_mfma_f32_16x16x32_bf16 v[72:75], v[152:155], v[200:203], v[72:75]
	v_mfma_f32_16x16x32_bf16 v[136:139], v[132:135], v[164:167], v[136:139]
	v_mfma_f32_16x16x32_bf16 v[136:139], v[144:147], v[168:171], v[136:139]
	v_mfma_f32_16x16x32_bf16 v[108:111], v[132:135], v[172:175], v[108:111]
	v_mfma_f32_16x16x32_bf16 v[108:111], v[144:147], v[176:179], v[108:111]
	v_mfma_f32_16x16x32_bf16 v[92:95], v[132:135], v[180:183], v[92:95]
	v_mfma_f32_16x16x32_bf16 v[92:95], v[144:147], v[184:187], v[92:95]
	v_mfma_f32_16x16x32_bf16 v[76:79], v[132:135], v[196:199], v[76:79]
	v_mfma_f32_16x16x32_bf16 v[76:79], v[144:147], v[200:203], v[76:79]
	v_mfma_f32_16x16x32_bf16 v[120:123], v[156:159], v[164:167], v[120:123]
	v_mfma_f32_16x16x32_bf16 v[120:123], v[160:163], v[168:171], v[120:123]
	v_mfma_f32_16x16x32_bf16 v[100:103], v[156:159], v[172:175], v[100:103]
	v_mfma_f32_16x16x32_bf16 v[100:103], v[160:163], v[176:179], v[100:103]
	v_mfma_f32_16x16x32_bf16 v[84:87], v[156:159], v[180:183], v[84:87]
	v_mfma_f32_16x16x32_bf16 v[84:87], v[160:163], v[184:187], v[84:87]
	v_mfma_f32_16x16x32_bf16 v[68:71], v[156:159], v[196:199], v[68:71]
	v_mfma_f32_16x16x32_bf16 v[68:71], v[160:163], v[200:203], v[68:71]
	s_setprio 0
	s_barrier
	s_sleep 2
	s_add_i32 s49, s49, s30
	v_lshl_add_u64 v[204:205], s[24:25], 0, v[2:3]
	s_mov_b32 m0, s49
	ds_read_b128 v[164:167], v221 offset:16384
	ds_read_b128 v[168:171], v221 offset:17408
	ds_read_b128 v[172:175], v221 offset:18432
	ds_read_b128 v[176:179], v221 offset:19456
	ds_read_b128 v[180:183], v221 offset:20480
	ds_read_b128 v[184:187], v221 offset:21504
	ds_read_b128 v[196:199], v221 offset:22528
	ds_read_b128 v[200:203], v221 offset:23552
	global_load_lds_dwordx4 v[204:205], off
	s_add_i32 m0, s49, 0x2000
	s_add_u32 s50, s24, 0x80000
	v_lshl_add_u64 v[206:207], s[24:25], 0, v[190:191]
	s_addc_u32 s51, s25, 0
	s_add_i32 s49, s52, s30
	global_load_lds_dwordx4 v[206:207], off
	v_lshl_add_u64 v[208:209], s[50:51], 0, v[2:3]
	s_mov_b32 m0, s49
	v_lshl_add_u64 v[210:211], s[26:27], 0, v[188:189]
	global_load_lds_dwordx4 v[208:209], off
	v_lshl_add_u64 v[208:209], s[50:51], 0, v[190:191]
	s_add_i32 m0, s49, 0x2000
	s_nop 0
	global_load_lds_dwordx4 v[208:209], off
	v_lshl_add_u64 v[208:209], s[26:27], 0, v[0:1]
	s_mov_b32 m0, s21
	s_nop 0
	global_load_lds_dwordx4 v[208:209], off
	s_mov_b32 m0, s31
	s_nop 0
	global_load_lds_dwordx4 v[210:211], off
	s_waitcnt vmcnt(8)
	s_waitcnt lgkmcnt(0)
	s_barrier
	s_setprio 1
	s_waitcnt lgkmcnt(0)
	v_mfma_f32_16x16x32_bf16 v[64:67], v[116:119], v[164:167], v[64:67]
	v_mfma_f32_16x16x32_bf16 v[64:67], v[124:127], v[168:171], v[64:67]
	v_mfma_f32_16x16x32_bf16 v[48:51], v[116:119], v[172:175], v[48:51]
	v_mfma_f32_16x16x32_bf16 v[48:51], v[124:127], v[176:179], v[48:51]
	v_mfma_f32_16x16x32_bf16 v[32:35], v[116:119], v[180:183], v[32:35]
	v_mfma_f32_16x16x32_bf16 v[32:35], v[124:127], v[184:187], v[32:35]
	v_mfma_f32_16x16x32_bf16 v[16:19], v[116:119], v[196:199], v[16:19]
	v_mfma_f32_16x16x32_bf16 v[16:19], v[124:127], v[200:203], v[16:19]
	v_mfma_f32_16x16x32_bf16 v[56:59], v[148:151], v[164:167], v[56:59]
	v_mfma_f32_16x16x32_bf16 v[56:59], v[152:155], v[168:171], v[56:59]
	v_mfma_f32_16x16x32_bf16 v[40:43], v[148:151], v[172:175], v[40:43]
	v_mfma_f32_16x16x32_bf16 v[40:43], v[152:155], v[176:179], v[40:43]
	v_mfma_f32_16x16x32_bf16 v[24:27], v[148:151], v[180:183], v[24:27]
	v_mfma_f32_16x16x32_bf16 v[24:27], v[152:155], v[184:187], v[24:27]
	v_mfma_f32_16x16x32_bf16 v[8:11], v[148:151], v[196:199], v[8:11]
	v_mfma_f32_16x16x32_bf16 v[8:11], v[152:155], v[200:203], v[8:11]
	v_mfma_f32_16x16x32_bf16 v[60:63], v[132:135], v[164:167], v[60:63]
	v_mfma_f32_16x16x32_bf16 v[60:63], v[144:147], v[168:171], v[60:63]
	v_mfma_f32_16x16x32_bf16 v[44:47], v[132:135], v[172:175], v[44:47]
	v_mfma_f32_16x16x32_bf16 v[44:47], v[144:147], v[176:179], v[44:47]
	v_mfma_f32_16x16x32_bf16 v[28:31], v[132:135], v[180:183], v[28:31]
	v_mfma_f32_16x16x32_bf16 v[28:31], v[144:147], v[184:187], v[28:31]
	v_mfma_f32_16x16x32_bf16 v[12:15], v[132:135], v[196:199], v[12:15]
	v_mfma_f32_16x16x32_bf16 v[12:15], v[144:147], v[200:203], v[12:15]
	v_mfma_f32_16x16x32_bf16 v[52:55], v[156:159], v[164:167], v[52:55]
	v_mfma_f32_16x16x32_bf16 v[52:55], v[160:163], v[168:171], v[52:55]
	v_mfma_f32_16x16x32_bf16 v[36:39], v[156:159], v[172:175], v[36:39]
	v_mfma_f32_16x16x32_bf16 v[36:39], v[160:163], v[176:179], v[36:39]
	v_mfma_f32_16x16x32_bf16 v[20:23], v[156:159], v[180:183], v[20:23]
	v_mfma_f32_16x16x32_bf16 v[20:23], v[160:163], v[184:187], v[20:23]
	v_mfma_f32_16x16x32_bf16 v[4:7], v[156:159], v[196:199], v[4:7]
	v_mfma_f32_16x16x32_bf16 v[4:7], v[160:163], v[200:203], v[4:7]
	s_setprio 0
	s_barrier
	s_sleep 1
	s_add_i32 s49, 0, 0x18000
	s_add_i32 s50, 0, 0x1c000
	s_add_u32 s26, s26, 0x80000
	s_addc_u32 s27, s27, 0
	s_mov_b32 m0, s35
	v_lshl_add_u64 v[212:213], s[26:27], 0, v[0:1]
	global_load_lds_dwordx4 v[212:213], off
	v_lshl_add_u64 v[212:213], s[26:27], 0, v[188:189]
	s_mov_b32 m0, s40
	s_nop 0
	global_load_lds_dwordx4 v[212:213], off
	v_add_u32_e32 v144, s49, v219
	v_add_u32_e32 v160, s50, v219
	ds_read_b128 v[116:119], v144
	ds_read_b128 v[124:127], v144 offset:1024
	ds_read_b128 v[132:135], v144 offset:2048
	ds_read_b128 v[144:147], v144 offset:3072
	ds_read_b128 v[148:151], v160
	ds_read_b128 v[152:155], v160 offset:1024
	ds_read_b128 v[156:159], v160 offset:2048
	ds_read_b128 v[160:163], v160 offset:3072
	ds_read_b128 v[164:167], v221 offset:32768
	ds_read_b128 v[168:171], v221 offset:33792
	ds_read_b128 v[172:175], v221 offset:34816
	ds_read_b128 v[176:179], v221 offset:35840
	ds_read_b128 v[180:183], v221 offset:36864
	ds_read_b128 v[184:187], v221 offset:37888
	ds_read_b128 v[196:199], v221 offset:38912
	ds_read_b128 v[200:203], v221 offset:39936
	s_waitcnt vmcnt(8)
	s_waitcnt lgkmcnt(0)
	s_barrier
	s_setprio 1
	s_waitcnt lgkmcnt(0)
	v_mfma_f32_16x16x32_bf16 v[140:143], v[116:119], v[164:167], v[140:143]
	v_mfma_f32_16x16x32_bf16 v[140:143], v[124:127], v[168:171], v[140:143]
	v_mfma_f32_16x16x32_bf16 v[112:115], v[116:119], v[172:175], v[112:115]
	v_mfma_f32_16x16x32_bf16 v[112:115], v[124:127], v[176:179], v[112:115]
	v_mfma_f32_16x16x32_bf16 v[96:99], v[116:119], v[180:183], v[96:99]
	v_mfma_f32_16x16x32_bf16 v[96:99], v[124:127], v[184:187], v[96:99]
	v_mfma_f32_16x16x32_bf16 v[80:83], v[116:119], v[196:199], v[80:83]
	v_mfma_f32_16x16x32_bf16 v[80:83], v[124:127], v[200:203], v[80:83]
	v_mfma_f32_16x16x32_bf16 v[128:131], v[148:151], v[164:167], v[128:131]
	v_mfma_f32_16x16x32_bf16 v[128:131], v[152:155], v[168:171], v[128:131]
	v_mfma_f32_16x16x32_bf16 v[104:107], v[148:151], v[172:175], v[104:107]
	v_mfma_f32_16x16x32_bf16 v[104:107], v[152:155], v[176:179], v[104:107]
	v_mfma_f32_16x16x32_bf16 v[88:91], v[148:151], v[180:183], v[88:91]
	v_mfma_f32_16x16x32_bf16 v[88:91], v[152:155], v[184:187], v[88:91]
	v_mfma_f32_16x16x32_bf16 v[72:75], v[148:151], v[196:199], v[72:75]
	v_mfma_f32_16x16x32_bf16 v[72:75], v[152:155], v[200:203], v[72:75]
	v_mfma_f32_16x16x32_bf16 v[136:139], v[132:135], v[164:167], v[136:139]
	v_mfma_f32_16x16x32_bf16 v[136:139], v[144:147], v[168:171], v[136:139]
	v_mfma_f32_16x16x32_bf16 v[108:111], v[132:135], v[172:175], v[108:111]
	v_mfma_f32_16x16x32_bf16 v[108:111], v[144:147], v[176:179], v[108:111]
	v_mfma_f32_16x16x32_bf16 v[92:95], v[132:135], v[180:183], v[92:95]
	v_mfma_f32_16x16x32_bf16 v[92:95], v[144:147], v[184:187], v[92:95]
	v_mfma_f32_16x16x32_bf16 v[76:79], v[132:135], v[196:199], v[76:79]
	v_mfma_f32_16x16x32_bf16 v[76:79], v[144:147], v[200:203], v[76:79]
	v_mfma_f32_16x16x32_bf16 v[120:123], v[156:159], v[164:167], v[120:123]
	v_mfma_f32_16x16x32_bf16 v[120:123], v[160:163], v[168:171], v[120:123]
	v_mfma_f32_16x16x32_bf16 v[100:103], v[156:159], v[172:175], v[100:103]
	v_mfma_f32_16x16x32_bf16 v[100:103], v[160:163], v[176:179], v[100:103]
	v_mfma_f32_16x16x32_bf16 v[84:87], v[156:159], v[180:183], v[84:87]
	v_mfma_f32_16x16x32_bf16 v[84:87], v[160:163], v[184:187], v[84:87]
	v_mfma_f32_16x16x32_bf16 v[68:71], v[156:159], v[196:199], v[68:71]
	v_mfma_f32_16x16x32_bf16 v[68:71], v[160:163], v[200:203], v[68:71]
	s_setprio 0
	s_barrier
	s_sleep 2
	s_add_i32 s26, s49, s30
	v_lshl_add_u64 v[204:205], v[204:205], 0, s[66:67]
	s_mov_b32 m0, s26
	ds_read_b128 v[164:167], v221 offset:49152
	ds_read_b128 v[168:171], v221 offset:50176
	ds_read_b128 v[172:175], v221 offset:51200
	ds_read_b128 v[176:179], v221 offset:52224
	ds_read_b128 v[180:183], v221 offset:53248
	ds_read_b128 v[184:187], v221 offset:54272
	ds_read_b128 v[196:199], v221 offset:55296
	ds_read_b128 v[200:203], v221 offset:56320
	global_load_lds_dwordx4 v[204:205], off
	s_add_i32 m0, s26, 0x2000
	s_add_u32 s24, s24, 0x80080
	v_lshl_add_u64 v[204:205], v[206:207], 0, s[66:67]
	s_addc_u32 s25, s25, 0
	s_add_i32 s26, s50, s30
	global_load_lds_dwordx4 v[204:205], off
	v_lshl_add_u64 v[204:205], s[24:25], 0, v[2:3]
	s_mov_b32 m0, s26
	s_nop 0
	global_load_lds_dwordx4 v[204:205], off
	v_lshl_add_u64 v[204:205], s[24:25], 0, v[190:191]
	s_add_i32 m0, s26, 0x2000
	s_nop 0
	global_load_lds_dwordx4 v[204:205], off
	v_lshl_add_u64 v[204:205], v[208:209], 0, s[66:67]
	s_mov_b32 m0, s41
	s_nop 0
	global_load_lds_dwordx4 v[204:205], off
	v_lshl_add_u64 v[204:205], v[210:211], 0, s[66:67]
	s_mov_b32 m0, s42
	s_nop 0
	global_load_lds_dwordx4 v[204:205], off
	s_waitcnt vmcnt(8)
	s_waitcnt lgkmcnt(0)
	s_barrier
	s_setprio 1
	s_waitcnt lgkmcnt(0)
	v_mfma_f32_16x16x32_bf16 v[64:67], v[116:119], v[164:167], v[64:67]
	v_mfma_f32_16x16x32_bf16 v[64:67], v[124:127], v[168:171], v[64:67]
	v_mfma_f32_16x16x32_bf16 v[48:51], v[116:119], v[172:175], v[48:51]
	v_mfma_f32_16x16x32_bf16 v[48:51], v[124:127], v[176:179], v[48:51]
	v_mfma_f32_16x16x32_bf16 v[32:35], v[116:119], v[180:183], v[32:35]
	v_mfma_f32_16x16x32_bf16 v[32:35], v[124:127], v[184:187], v[32:35]
	v_mfma_f32_16x16x32_bf16 v[16:19], v[116:119], v[196:199], v[16:19]
	v_mfma_f32_16x16x32_bf16 v[16:19], v[124:127], v[200:203], v[16:19]
	v_mfma_f32_16x16x32_bf16 v[56:59], v[148:151], v[164:167], v[56:59]
	v_mfma_f32_16x16x32_bf16 v[56:59], v[152:155], v[168:171], v[56:59]
	v_mfma_f32_16x16x32_bf16 v[40:43], v[148:151], v[172:175], v[40:43]
	v_mfma_f32_16x16x32_bf16 v[40:43], v[152:155], v[176:179], v[40:43]
	v_mfma_f32_16x16x32_bf16 v[24:27], v[148:151], v[180:183], v[24:27]
	v_mfma_f32_16x16x32_bf16 v[24:27], v[152:155], v[184:187], v[24:27]
	v_mfma_f32_16x16x32_bf16 v[8:11], v[148:151], v[196:199], v[8:11]
	v_mfma_f32_16x16x32_bf16 v[8:11], v[152:155], v[200:203], v[8:11]
	v_mfma_f32_16x16x32_bf16 v[60:63], v[132:135], v[164:167], v[60:63]
	v_mfma_f32_16x16x32_bf16 v[60:63], v[144:147], v[168:171], v[60:63]
	v_mfma_f32_16x16x32_bf16 v[44:47], v[132:135], v[172:175], v[44:47]
	v_mfma_f32_16x16x32_bf16 v[44:47], v[144:147], v[176:179], v[44:47]
	v_mfma_f32_16x16x32_bf16 v[28:31], v[132:135], v[180:183], v[28:31]
	v_mfma_f32_16x16x32_bf16 v[28:31], v[144:147], v[184:187], v[28:31]
	v_mfma_f32_16x16x32_bf16 v[12:15], v[132:135], v[196:199], v[12:15]
	v_mfma_f32_16x16x32_bf16 v[12:15], v[144:147], v[200:203], v[12:15]
	v_mfma_f32_16x16x32_bf16 v[52:55], v[156:159], v[164:167], v[52:55]
	v_mfma_f32_16x16x32_bf16 v[52:55], v[160:163], v[168:171], v[52:55]
	v_mfma_f32_16x16x32_bf16 v[36:39], v[156:159], v[172:175], v[36:39]
	v_mfma_f32_16x16x32_bf16 v[36:39], v[160:163], v[176:179], v[36:39]
	v_mfma_f32_16x16x32_bf16 v[20:23], v[156:159], v[180:183], v[20:23]
	v_mfma_f32_16x16x32_bf16 v[20:23], v[160:163], v[184:187], v[20:23]
	v_mfma_f32_16x16x32_bf16 v[4:7], v[156:159], v[196:199], v[4:7]
	v_mfma_f32_16x16x32_bf16 v[4:7], v[160:163], v[200:203], v[4:7]
	s_setprio 0
	s_barrier
	s_add_i32 s48, s48, 2
	s_add_u32 s22, s22, 0x100
	s_addc_u32 s23, s23, 0
	s_add_u32 s46, s46, 0x100
	s_addc_u32 s47, s47, 0
	s_cmp_gt_u32 s48, 29
	s_cbranch_scc0 .LBB0_1010
	s_and_b64 vcc, exec, s[8:9]
	s_cbranch_vccz .LBB0_1013
	s_barrier
